# pair-tile FFN-up GEMM: next tile's first two K-tiles requested before the current epilogue; tile-invariant address math hoisted
# baseline (speedup 1.0000x reference)
; DI u16 f2bf(float x) { return (u16)(pack2(x, 0.f) & 0xffffu); }
; DI int opaque_tid() { int t = threadIdx.x; asm volatile("" : "+v"(t)); return t; }
; DI int crow(int i, int h) { return (i & 3) + 8 * (i >> 2) + 4 * h; }
; template <class AL, class BL>
; DI void gemm_core(AL al, BL bl, int m0, int n0, int K, char* smem, f32x16 (&acc)[2][2]) {
;   const int tid = opaque_tid(), lane = tid & 63, w = tid >> 6, wm = w >> 1, wn = w & 1;
;   u16* As = (u16*)smem;
;   u16* Bs = As + 2 * 128 * 72;
;   uint4 xa0, xa1, xa2, xa3, xb0, xb1, xb2, xb3, ya0, ya1, ya2, ya3, yb0, yb1, yb2, yb3;
;   const int nk = K / 64;
; #pragma unroll
;   for (int mt = 0; mt < 2; mt++)
; #pragma unroll
;     for (int nt = 0; nt < 2; nt++)
; #pragma unroll
;       for (int i = 0; i < 16; i++) acc[mt][nt][i] = 0.f;
;   const int srow = tid >> 3, sch = tid & 7;
; template <class F>
; DI void epi_bf16_tile(const f32x16 (&acc)[2][2], int m0, int n0, u16* dst0, long ld, char* smem, F f) {
;   const int tid = opaque_tid(), lane = tid & 63, w = tid >> 6, wm = w >> 1, wn = w & 1, h = lane >> 5;
;   u16* T = (u16*)smem;
; #pragma unroll
;   for (int mt = 0; mt < 2; mt++)
; #pragma unroll
;     for (int nt = 0; nt < 2; nt++)
; #pragma unroll
;       for (int i = 0; i < 16; i++) {
;         const int ml = wm * 64 + mt * 32 + crow(i, h), nl = wn * 64 + nt * 32 + (lane & 31);
;         T[ml * 136 + nl] = f2bf(f(m0 + ml, n0 + nl, acc[mt][nt][i]));
;       }
;   __syncthreads();
; #pragma unroll
;   for (int j = 0; j < 8; j++) {
;     const int idx = tid + 256 * j, row = idx >> 4, ch = idx & 15;
;     *(uint4*)(dst0 + (long)row * ld + ch * 8) = *(const uint4*)(T + row * 136 + ch * 8);
.LBB0_976:
	s_or_b64 exec, exec, s[0:1]
	s_cmpk_lt_i32 s78, 0x1200
	s_cselect_b64 s[58:59], -1, 0
	s_cmpk_gt_i32 s78, 0x11ff
	s_mov_b64 s[2:3], s[70:71]
	s_waitcnt lgkmcnt(0)
	s_barrier
	s_cbranch_scc1 .LBB0_980
	s_add_u32 s8, s70, 0xdc00000
	s_addc_u32 s9, s71, 0
	s_add_u32 s22, s70, 0x4c00000
	s_addc_u32 s23, s71, 0
	s_add_u32 s14, s70, 0x10000
	s_mov_b64 s[12:13], 0x10000
	s_addc_u32 s15, s71, 0
	s_add_i32 s24, s67, 48
	s_lshl_b32 s25, s50, 7
	v_mov_b32_e32 v65, 0
	s_mov_b32 s26, 0x10000
	s_mov_b64 s[16:17], 0x20000
	s_mov_b32 s27, 0x20000
	s_mov_b64 s[18:19], 0x30000
	s_mov_b32 s28, 0x30000
	s_movk_i32 s29, 0x90
	s_mov_b32 s30, 0xfffffc0
	s_movk_i32 s31, 0x110
	s_mov_b32 s33, s78
	v_bfe_u32 v62, v202, 5, 1
	v_and_b32_e32 v63, 31, v202
	v_lshrrev_b32_e32 v64, 7, v202
	v_bfe_u32 v254, v202, 6, 1
	v_lshlrev_b32_e32 v253, 2, v62
	v_lshl_add_u32 v253, v64, 6, v253
	v_mul_u32_u24_e32 v59, 528, v253
	v_lshlrev_b32_e32 v252, 2, v253
	v_lshl_add_u32 v253, v254, 7, v63
	v_lshl_add_u32 v59, v253, 1, v59
	v_mul_u32_u24_e32 v57, 80, v253
	v_lshl_add_u32 v57, v62, 4, v57
	v_add_u32_e32 v57, 10240, v57
	v_lshl_add_u32 v253, v64, 6, v63
	v_mul_u32_u24_e32 v56, 80, v253
	v_lshl_add_u32 v56, v62, 4, v56
	v_lshrrev_b32_e32 v253, 5, v202
	v_mul_u32_u24_e32 v60, 528, v253
	v_lshl_add_u32 v60, v63, 4, v60
	v_mul_u32_u24_e32 v227, 8192, v253
	v_lshl_add_u32 v227, v63, 4, v227
	v_lshrrev_b32_e32 v253, 2, v202
	v_and_b32_e32 v254, 3, v202
	v_lshlrev_b32_e32 v254, 4, v254
	v_mov_b32_e32 v255, 0
	v_mul_u32_u24_e32 v58, 80, v253
	v_add_u32_e32 v58, v58, v254
	s_mov_b32 s98, s78
	s_cmpk_lt_u32 s98, 2016
	s_cbranch_scc1 .Lfu0_m0
	s_sub_u32 s34, s98, 2016
	s_mov_b32 s35, 14
	s_branch .Lfu0_g0

; #define G_LOAD(S, kt_) do { G_LD1(S##a0, S##b0, 0, kt_); G_LD1(S##a1, S##b1, 1, kt_); G_LD1(S##a2, S##b2, 2, kt_); G_LD1(S##a3, S##b3, 3, kt_); } while (0)
; #define G_STORE(S, buf_) do { G_ST1(S##a0, S##b0, 0, buf_); G_ST1(S##a1, S##b1, 1, buf_); G_ST1(S##a2, S##b2, 2, buf_); G_ST1(S##a3, S##b3, 3, buf_); } while (0)
; template <class AL, class BL>
; DI void gemm_core(AL al, BL bl, int m0, int n0, int K, char* smem, f32x16 (&acc)[2][2]) {
;     ...
;   G_LOAD(x, 0);
;   G_STORE(x, 0);
;   G_LOAD(x, 1);
;   G_LOAD(y, (nk > 2) ? 2 : 1);
;   __syncthreads();
;   for (int kt = 0; kt < nk; kt += 2) {
;     G_TILE(0, x, true, (kt + 3 < nk), kt + 3);
;     __syncthreads();
;     G_TILE(1, y, (kt + 2 < nk), (kt + 4 < nk), kt + 4);
;     __syncthreads();
;   }
.Lfu0_g0:
	s_lshl_b32 s0, s34, 7
	v_add_u32_e32 v62, s0, v253
	v_mov_b32_e32 v63, 4096
	v_mad_u64_u32 v[240:241], s[0:1], v62, v63, v[254:255]
	v_lshl_add_u64 v[240:241], v[240:241], 0, s[68:69]
	s_mov_b32 s0, 262144
	s_mov_b32 s1, 0
	v_lshl_add_u64 v[242:243], v[240:241], 0, s[0:1]
	s_lshl_b32 s0, s35, 8
	v_add_u32_e32 v62, s0, v253
	v_mov_b32_e32 v63, 2048
	v_mad_u64_u32 v[244:245], s[0:1], v62, v63, v[254:255]
	v_lshl_add_u64 v[244:245], v[244:245], 0, s[8:9]
	s_mov_b32 s0, 131072
	s_mov_b32 s1, 0
	v_lshl_add_u64 v[246:247], v[244:245], 0, s[0:1]
	v_lshl_add_u64 v[248:249], v[246:247], 0, s[0:1]
	v_lshl_add_u64 v[250:251], v[248:249], 0, s[0:1]
	global_load_dwordx4 v[32:35], v[240:241], off offset:2048
	global_load_dwordx4 v[36:39], v[242:243], off offset:2048
	global_load_dwordx4 v[40:43], v[244:245], off offset:0
	global_load_dwordx4 v[44:47], v[246:247], off offset:0
	global_load_dwordx4 v[48:51], v[248:249], off offset:0
	global_load_dwordx4 v[52:55], v[250:251], off offset:0
	global_load_dwordx4 v[214:217], v[240:241], off offset:2112
	global_load_dwordx4 v[218:221], v[242:243], off offset:2112
	global_load_dwordx4 v[222:225], v[244:245], off offset:64
	global_load_dwordx4 v[228:231], v[246:247], off offset:64
	global_load_dwordx4 v[232:235], v[248:249], off offset:64
	global_load_dwordx4 v[236:239], v[250:251], off offset:64
.Lfu0_tile:
	s_lshl_b32 s0, s34, 9
	v_add_u32_e32 v61, s0, v252
	s_lshl_b32 s0, s34, 7
	s_mul_i32 s1, s0, 8192
	s_mul_hi_u32 s2, s0, 8192
	s_add_u32 s20, s22, s1
	s_addc_u32 s21, s23, s2
	s_lshl_b32 s1, s35, 9
	s_add_u32 s20, s20, s1
	s_addc_u32 s21, s21, 0
	s_waitcnt vmcnt(6)
	ds_write_b128 v58, v[32:35] offset:0
	ds_write_b128 v58, v[36:39] offset:5120
	ds_write_b128 v58, v[40:43] offset:10240
	ds_write_b128 v58, v[44:47] offset:15360
	ds_write_b128 v58, v[48:51] offset:20480
	ds_write_b128 v58, v[52:55] offset:25600
	global_load_dwordx4 v[32:35], v[240:241], off offset:2176
	global_load_dwordx4 v[36:39], v[242:243], off offset:2176
	global_load_dwordx4 v[40:43], v[244:245], off offset:128
	global_load_dwordx4 v[44:47], v[246:247], off offset:128
	global_load_dwordx4 v[48:51], v[248:249], off offset:128
	global_load_dwordx4 v[52:55], v[250:251], off offset:128
	s_waitcnt lgkmcnt(0)
	s_barrier
	ds_read_b128 v[0:3], v56 offset:0
	ds_read_b128 v[4:7], v56 offset:2560
	ds_read_b128 v[8:11], v57 offset:0
	ds_read_b128 v[12:15], v57 offset:2560
	ds_read_b128 v[16:19], v57 offset:5120
	ds_read_b128 v[20:23], v57 offset:7680
	ds_read_b128 v[24:27], v56 offset:32
	ds_read_b128 v[28:31], v56 offset:2592
	s_waitcnt lgkmcnt(4)
	v_mfma_f32_32x32x16_bf16 v[66:81], v[0:3], v[8:11], 0
	v_mfma_f32_32x32x16_bf16 v[82:97], v[0:3], v[12:15], 0
	s_waitcnt vmcnt(6)
	ds_write_b128 v58, v[214:217] offset:30720
	ds_write_b128 v58, v[218:221] offset:35840
	s_waitcnt lgkmcnt(4)
	v_mfma_f32_32x32x16_bf16 v[98:113], v[0:3], v[16:19], 0
	v_mfma_f32_32x32x16_bf16 v[114:129], v[0:3], v[20:23], 0
	ds_read_b128 v[0:3], v57 offset:32
	ds_write_b128 v58, v[222:225] offset:40960
	ds_write_b128 v58, v[228:231] offset:46080
	v_mfma_f32_32x32x16_bf16 v[130:145], v[4:7], v[8:11], 0
	v_mfma_f32_32x32x16_bf16 v[146:161], v[4:7], v[12:15], 0
	ds_write_b128 v58, v[232:235] offset:51200
	ds_write_b128 v58, v[236:239] offset:56320
	v_mfma_f32_32x32x16_bf16 v[162:177], v[4:7], v[16:19], 0
	v_mfma_f32_32x32x16_bf16 v[178:193], v[4:7], v[20:23], 0
	ds_read_b128 v[4:7], v57 offset:2592
	ds_read_b128 v[8:11], v57 offset:5152
	ds_read_b128 v[12:15], v57 offset:7712
	s_waitcnt lgkmcnt(2)
	v_mfma_f32_32x32x16_bf16 v[66:81], v[24:27], v[0:3], v[66:81]
	global_load_dwordx4 v[214:217], v[240:241], off offset:2240
	global_load_dwordx4 v[218:221], v[242:243], off offset:2240
	v_mfma_f32_32x32x16_bf16 v[82:97], v[24:27], v[4:7], v[82:97]
	s_waitcnt lgkmcnt(0)
	v_mfma_f32_32x32x16_bf16 v[98:113], v[24:27], v[8:11], v[98:113]
	global_load_dwordx4 v[222:225], v[244:245], off offset:192
	global_load_dwordx4 v[228:231], v[246:247], off offset:192
	v_mfma_f32_32x32x16_bf16 v[114:129], v[24:27], v[12:15], v[114:129]
	v_mfma_f32_32x32x16_bf16 v[130:145], v[28:31], v[0:3], v[130:145]
	global_load_dwordx4 v[232:235], v[248:249], off offset:192
	global_load_dwordx4 v[236:239], v[250:251], off offset:192
	v_mfma_f32_32x32x16_bf16 v[146:161], v[28:31], v[4:7], v[146:161]
	v_mfma_f32_32x32x16_bf16 v[162:177], v[28:31], v[8:11], v[162:177]
	v_mfma_f32_32x32x16_bf16 v[178:193], v[28:31], v[12:15], v[178:193]
	s_waitcnt lgkmcnt(0)
	s_barrier
	ds_read_b128 v[0:3], v56 offset:30720
	ds_read_b128 v[4:7], v56 offset:33280
	ds_read_b128 v[8:11], v57 offset:30720
	ds_read_b128 v[12:15], v57 offset:33280
	ds_read_b128 v[16:19], v57 offset:35840
	ds_read_b128 v[20:23], v57 offset:38400
	ds_read_b128 v[24:27], v56 offset:30752
	ds_read_b128 v[28:31], v56 offset:33312
	s_waitcnt lgkmcnt(4)
	v_mfma_f32_32x32x16_bf16 v[66:81], v[0:3], v[8:11], v[66:81]
	v_mfma_f32_32x32x16_bf16 v[82:97], v[0:3], v[12:15], v[82:97]
	s_waitcnt vmcnt(6)
	ds_write_b128 v58, v[32:35] offset:0
	ds_write_b128 v58, v[36:39] offset:5120
	s_waitcnt lgkmcnt(4)
	v_mfma_f32_32x32x16_bf16 v[98:113], v[0:3], v[16:19], v[98:113]
	v_mfma_f32_32x32x16_bf16 v[114:129], v[0:3], v[20:23], v[114:129]
	ds_read_b128 v[0:3], v57 offset:30752
	ds_write_b128 v58, v[40:43] offset:10240
	ds_write_b128 v58, v[44:47] offset:15360
	v_mfma_f32_32x32x16_bf16 v[130:145], v[4:7], v[8:11], v[130:145]
	v_mfma_f32_32x32x16_bf16 v[146:161], v[4:7], v[12:15], v[146:161]
	ds_write_b128 v58, v[48:51] offset:20480
	ds_write_b128 v58, v[52:55] offset:25600
	v_mfma_f32_32x32x16_bf16 v[162:177], v[4:7], v[16:19], v[162:177]
	v_mfma_f32_32x32x16_bf16 v[178:193], v[4:7], v[20:23], v[178:193]
	ds_read_b128 v[4:7], v57 offset:33312
	ds_read_b128 v[8:11], v57 offset:35872
	ds_read_b128 v[12:15], v57 offset:38432
	s_waitcnt lgkmcnt(2)
	v_mfma_f32_32x32x16_bf16 v[66:81], v[24:27], v[0:3], v[66:81]
	global_load_dwordx4 v[32:35], v[240:241], off offset:2304
	global_load_dwordx4 v[36:39], v[242:243], off offset:2304
	v_mfma_f32_32x32x16_bf16 v[82:97], v[24:27], v[4:7], v[82:97]
	s_waitcnt lgkmcnt(0)
	v_mfma_f32_32x32x16_bf16 v[98:113], v[24:27], v[8:11], v[98:113]
	global_load_dwordx4 v[40:43], v[244:245], off offset:256
	global_load_dwordx4 v[44:47], v[246:247], off offset:256
	v_mfma_f32_32x32x16_bf16 v[114:129], v[24:27], v[12:15], v[114:129]
	v_mfma_f32_32x32x16_bf16 v[130:145], v[28:31], v[0:3], v[130:145]
	global_load_dwordx4 v[48:51], v[248:249], off offset:256
	global_load_dwordx4 v[52:55], v[250:251], off offset:256
	v_mfma_f32_32x32x16_bf16 v[146:161], v[28:31], v[4:7], v[146:161]
	v_mfma_f32_32x32x16_bf16 v[162:177], v[28:31], v[8:11], v[162:177]
	v_mfma_f32_32x32x16_bf16 v[178:193], v[28:31], v[12:15], v[178:193]
	s_waitcnt lgkmcnt(0)
	s_barrier
; #define G_LOAD(S, kt_) do { G_LD1(S##a0, S##b0, 0, kt_); G_LD1(S##a1, S##b1, 1, kt_); G_LD1(S##a2, S##b2, 2, kt_); G_LD1(S##a3, S##b3, 3, kt_); } while (0)
; #define G_STORE(S, buf_) do { G_ST1(S##a0, S##b0, 0, buf_); G_ST1(S##a1, S##b1, 1, buf_); G_ST1(S##a2, S##b2, 2, buf_); G_ST1(S##a3, S##b3, 3, buf_); } while (0)
; template <class AL, class BL>
; DI void gemm_core(AL al, BL bl, int m0, int n0, int K, char* smem, f32x16 (&acc)[2][2]) {
;     ...
;   G_LOAD(x, 0);
;   G_STORE(x, 0);
;   G_LOAD(x, 1);
;   G_LOAD(y, (nk > 2) ? 2 : 1);
;   __syncthreads();
;   for (int kt = 0; kt < nk; kt += 2) {
;     G_TILE(0, x, true, (kt + 3 < nk), kt + 3);
;     __syncthreads();
;     G_TILE(1, y, (kt + 2 < nk), (kt + 4 < nk), kt + 4);
;     __syncthreads();
;   }
	ds_read_b128 v[0:3], v56 offset:0
	ds_read_b128 v[4:7], v56 offset:2560
	ds_read_b128 v[8:11], v57 offset:0
	ds_read_b128 v[12:15], v57 offset:2560
	ds_read_b128 v[16:19], v57 offset:5120
	ds_read_b128 v[20:23], v57 offset:7680
	ds_read_b128 v[24:27], v56 offset:32
	ds_read_b128 v[28:31], v56 offset:2592
	s_waitcnt lgkmcnt(4)
	v_mfma_f32_32x32x16_bf16 v[66:81], v[0:3], v[8:11], v[66:81]
	v_mfma_f32_32x32x16_bf16 v[82:97], v[0:3], v[12:15], v[82:97]
	s_waitcnt vmcnt(6)
	ds_write_b128 v58, v[214:217] offset:30720
	ds_write_b128 v58, v[218:221] offset:35840
	s_waitcnt lgkmcnt(4)
	v_mfma_f32_32x32x16_bf16 v[98:113], v[0:3], v[16:19], v[98:113]
	v_mfma_f32_32x32x16_bf16 v[114:129], v[0:3], v[20:23], v[114:129]
	ds_read_b128 v[0:3], v57 offset:32
	ds_write_b128 v58, v[222:225] offset:40960
	ds_write_b128 v58, v[228:231] offset:46080
	v_mfma_f32_32x32x16_bf16 v[130:145], v[4:7], v[8:11], v[130:145]
	v_mfma_f32_32x32x16_bf16 v[146:161], v[4:7], v[12:15], v[146:161]
	ds_write_b128 v58, v[232:235] offset:51200
	ds_write_b128 v58, v[236:239] offset:56320
	v_mfma_f32_32x32x16_bf16 v[162:177], v[4:7], v[16:19], v[162:177]
	v_mfma_f32_32x32x16_bf16 v[178:193], v[4:7], v[20:23], v[178:193]
	ds_read_b128 v[4:7], v57 offset:2592
	ds_read_b128 v[8:11], v57 offset:5152
	ds_read_b128 v[12:15], v57 offset:7712
	s_waitcnt lgkmcnt(2)
	v_mfma_f32_32x32x16_bf16 v[66:81], v[24:27], v[0:3], v[66:81]
	global_load_dwordx4 v[214:217], v[240:241], off offset:2368
	global_load_dwordx4 v[218:221], v[242:243], off offset:2368
	v_mfma_f32_32x32x16_bf16 v[82:97], v[24:27], v[4:7], v[82:97]
	s_waitcnt lgkmcnt(0)
	v_mfma_f32_32x32x16_bf16 v[98:113], v[24:27], v[8:11], v[98:113]
	global_load_dwordx4 v[222:225], v[244:245], off offset:320
	global_load_dwordx4 v[228:231], v[246:247], off offset:320
	v_mfma_f32_32x32x16_bf16 v[114:129], v[24:27], v[12:15], v[114:129]
	v_mfma_f32_32x32x16_bf16 v[130:145], v[28:31], v[0:3], v[130:145]
	global_load_dwordx4 v[232:235], v[248:249], off offset:320
	global_load_dwordx4 v[236:239], v[250:251], off offset:320
	v_mfma_f32_32x32x16_bf16 v[146:161], v[28:31], v[4:7], v[146:161]
	v_mfma_f32_32x32x16_bf16 v[162:177], v[28:31], v[8:11], v[162:177]
	v_mfma_f32_32x32x16_bf16 v[178:193], v[28:31], v[12:15], v[178:193]
	s_waitcnt lgkmcnt(0)
	s_barrier
	ds_read_b128 v[0:3], v56 offset:30720
	ds_read_b128 v[4:7], v56 offset:33280
	ds_read_b128 v[8:11], v57 offset:30720
	ds_read_b128 v[12:15], v57 offset:33280
	ds_read_b128 v[16:19], v57 offset:35840
	ds_read_b128 v[20:23], v57 offset:38400
	ds_read_b128 v[24:27], v56 offset:30752
	ds_read_b128 v[28:31], v56 offset:33312
	s_waitcnt lgkmcnt(4)
	v_mfma_f32_32x32x16_bf16 v[66:81], v[0:3], v[8:11], v[66:81]
	v_mfma_f32_32x32x16_bf16 v[82:97], v[0:3], v[12:15], v[82:97]
	s_waitcnt vmcnt(6)
	ds_write_b128 v58, v[32:35] offset:0
	ds_write_b128 v58, v[36:39] offset:5120
	s_waitcnt lgkmcnt(4)
	v_mfma_f32_32x32x16_bf16 v[98:113], v[0:3], v[16:19], v[98:113]
	v_mfma_f32_32x32x16_bf16 v[114:129], v[0:3], v[20:23], v[114:129]
	ds_read_b128 v[0:3], v57 offset:30752
	ds_write_b128 v58, v[40:43] offset:10240
	ds_write_b128 v58, v[44:47] offset:15360
	v_mfma_f32_32x32x16_bf16 v[130:145], v[4:7], v[8:11], v[130:145]
	v_mfma_f32_32x32x16_bf16 v[146:161], v[4:7], v[12:15], v[146:161]
	ds_write_b128 v58, v[48:51] offset:20480
	ds_write_b128 v58, v[52:55] offset:25600
	v_mfma_f32_32x32x16_bf16 v[162:177], v[4:7], v[16:19], v[162:177]
	v_mfma_f32_32x32x16_bf16 v[178:193], v[4:7], v[20:23], v[178:193]
	ds_read_b128 v[4:7], v57 offset:33312
	ds_read_b128 v[8:11], v57 offset:35872
	ds_read_b128 v[12:15], v57 offset:38432
	s_waitcnt lgkmcnt(2)
	v_mfma_f32_32x32x16_bf16 v[66:81], v[24:27], v[0:3], v[66:81]
	global_load_dwordx4 v[32:35], v[240:241], off offset:2432
	global_load_dwordx4 v[36:39], v[242:243], off offset:2432
	v_mfma_f32_32x32x16_bf16 v[82:97], v[24:27], v[4:7], v[82:97]
	s_waitcnt lgkmcnt(0)
	v_mfma_f32_32x32x16_bf16 v[98:113], v[24:27], v[8:11], v[98:113]
	global_load_dwordx4 v[40:43], v[244:245], off offset:384
	global_load_dwordx4 v[44:47], v[246:247], off offset:384
	v_mfma_f32_32x32x16_bf16 v[114:129], v[24:27], v[12:15], v[114:129]
	v_mfma_f32_32x32x16_bf16 v[130:145], v[28:31], v[0:3], v[130:145]
	global_load_dwordx4 v[48:51], v[248:249], off offset:384
	global_load_dwordx4 v[52:55], v[250:251], off offset:384
	v_mfma_f32_32x32x16_bf16 v[146:161], v[28:31], v[4:7], v[146:161]
	v_mfma_f32_32x32x16_bf16 v[162:177], v[28:31], v[8:11], v[162:177]
	v_mfma_f32_32x32x16_bf16 v[178:193], v[28:31], v[12:15], v[178:193]
	s_waitcnt lgkmcnt(0)
	s_barrier
; #define G_LOAD(S, kt_) do { G_LD1(S##a0, S##b0, 0, kt_); G_LD1(S##a1, S##b1, 1, kt_); G_LD1(S##a2, S##b2, 2, kt_); G_LD1(S##a3, S##b3, 3, kt_); } while (0)
; #define G_STORE(S, buf_) do { G_ST1(S##a0, S##b0, 0, buf_); G_ST1(S##a1, S##b1, 1, buf_); G_ST1(S##a2, S##b2, 2, buf_); G_ST1(S##a3, S##b3, 3, buf_); } while (0)
; template <class AL, class BL>
; DI void gemm_core(AL al, BL bl, int m0, int n0, int K, char* smem, f32x16 (&acc)[2][2]) {
;     ...
;   G_LOAD(x, 0);
;   G_STORE(x, 0);
;   G_LOAD(x, 1);
;   G_LOAD(y, (nk > 2) ? 2 : 1);
;   __syncthreads();
;   for (int kt = 0; kt < nk; kt += 2) {
;     G_TILE(0, x, true, (kt + 3 < nk), kt + 3);
;     __syncthreads();
;     G_TILE(1, y, (kt + 2 < nk), (kt + 4 < nk), kt + 4);
;     __syncthreads();
;   }
	ds_read_b128 v[0:3], v56 offset:0
	ds_read_b128 v[4:7], v56 offset:2560
	ds_read_b128 v[8:11], v57 offset:0
	ds_read_b128 v[12:15], v57 offset:2560
	ds_read_b128 v[16:19], v57 offset:5120
	ds_read_b128 v[20:23], v57 offset:7680
	ds_read_b128 v[24:27], v56 offset:32
	ds_read_b128 v[28:31], v56 offset:2592
	s_waitcnt lgkmcnt(4)
	v_mfma_f32_32x32x16_bf16 v[66:81], v[0:3], v[8:11], v[66:81]
	v_mfma_f32_32x32x16_bf16 v[82:97], v[0:3], v[12:15], v[82:97]
	s_waitcnt vmcnt(6)
	ds_write_b128 v58, v[214:217] offset:30720
	ds_write_b128 v58, v[218:221] offset:35840
	s_waitcnt lgkmcnt(4)
	v_mfma_f32_32x32x16_bf16 v[98:113], v[0:3], v[16:19], v[98:113]
	v_mfma_f32_32x32x16_bf16 v[114:129], v[0:3], v[20:23], v[114:129]
	ds_read_b128 v[0:3], v57 offset:32
	ds_write_b128 v58, v[222:225] offset:40960
	ds_write_b128 v58, v[228:231] offset:46080
	v_mfma_f32_32x32x16_bf16 v[130:145], v[4:7], v[8:11], v[130:145]
	v_mfma_f32_32x32x16_bf16 v[146:161], v[4:7], v[12:15], v[146:161]
	ds_write_b128 v58, v[232:235] offset:51200
	ds_write_b128 v58, v[236:239] offset:56320
	v_mfma_f32_32x32x16_bf16 v[162:177], v[4:7], v[16:19], v[162:177]
	v_mfma_f32_32x32x16_bf16 v[178:193], v[4:7], v[20:23], v[178:193]
	ds_read_b128 v[4:7], v57 offset:2592
	ds_read_b128 v[8:11], v57 offset:5152
	ds_read_b128 v[12:15], v57 offset:7712
	s_waitcnt lgkmcnt(2)
	v_mfma_f32_32x32x16_bf16 v[66:81], v[24:27], v[0:3], v[66:81]
	global_load_dwordx4 v[214:217], v[240:241], off offset:2496
	global_load_dwordx4 v[218:221], v[242:243], off offset:2496
	v_mfma_f32_32x32x16_bf16 v[82:97], v[24:27], v[4:7], v[82:97]
	s_waitcnt lgkmcnt(0)
	v_mfma_f32_32x32x16_bf16 v[98:113], v[24:27], v[8:11], v[98:113]
	global_load_dwordx4 v[222:225], v[244:245], off offset:448
	global_load_dwordx4 v[228:231], v[246:247], off offset:448
	v_mfma_f32_32x32x16_bf16 v[114:129], v[24:27], v[12:15], v[114:129]
	v_mfma_f32_32x32x16_bf16 v[130:145], v[28:31], v[0:3], v[130:145]
	global_load_dwordx4 v[232:235], v[248:249], off offset:448
	global_load_dwordx4 v[236:239], v[250:251], off offset:448
	v_mfma_f32_32x32x16_bf16 v[146:161], v[28:31], v[4:7], v[146:161]
	v_mfma_f32_32x32x16_bf16 v[162:177], v[28:31], v[8:11], v[162:177]
	v_mfma_f32_32x32x16_bf16 v[178:193], v[28:31], v[12:15], v[178:193]
	s_waitcnt lgkmcnt(0)
	s_barrier
	ds_read_b128 v[0:3], v56 offset:30720
	ds_read_b128 v[4:7], v56 offset:33280
	ds_read_b128 v[8:11], v57 offset:30720
	ds_read_b128 v[12:15], v57 offset:33280
	ds_read_b128 v[16:19], v57 offset:35840
	ds_read_b128 v[20:23], v57 offset:38400
	ds_read_b128 v[24:27], v56 offset:30752
	ds_read_b128 v[28:31], v56 offset:33312
	s_waitcnt lgkmcnt(4)
	v_mfma_f32_32x32x16_bf16 v[66:81], v[0:3], v[8:11], v[66:81]
	v_mfma_f32_32x32x16_bf16 v[82:97], v[0:3], v[12:15], v[82:97]
	s_waitcnt vmcnt(6)
	ds_write_b128 v58, v[32:35] offset:0
	ds_write_b128 v58, v[36:39] offset:5120
	s_waitcnt lgkmcnt(4)
	v_mfma_f32_32x32x16_bf16 v[98:113], v[0:3], v[16:19], v[98:113]
	v_mfma_f32_32x32x16_bf16 v[114:129], v[0:3], v[20:23], v[114:129]
	ds_read_b128 v[0:3], v57 offset:30752
	ds_write_b128 v58, v[40:43] offset:10240
	ds_write_b128 v58, v[44:47] offset:15360
	v_mfma_f32_32x32x16_bf16 v[130:145], v[4:7], v[8:11], v[130:145]
	v_mfma_f32_32x32x16_bf16 v[146:161], v[4:7], v[12:15], v[146:161]
	ds_write_b128 v58, v[48:51] offset:20480
	ds_write_b128 v58, v[52:55] offset:25600
	v_mfma_f32_32x32x16_bf16 v[162:177], v[4:7], v[16:19], v[162:177]
	v_mfma_f32_32x32x16_bf16 v[178:193], v[4:7], v[20:23], v[178:193]
	ds_read_b128 v[4:7], v57 offset:33312
	ds_read_b128 v[8:11], v57 offset:35872
	ds_read_b128 v[12:15], v57 offset:38432
	s_waitcnt lgkmcnt(2)
	v_mfma_f32_32x32x16_bf16 v[66:81], v[24:27], v[0:3], v[66:81]
	global_load_dwordx4 v[32:35], v[240:241], off offset:2560
	global_load_dwordx4 v[36:39], v[242:243], off offset:2560
	v_mfma_f32_32x32x16_bf16 v[82:97], v[24:27], v[4:7], v[82:97]
	s_waitcnt lgkmcnt(0)
	v_mfma_f32_32x32x16_bf16 v[98:113], v[24:27], v[8:11], v[98:113]
	global_load_dwordx4 v[40:43], v[244:245], off offset:512
	global_load_dwordx4 v[44:47], v[246:247], off offset:512
	v_mfma_f32_32x32x16_bf16 v[114:129], v[24:27], v[12:15], v[114:129]
	v_mfma_f32_32x32x16_bf16 v[130:145], v[28:31], v[0:3], v[130:145]
	global_load_dwordx4 v[48:51], v[248:249], off offset:512
	global_load_dwordx4 v[52:55], v[250:251], off offset:512
	v_mfma_f32_32x32x16_bf16 v[146:161], v[28:31], v[4:7], v[146:161]
	v_mfma_f32_32x32x16_bf16 v[162:177], v[28:31], v[8:11], v[162:177]
	v_mfma_f32_32x32x16_bf16 v[178:193], v[28:31], v[12:15], v[178:193]
	s_waitcnt lgkmcnt(0)
	s_barrier
; #define G_LOAD(S, kt_) do { G_LD1(S##a0, S##b0, 0, kt_); G_LD1(S##a1, S##b1, 1, kt_); G_LD1(S##a2, S##b2, 2, kt_); G_LD1(S##a3, S##b3, 3, kt_); } while (0)
; #define G_STORE(S, buf_) do { G_ST1(S##a0, S##b0, 0, buf_); G_ST1(S##a1, S##b1, 1, buf_); G_ST1(S##a2, S##b2, 2, buf_); G_ST1(S##a3, S##b3, 3, buf_); } while (0)
; template <class AL, class BL>
; DI void gemm_core(AL al, BL bl, int m0, int n0, int K, char* smem, f32x16 (&acc)[2][2]) {
;     ...
;   G_LOAD(x, 0);
;   G_STORE(x, 0);
;   G_LOAD(x, 1);
;   G_LOAD(y, (nk > 2) ? 2 : 1);
;   __syncthreads();
;   for (int kt = 0; kt < nk; kt += 2) {
;     G_TILE(0, x, true, (kt + 3 < nk), kt + 3);
;     __syncthreads();
;     G_TILE(1, y, (kt + 2 < nk), (kt + 4 < nk), kt + 4);
;     __syncthreads();
;   }
	ds_read_b128 v[0:3], v56 offset:0
	ds_read_b128 v[4:7], v56 offset:2560
	ds_read_b128 v[8:11], v57 offset:0
	ds_read_b128 v[12:15], v57 offset:2560
	ds_read_b128 v[16:19], v57 offset:5120
	ds_read_b128 v[20:23], v57 offset:7680
	ds_read_b128 v[24:27], v56 offset:32
	ds_read_b128 v[28:31], v56 offset:2592
	s_waitcnt lgkmcnt(4)
	v_mfma_f32_32x32x16_bf16 v[66:81], v[0:3], v[8:11], v[66:81]
	v_mfma_f32_32x32x16_bf16 v[82:97], v[0:3], v[12:15], v[82:97]
	s_waitcnt vmcnt(6)
	ds_write_b128 v58, v[214:217] offset:30720
	ds_write_b128 v58, v[218:221] offset:35840
	s_waitcnt lgkmcnt(4)
	v_mfma_f32_32x32x16_bf16 v[98:113], v[0:3], v[16:19], v[98:113]
	v_mfma_f32_32x32x16_bf16 v[114:129], v[0:3], v[20:23], v[114:129]
	ds_read_b128 v[0:3], v57 offset:32
	ds_write_b128 v58, v[222:225] offset:40960
	ds_write_b128 v58, v[228:231] offset:46080
	v_mfma_f32_32x32x16_bf16 v[130:145], v[4:7], v[8:11], v[130:145]
	v_mfma_f32_32x32x16_bf16 v[146:161], v[4:7], v[12:15], v[146:161]
	ds_write_b128 v58, v[232:235] offset:51200
	ds_write_b128 v58, v[236:239] offset:56320
	v_mfma_f32_32x32x16_bf16 v[162:177], v[4:7], v[16:19], v[162:177]
	v_mfma_f32_32x32x16_bf16 v[178:193], v[4:7], v[20:23], v[178:193]
	ds_read_b128 v[4:7], v57 offset:2592
	ds_read_b128 v[8:11], v57 offset:5152
	ds_read_b128 v[12:15], v57 offset:7712
	s_waitcnt lgkmcnt(2)
	v_mfma_f32_32x32x16_bf16 v[66:81], v[24:27], v[0:3], v[66:81]
	global_load_dwordx4 v[214:217], v[240:241], off offset:2624
	global_load_dwordx4 v[218:221], v[242:243], off offset:2624
	v_mfma_f32_32x32x16_bf16 v[82:97], v[24:27], v[4:7], v[82:97]
	s_waitcnt lgkmcnt(0)
	v_mfma_f32_32x32x16_bf16 v[98:113], v[24:27], v[8:11], v[98:113]
	global_load_dwordx4 v[222:225], v[244:245], off offset:576
	global_load_dwordx4 v[228:231], v[246:247], off offset:576
	v_mfma_f32_32x32x16_bf16 v[114:129], v[24:27], v[12:15], v[114:129]
	v_mfma_f32_32x32x16_bf16 v[130:145], v[28:31], v[0:3], v[130:145]
	global_load_dwordx4 v[232:235], v[248:249], off offset:576
	global_load_dwordx4 v[236:239], v[250:251], off offset:576
	v_mfma_f32_32x32x16_bf16 v[146:161], v[28:31], v[4:7], v[146:161]
	v_mfma_f32_32x32x16_bf16 v[162:177], v[28:31], v[8:11], v[162:177]
	v_mfma_f32_32x32x16_bf16 v[178:193], v[28:31], v[12:15], v[178:193]
	s_waitcnt lgkmcnt(0)
	s_barrier
	ds_read_b128 v[0:3], v56 offset:30720
	ds_read_b128 v[4:7], v56 offset:33280
	ds_read_b128 v[8:11], v57 offset:30720
	ds_read_b128 v[12:15], v57 offset:33280
	ds_read_b128 v[16:19], v57 offset:35840
	ds_read_b128 v[20:23], v57 offset:38400
	ds_read_b128 v[24:27], v56 offset:30752
	ds_read_b128 v[28:31], v56 offset:33312
	s_waitcnt lgkmcnt(4)
	v_mfma_f32_32x32x16_bf16 v[66:81], v[0:3], v[8:11], v[66:81]
	v_mfma_f32_32x32x16_bf16 v[82:97], v[0:3], v[12:15], v[82:97]
	s_waitcnt vmcnt(6)
	ds_write_b128 v58, v[32:35] offset:0
	ds_write_b128 v58, v[36:39] offset:5120
	s_waitcnt lgkmcnt(4)
	v_mfma_f32_32x32x16_bf16 v[98:113], v[0:3], v[16:19], v[98:113]
	v_mfma_f32_32x32x16_bf16 v[114:129], v[0:3], v[20:23], v[114:129]
	ds_read_b128 v[0:3], v57 offset:30752
	ds_write_b128 v58, v[40:43] offset:10240
	ds_write_b128 v58, v[44:47] offset:15360
	v_mfma_f32_32x32x16_bf16 v[130:145], v[4:7], v[8:11], v[130:145]
	v_mfma_f32_32x32x16_bf16 v[146:161], v[4:7], v[12:15], v[146:161]
	ds_write_b128 v58, v[48:51] offset:20480
	ds_write_b128 v58, v[52:55] offset:25600
	v_mfma_f32_32x32x16_bf16 v[162:177], v[4:7], v[16:19], v[162:177]
	v_mfma_f32_32x32x16_bf16 v[178:193], v[4:7], v[20:23], v[178:193]
	ds_read_b128 v[4:7], v57 offset:33312
	ds_read_b128 v[8:11], v57 offset:35872
	ds_read_b128 v[12:15], v57 offset:38432
	s_waitcnt lgkmcnt(2)
	v_mfma_f32_32x32x16_bf16 v[66:81], v[24:27], v[0:3], v[66:81]
	global_load_dwordx4 v[32:35], v[240:241], off offset:2688
	global_load_dwordx4 v[36:39], v[242:243], off offset:2688
	v_mfma_f32_32x32x16_bf16 v[82:97], v[24:27], v[4:7], v[82:97]
	s_waitcnt lgkmcnt(0)
	v_mfma_f32_32x32x16_bf16 v[98:113], v[24:27], v[8:11], v[98:113]
	global_load_dwordx4 v[40:43], v[244:245], off offset:640
	global_load_dwordx4 v[44:47], v[246:247], off offset:640
	v_mfma_f32_32x32x16_bf16 v[114:129], v[24:27], v[12:15], v[114:129]
	v_mfma_f32_32x32x16_bf16 v[130:145], v[28:31], v[0:3], v[130:145]
	global_load_dwordx4 v[48:51], v[248:249], off offset:640
	global_load_dwordx4 v[52:55], v[250:251], off offset:640
	v_mfma_f32_32x32x16_bf16 v[146:161], v[28:31], v[4:7], v[146:161]
	v_mfma_f32_32x32x16_bf16 v[162:177], v[28:31], v[8:11], v[162:177]
	v_mfma_f32_32x32x16_bf16 v[178:193], v[28:31], v[12:15], v[178:193]
	s_waitcnt lgkmcnt(0)
	s_barrier
; #define G_LOAD(S, kt_) do { G_LD1(S##a0, S##b0, 0, kt_); G_LD1(S##a1, S##b1, 1, kt_); G_LD1(S##a2, S##b2, 2, kt_); G_LD1(S##a3, S##b3, 3, kt_); } while (0)
; #define G_STORE(S, buf_) do { G_ST1(S##a0, S##b0, 0, buf_); G_ST1(S##a1, S##b1, 1, buf_); G_ST1(S##a2, S##b2, 2, buf_); G_ST1(S##a3, S##b3, 3, buf_); } while (0)
; template <class AL, class BL>
; DI void gemm_core(AL al, BL bl, int m0, int n0, int K, char* smem, f32x16 (&acc)[2][2]) {
;     ...
;   G_LOAD(x, 0);
;   G_STORE(x, 0);
;   G_LOAD(x, 1);
;   G_LOAD(y, (nk > 2) ? 2 : 1);
;   __syncthreads();
;   for (int kt = 0; kt < nk; kt += 2) {
;     G_TILE(0, x, true, (kt + 3 < nk), kt + 3);
;     __syncthreads();
;     G_TILE(1, y, (kt + 2 < nk), (kt + 4 < nk), kt + 4);
;     __syncthreads();
;   }
	ds_read_b128 v[0:3], v56 offset:0
	ds_read_b128 v[4:7], v56 offset:2560
	ds_read_b128 v[8:11], v57 offset:0
	ds_read_b128 v[12:15], v57 offset:2560
	ds_read_b128 v[16:19], v57 offset:5120
	ds_read_b128 v[20:23], v57 offset:7680
	ds_read_b128 v[24:27], v56 offset:32
	ds_read_b128 v[28:31], v56 offset:2592
	s_waitcnt lgkmcnt(4)
	v_mfma_f32_32x32x16_bf16 v[66:81], v[0:3], v[8:11], v[66:81]
	v_mfma_f32_32x32x16_bf16 v[82:97], v[0:3], v[12:15], v[82:97]
	s_waitcnt vmcnt(6)
	ds_write_b128 v58, v[214:217] offset:30720
	ds_write_b128 v58, v[218:221] offset:35840
	s_waitcnt lgkmcnt(4)
	v_mfma_f32_32x32x16_bf16 v[98:113], v[0:3], v[16:19], v[98:113]
	v_mfma_f32_32x32x16_bf16 v[114:129], v[0:3], v[20:23], v[114:129]
	ds_read_b128 v[0:3], v57 offset:32
	ds_write_b128 v58, v[222:225] offset:40960
	ds_write_b128 v58, v[228:231] offset:46080
	v_mfma_f32_32x32x16_bf16 v[130:145], v[4:7], v[8:11], v[130:145]
	v_mfma_f32_32x32x16_bf16 v[146:161], v[4:7], v[12:15], v[146:161]
	ds_write_b128 v58, v[232:235] offset:51200
	ds_write_b128 v58, v[236:239] offset:56320
	v_mfma_f32_32x32x16_bf16 v[162:177], v[4:7], v[16:19], v[162:177]
	v_mfma_f32_32x32x16_bf16 v[178:193], v[4:7], v[20:23], v[178:193]
	ds_read_b128 v[4:7], v57 offset:2592
	ds_read_b128 v[8:11], v57 offset:5152
	ds_read_b128 v[12:15], v57 offset:7712
	s_waitcnt lgkmcnt(2)
	v_mfma_f32_32x32x16_bf16 v[66:81], v[24:27], v[0:3], v[66:81]
	global_load_dwordx4 v[214:217], v[240:241], off offset:2752
	global_load_dwordx4 v[218:221], v[242:243], off offset:2752
	v_mfma_f32_32x32x16_bf16 v[82:97], v[24:27], v[4:7], v[82:97]
	s_waitcnt lgkmcnt(0)
	v_mfma_f32_32x32x16_bf16 v[98:113], v[24:27], v[8:11], v[98:113]
	global_load_dwordx4 v[222:225], v[244:245], off offset:704
	global_load_dwordx4 v[228:231], v[246:247], off offset:704
	v_mfma_f32_32x32x16_bf16 v[114:129], v[24:27], v[12:15], v[114:129]
	v_mfma_f32_32x32x16_bf16 v[130:145], v[28:31], v[0:3], v[130:145]
	global_load_dwordx4 v[232:235], v[248:249], off offset:704
	global_load_dwordx4 v[236:239], v[250:251], off offset:704
	v_mfma_f32_32x32x16_bf16 v[146:161], v[28:31], v[4:7], v[146:161]
	v_mfma_f32_32x32x16_bf16 v[162:177], v[28:31], v[8:11], v[162:177]
	v_mfma_f32_32x32x16_bf16 v[178:193], v[28:31], v[12:15], v[178:193]
	s_waitcnt lgkmcnt(0)
	s_barrier
	ds_read_b128 v[0:3], v56 offset:30720
	ds_read_b128 v[4:7], v56 offset:33280
	ds_read_b128 v[8:11], v57 offset:30720
	ds_read_b128 v[12:15], v57 offset:33280
	ds_read_b128 v[16:19], v57 offset:35840
	ds_read_b128 v[20:23], v57 offset:38400
	ds_read_b128 v[24:27], v56 offset:30752
	ds_read_b128 v[28:31], v56 offset:33312
	s_waitcnt lgkmcnt(4)
	v_mfma_f32_32x32x16_bf16 v[66:81], v[0:3], v[8:11], v[66:81]
	v_mfma_f32_32x32x16_bf16 v[82:97], v[0:3], v[12:15], v[82:97]
	s_waitcnt vmcnt(6)
	ds_write_b128 v58, v[32:35] offset:0
	ds_write_b128 v58, v[36:39] offset:5120
	s_waitcnt lgkmcnt(4)
	v_mfma_f32_32x32x16_bf16 v[98:113], v[0:3], v[16:19], v[98:113]
	v_mfma_f32_32x32x16_bf16 v[114:129], v[0:3], v[20:23], v[114:129]
	ds_read_b128 v[0:3], v57 offset:30752
	ds_write_b128 v58, v[40:43] offset:10240
	ds_write_b128 v58, v[44:47] offset:15360
	v_mfma_f32_32x32x16_bf16 v[130:145], v[4:7], v[8:11], v[130:145]
	v_mfma_f32_32x32x16_bf16 v[146:161], v[4:7], v[12:15], v[146:161]
	ds_write_b128 v58, v[48:51] offset:20480
	ds_write_b128 v58, v[52:55] offset:25600
	v_mfma_f32_32x32x16_bf16 v[162:177], v[4:7], v[16:19], v[162:177]
	v_mfma_f32_32x32x16_bf16 v[178:193], v[4:7], v[20:23], v[178:193]
	ds_read_b128 v[4:7], v57 offset:33312
	ds_read_b128 v[8:11], v57 offset:35872
	ds_read_b128 v[12:15], v57 offset:38432
	s_waitcnt lgkmcnt(2)
	v_mfma_f32_32x32x16_bf16 v[66:81], v[24:27], v[0:3], v[66:81]
	global_load_dwordx4 v[32:35], v[240:241], off offset:2816
	global_load_dwordx4 v[36:39], v[242:243], off offset:2816
	v_mfma_f32_32x32x16_bf16 v[82:97], v[24:27], v[4:7], v[82:97]
	s_waitcnt lgkmcnt(0)
	v_mfma_f32_32x32x16_bf16 v[98:113], v[24:27], v[8:11], v[98:113]
	global_load_dwordx4 v[40:43], v[244:245], off offset:768
	global_load_dwordx4 v[44:47], v[246:247], off offset:768
	v_mfma_f32_32x32x16_bf16 v[114:129], v[24:27], v[12:15], v[114:129]
	v_mfma_f32_32x32x16_bf16 v[130:145], v[28:31], v[0:3], v[130:145]
	global_load_dwordx4 v[48:51], v[248:249], off offset:768
	global_load_dwordx4 v[52:55], v[250:251], off offset:768
	v_mfma_f32_32x32x16_bf16 v[146:161], v[28:31], v[4:7], v[146:161]
	v_mfma_f32_32x32x16_bf16 v[162:177], v[28:31], v[8:11], v[162:177]
	v_mfma_f32_32x32x16_bf16 v[178:193], v[28:31], v[12:15], v[178:193]
	s_waitcnt lgkmcnt(0)
	s_barrier
; #define G_LOAD(S, kt_) do { G_LD1(S##a0, S##b0, 0, kt_); G_LD1(S##a1, S##b1, 1, kt_); G_LD1(S##a2, S##b2, 2, kt_); G_LD1(S##a3, S##b3, 3, kt_); } while (0)
; #define G_STORE(S, buf_) do { G_ST1(S##a0, S##b0, 0, buf_); G_ST1(S##a1, S##b1, 1, buf_); G_ST1(S##a2, S##b2, 2, buf_); G_ST1(S##a3, S##b3, 3, buf_); } while (0)
; template <class AL, class BL>
; DI void gemm_core(AL al, BL bl, int m0, int n0, int K, char* smem, f32x16 (&acc)[2][2]) {
;     ...
;   G_LOAD(x, 0);
;   G_STORE(x, 0);
;   G_LOAD(x, 1);
;   G_LOAD(y, (nk > 2) ? 2 : 1);
;   __syncthreads();
;   for (int kt = 0; kt < nk; kt += 2) {
;     G_TILE(0, x, true, (kt + 3 < nk), kt + 3);
;     __syncthreads();
;     G_TILE(1, y, (kt + 2 < nk), (kt + 4 < nk), kt + 4);
;     __syncthreads();
;   }
	ds_read_b128 v[0:3], v56 offset:0
	ds_read_b128 v[4:7], v56 offset:2560
	ds_read_b128 v[8:11], v57 offset:0
	ds_read_b128 v[12:15], v57 offset:2560
	ds_read_b128 v[16:19], v57 offset:5120
	ds_read_b128 v[20:23], v57 offset:7680
	ds_read_b128 v[24:27], v56 offset:32
	ds_read_b128 v[28:31], v56 offset:2592
	s_waitcnt lgkmcnt(4)
	v_mfma_f32_32x32x16_bf16 v[66:81], v[0:3], v[8:11], v[66:81]
	v_mfma_f32_32x32x16_bf16 v[82:97], v[0:3], v[12:15], v[82:97]
	s_waitcnt vmcnt(6)
	ds_write_b128 v58, v[214:217] offset:30720
	ds_write_b128 v58, v[218:221] offset:35840
	s_waitcnt lgkmcnt(4)
	v_mfma_f32_32x32x16_bf16 v[98:113], v[0:3], v[16:19], v[98:113]
	v_mfma_f32_32x32x16_bf16 v[114:129], v[0:3], v[20:23], v[114:129]
	ds_read_b128 v[0:3], v57 offset:32
	ds_write_b128 v58, v[222:225] offset:40960
	ds_write_b128 v58, v[228:231] offset:46080
	v_mfma_f32_32x32x16_bf16 v[130:145], v[4:7], v[8:11], v[130:145]
	v_mfma_f32_32x32x16_bf16 v[146:161], v[4:7], v[12:15], v[146:161]
	ds_write_b128 v58, v[232:235] offset:51200
	ds_write_b128 v58, v[236:239] offset:56320
	v_mfma_f32_32x32x16_bf16 v[162:177], v[4:7], v[16:19], v[162:177]
	v_mfma_f32_32x32x16_bf16 v[178:193], v[4:7], v[20:23], v[178:193]
	ds_read_b128 v[4:7], v57 offset:2592
	ds_read_b128 v[8:11], v57 offset:5152
	ds_read_b128 v[12:15], v57 offset:7712
	s_waitcnt lgkmcnt(2)
	v_mfma_f32_32x32x16_bf16 v[66:81], v[24:27], v[0:3], v[66:81]
	global_load_dwordx4 v[214:217], v[240:241], off offset:2880
	global_load_dwordx4 v[218:221], v[242:243], off offset:2880
	v_mfma_f32_32x32x16_bf16 v[82:97], v[24:27], v[4:7], v[82:97]
	s_waitcnt lgkmcnt(0)
	v_mfma_f32_32x32x16_bf16 v[98:113], v[24:27], v[8:11], v[98:113]
	global_load_dwordx4 v[222:225], v[244:245], off offset:832
	global_load_dwordx4 v[228:231], v[246:247], off offset:832
	v_mfma_f32_32x32x16_bf16 v[114:129], v[24:27], v[12:15], v[114:129]
	v_mfma_f32_32x32x16_bf16 v[130:145], v[28:31], v[0:3], v[130:145]
	global_load_dwordx4 v[232:235], v[248:249], off offset:832
	global_load_dwordx4 v[236:239], v[250:251], off offset:832
	v_mfma_f32_32x32x16_bf16 v[146:161], v[28:31], v[4:7], v[146:161]
	v_mfma_f32_32x32x16_bf16 v[162:177], v[28:31], v[8:11], v[162:177]
	v_mfma_f32_32x32x16_bf16 v[178:193], v[28:31], v[12:15], v[178:193]
	s_waitcnt lgkmcnt(0)
	s_barrier
	ds_read_b128 v[0:3], v56 offset:30720
	ds_read_b128 v[4:7], v56 offset:33280
	ds_read_b128 v[8:11], v57 offset:30720
	ds_read_b128 v[12:15], v57 offset:33280
	ds_read_b128 v[16:19], v57 offset:35840
	ds_read_b128 v[20:23], v57 offset:38400
	ds_read_b128 v[24:27], v56 offset:30752
	ds_read_b128 v[28:31], v56 offset:33312
	s_waitcnt lgkmcnt(4)
	v_mfma_f32_32x32x16_bf16 v[66:81], v[0:3], v[8:11], v[66:81]
	v_mfma_f32_32x32x16_bf16 v[82:97], v[0:3], v[12:15], v[82:97]
	s_waitcnt vmcnt(6)
	ds_write_b128 v58, v[32:35] offset:0
	ds_write_b128 v58, v[36:39] offset:5120
	s_waitcnt lgkmcnt(4)
	v_mfma_f32_32x32x16_bf16 v[98:113], v[0:3], v[16:19], v[98:113]
	v_mfma_f32_32x32x16_bf16 v[114:129], v[0:3], v[20:23], v[114:129]
	ds_read_b128 v[0:3], v57 offset:30752
	ds_write_b128 v58, v[40:43] offset:10240
	ds_write_b128 v58, v[44:47] offset:15360
	v_mfma_f32_32x32x16_bf16 v[130:145], v[4:7], v[8:11], v[130:145]
	v_mfma_f32_32x32x16_bf16 v[146:161], v[4:7], v[12:15], v[146:161]
	ds_write_b128 v58, v[48:51] offset:20480
	ds_write_b128 v58, v[52:55] offset:25600
	v_mfma_f32_32x32x16_bf16 v[162:177], v[4:7], v[16:19], v[162:177]
	v_mfma_f32_32x32x16_bf16 v[178:193], v[4:7], v[20:23], v[178:193]
	ds_read_b128 v[4:7], v57 offset:33312
	ds_read_b128 v[8:11], v57 offset:35872
	ds_read_b128 v[12:15], v57 offset:38432
	s_waitcnt lgkmcnt(2)
	v_mfma_f32_32x32x16_bf16 v[66:81], v[24:27], v[0:3], v[66:81]
	global_load_dwordx4 v[32:35], v[240:241], off offset:2944
	global_load_dwordx4 v[36:39], v[242:243], off offset:2944
	v_mfma_f32_32x32x16_bf16 v[82:97], v[24:27], v[4:7], v[82:97]
	s_waitcnt lgkmcnt(0)
	v_mfma_f32_32x32x16_bf16 v[98:113], v[24:27], v[8:11], v[98:113]
	global_load_dwordx4 v[40:43], v[244:245], off offset:896
	global_load_dwordx4 v[44:47], v[246:247], off offset:896
	v_mfma_f32_32x32x16_bf16 v[114:129], v[24:27], v[12:15], v[114:129]
	v_mfma_f32_32x32x16_bf16 v[130:145], v[28:31], v[0:3], v[130:145]
	global_load_dwordx4 v[48:51], v[248:249], off offset:896
	global_load_dwordx4 v[52:55], v[250:251], off offset:896
	v_mfma_f32_32x32x16_bf16 v[146:161], v[28:31], v[4:7], v[146:161]
	v_mfma_f32_32x32x16_bf16 v[162:177], v[28:31], v[8:11], v[162:177]
	v_mfma_f32_32x32x16_bf16 v[178:193], v[28:31], v[12:15], v[178:193]
	s_waitcnt lgkmcnt(0)
	s_barrier
; #define G_LOAD(S, kt_) do { G_LD1(S##a0, S##b0, 0, kt_); G_LD1(S##a1, S##b1, 1, kt_); G_LD1(S##a2, S##b2, 2, kt_); G_LD1(S##a3, S##b3, 3, kt_); } while (0)
; #define G_STORE(S, buf_) do { G_ST1(S##a0, S##b0, 0, buf_); G_ST1(S##a1, S##b1, 1, buf_); G_ST1(S##a2, S##b2, 2, buf_); G_ST1(S##a3, S##b3, 3, buf_); } while (0)
; template <class AL, class BL>
; DI void gemm_core(AL al, BL bl, int m0, int n0, int K, char* smem, f32x16 (&acc)[2][2]) {
;     ...
;   G_LOAD(x, 0);
;   G_STORE(x, 0);
;   G_LOAD(x, 1);
;   G_LOAD(y, (nk > 2) ? 2 : 1);
;   __syncthreads();
;   for (int kt = 0; kt < nk; kt += 2) {
;     G_TILE(0, x, true, (kt + 3 < nk), kt + 3);
;     __syncthreads();
;     G_TILE(1, y, (kt + 2 < nk), (kt + 4 < nk), kt + 4);
;     __syncthreads();
;   }
	ds_read_b128 v[0:3], v56 offset:0
	ds_read_b128 v[4:7], v56 offset:2560
	ds_read_b128 v[8:11], v57 offset:0
	ds_read_b128 v[12:15], v57 offset:2560
	ds_read_b128 v[16:19], v57 offset:5120
	ds_read_b128 v[20:23], v57 offset:7680
	ds_read_b128 v[24:27], v56 offset:32
	ds_read_b128 v[28:31], v56 offset:2592
	s_waitcnt lgkmcnt(4)
	v_mfma_f32_32x32x16_bf16 v[66:81], v[0:3], v[8:11], v[66:81]
	v_mfma_f32_32x32x16_bf16 v[82:97], v[0:3], v[12:15], v[82:97]
	s_waitcnt vmcnt(6)
	ds_write_b128 v58, v[214:217] offset:30720
	ds_write_b128 v58, v[218:221] offset:35840
	s_waitcnt lgkmcnt(4)
	v_mfma_f32_32x32x16_bf16 v[98:113], v[0:3], v[16:19], v[98:113]
	v_mfma_f32_32x32x16_bf16 v[114:129], v[0:3], v[20:23], v[114:129]
	ds_read_b128 v[0:3], v57 offset:32
	ds_write_b128 v58, v[222:225] offset:40960
	ds_write_b128 v58, v[228:231] offset:46080
	v_mfma_f32_32x32x16_bf16 v[130:145], v[4:7], v[8:11], v[130:145]
	v_mfma_f32_32x32x16_bf16 v[146:161], v[4:7], v[12:15], v[146:161]
	ds_write_b128 v58, v[232:235] offset:51200
	ds_write_b128 v58, v[236:239] offset:56320
	v_mfma_f32_32x32x16_bf16 v[162:177], v[4:7], v[16:19], v[162:177]
	v_mfma_f32_32x32x16_bf16 v[178:193], v[4:7], v[20:23], v[178:193]
	ds_read_b128 v[4:7], v57 offset:2592
	ds_read_b128 v[8:11], v57 offset:5152
	ds_read_b128 v[12:15], v57 offset:7712
	s_waitcnt lgkmcnt(2)
	v_mfma_f32_32x32x16_bf16 v[66:81], v[24:27], v[0:3], v[66:81]
	global_load_dwordx4 v[214:217], v[240:241], off offset:3008
	global_load_dwordx4 v[218:221], v[242:243], off offset:3008
	v_mfma_f32_32x32x16_bf16 v[82:97], v[24:27], v[4:7], v[82:97]
	s_waitcnt lgkmcnt(0)
	v_mfma_f32_32x32x16_bf16 v[98:113], v[24:27], v[8:11], v[98:113]
	global_load_dwordx4 v[222:225], v[244:245], off offset:960
	global_load_dwordx4 v[228:231], v[246:247], off offset:960
	v_mfma_f32_32x32x16_bf16 v[114:129], v[24:27], v[12:15], v[114:129]
	v_mfma_f32_32x32x16_bf16 v[130:145], v[28:31], v[0:3], v[130:145]
	global_load_dwordx4 v[232:235], v[248:249], off offset:960
	global_load_dwordx4 v[236:239], v[250:251], off offset:960
	v_mfma_f32_32x32x16_bf16 v[146:161], v[28:31], v[4:7], v[146:161]
	v_mfma_f32_32x32x16_bf16 v[162:177], v[28:31], v[8:11], v[162:177]
	v_mfma_f32_32x32x16_bf16 v[178:193], v[28:31], v[12:15], v[178:193]
	s_waitcnt lgkmcnt(0)
	s_barrier
	ds_read_b128 v[0:3], v56 offset:30720
	ds_read_b128 v[4:7], v56 offset:33280
	ds_read_b128 v[8:11], v57 offset:30720
	ds_read_b128 v[12:15], v57 offset:33280
	ds_read_b128 v[16:19], v57 offset:35840
	ds_read_b128 v[20:23], v57 offset:38400
	ds_read_b128 v[24:27], v56 offset:30752
	ds_read_b128 v[28:31], v56 offset:33312
	s_waitcnt lgkmcnt(4)
	v_mfma_f32_32x32x16_bf16 v[66:81], v[0:3], v[8:11], v[66:81]
	v_mfma_f32_32x32x16_bf16 v[82:97], v[0:3], v[12:15], v[82:97]
	s_waitcnt vmcnt(6)
	ds_write_b128 v58, v[32:35] offset:0
	ds_write_b128 v58, v[36:39] offset:5120
	s_waitcnt lgkmcnt(4)
	v_mfma_f32_32x32x16_bf16 v[98:113], v[0:3], v[16:19], v[98:113]
	v_mfma_f32_32x32x16_bf16 v[114:129], v[0:3], v[20:23], v[114:129]
	ds_read_b128 v[0:3], v57 offset:30752
	ds_write_b128 v58, v[40:43] offset:10240
	ds_write_b128 v58, v[44:47] offset:15360
	v_mfma_f32_32x32x16_bf16 v[130:145], v[4:7], v[8:11], v[130:145]
	v_mfma_f32_32x32x16_bf16 v[146:161], v[4:7], v[12:15], v[146:161]
	ds_write_b128 v58, v[48:51] offset:20480
	ds_write_b128 v58, v[52:55] offset:25600
	v_mfma_f32_32x32x16_bf16 v[162:177], v[4:7], v[16:19], v[162:177]
	v_mfma_f32_32x32x16_bf16 v[178:193], v[4:7], v[20:23], v[178:193]
	ds_read_b128 v[4:7], v57 offset:33312
	ds_read_b128 v[8:11], v57 offset:35872
	ds_read_b128 v[12:15], v57 offset:38432
	s_waitcnt lgkmcnt(2)
	v_mfma_f32_32x32x16_bf16 v[66:81], v[24:27], v[0:3], v[66:81]
	global_load_dwordx4 v[32:35], v[240:241], off offset:3072
	global_load_dwordx4 v[36:39], v[242:243], off offset:3072
	v_mfma_f32_32x32x16_bf16 v[82:97], v[24:27], v[4:7], v[82:97]
	s_waitcnt lgkmcnt(0)
	v_mfma_f32_32x32x16_bf16 v[98:113], v[24:27], v[8:11], v[98:113]
	global_load_dwordx4 v[40:43], v[244:245], off offset:1024
	global_load_dwordx4 v[44:47], v[246:247], off offset:1024
	v_mfma_f32_32x32x16_bf16 v[114:129], v[24:27], v[12:15], v[114:129]
	v_mfma_f32_32x32x16_bf16 v[130:145], v[28:31], v[0:3], v[130:145]
	global_load_dwordx4 v[48:51], v[248:249], off offset:1024
	global_load_dwordx4 v[52:55], v[250:251], off offset:1024
	v_mfma_f32_32x32x16_bf16 v[146:161], v[28:31], v[4:7], v[146:161]
	v_mfma_f32_32x32x16_bf16 v[162:177], v[28:31], v[8:11], v[162:177]
	v_mfma_f32_32x32x16_bf16 v[178:193], v[28:31], v[12:15], v[178:193]
	s_waitcnt lgkmcnt(0)
	s_barrier
; #define G_LOAD(S, kt_) do { G_LD1(S##a0, S##b0, 0, kt_); G_LD1(S##a1, S##b1, 1, kt_); G_LD1(S##a2, S##b2, 2, kt_); G_LD1(S##a3, S##b3, 3, kt_); } while (0)
; #define G_STORE(S, buf_) do { G_ST1(S##a0, S##b0, 0, buf_); G_ST1(S##a1, S##b1, 1, buf_); G_ST1(S##a2, S##b2, 2, buf_); G_ST1(S##a3, S##b3, 3, buf_); } while (0)
; template <class AL, class BL>
; DI void gemm_core(AL al, BL bl, int m0, int n0, int K, char* smem, f32x16 (&acc)[2][2]) {
;     ...
;   G_LOAD(x, 0);
;   G_STORE(x, 0);
;   G_LOAD(x, 1);
;   G_LOAD(y, (nk > 2) ? 2 : 1);
;   __syncthreads();
;   for (int kt = 0; kt < nk; kt += 2) {
;     G_TILE(0, x, true, (kt + 3 < nk), kt + 3);
;     __syncthreads();
;     G_TILE(1, y, (kt + 2 < nk), (kt + 4 < nk), kt + 4);
;     __syncthreads();
;   }
	ds_read_b128 v[0:3], v56 offset:0
	ds_read_b128 v[4:7], v56 offset:2560
	ds_read_b128 v[8:11], v57 offset:0
	ds_read_b128 v[12:15], v57 offset:2560
	ds_read_b128 v[16:19], v57 offset:5120
	ds_read_b128 v[20:23], v57 offset:7680
	ds_read_b128 v[24:27], v56 offset:32
	ds_read_b128 v[28:31], v56 offset:2592
	s_waitcnt lgkmcnt(4)
	v_mfma_f32_32x32x16_bf16 v[66:81], v[0:3], v[8:11], v[66:81]
	v_mfma_f32_32x32x16_bf16 v[82:97], v[0:3], v[12:15], v[82:97]
	s_waitcnt vmcnt(6)
	ds_write_b128 v58, v[214:217] offset:30720
	ds_write_b128 v58, v[218:221] offset:35840
	s_waitcnt lgkmcnt(4)
	v_mfma_f32_32x32x16_bf16 v[98:113], v[0:3], v[16:19], v[98:113]
	v_mfma_f32_32x32x16_bf16 v[114:129], v[0:3], v[20:23], v[114:129]
	ds_read_b128 v[0:3], v57 offset:32
	ds_write_b128 v58, v[222:225] offset:40960
	ds_write_b128 v58, v[228:231] offset:46080
	v_mfma_f32_32x32x16_bf16 v[130:145], v[4:7], v[8:11], v[130:145]
	v_mfma_f32_32x32x16_bf16 v[146:161], v[4:7], v[12:15], v[146:161]
	ds_write_b128 v58, v[232:235] offset:51200
	ds_write_b128 v58, v[236:239] offset:56320
	v_mfma_f32_32x32x16_bf16 v[162:177], v[4:7], v[16:19], v[162:177]
	v_mfma_f32_32x32x16_bf16 v[178:193], v[4:7], v[20:23], v[178:193]
	ds_read_b128 v[4:7], v57 offset:2592
	ds_read_b128 v[8:11], v57 offset:5152
	ds_read_b128 v[12:15], v57 offset:7712
	s_waitcnt lgkmcnt(2)
	v_mfma_f32_32x32x16_bf16 v[66:81], v[24:27], v[0:3], v[66:81]
	global_load_dwordx4 v[214:217], v[240:241], off offset:3136
	global_load_dwordx4 v[218:221], v[242:243], off offset:3136
	v_mfma_f32_32x32x16_bf16 v[82:97], v[24:27], v[4:7], v[82:97]
	s_waitcnt lgkmcnt(0)
	v_mfma_f32_32x32x16_bf16 v[98:113], v[24:27], v[8:11], v[98:113]
	global_load_dwordx4 v[222:225], v[244:245], off offset:1088
	global_load_dwordx4 v[228:231], v[246:247], off offset:1088
	v_mfma_f32_32x32x16_bf16 v[114:129], v[24:27], v[12:15], v[114:129]
	v_mfma_f32_32x32x16_bf16 v[130:145], v[28:31], v[0:3], v[130:145]
	global_load_dwordx4 v[232:235], v[248:249], off offset:1088
	global_load_dwordx4 v[236:239], v[250:251], off offset:1088
	v_mfma_f32_32x32x16_bf16 v[146:161], v[28:31], v[4:7], v[146:161]
	v_mfma_f32_32x32x16_bf16 v[162:177], v[28:31], v[8:11], v[162:177]
	v_mfma_f32_32x32x16_bf16 v[178:193], v[28:31], v[12:15], v[178:193]
	s_waitcnt lgkmcnt(0)
	s_barrier
	ds_read_b128 v[0:3], v56 offset:30720
	ds_read_b128 v[4:7], v56 offset:33280
	ds_read_b128 v[8:11], v57 offset:30720
	ds_read_b128 v[12:15], v57 offset:33280
	ds_read_b128 v[16:19], v57 offset:35840
	ds_read_b128 v[20:23], v57 offset:38400
	ds_read_b128 v[24:27], v56 offset:30752
	ds_read_b128 v[28:31], v56 offset:33312
	s_waitcnt lgkmcnt(4)
	v_mfma_f32_32x32x16_bf16 v[66:81], v[0:3], v[8:11], v[66:81]
	v_mfma_f32_32x32x16_bf16 v[82:97], v[0:3], v[12:15], v[82:97]
	s_waitcnt vmcnt(6)
	ds_write_b128 v58, v[32:35] offset:0
	ds_write_b128 v58, v[36:39] offset:5120
	s_waitcnt lgkmcnt(4)
	v_mfma_f32_32x32x16_bf16 v[98:113], v[0:3], v[16:19], v[98:113]
	v_mfma_f32_32x32x16_bf16 v[114:129], v[0:3], v[20:23], v[114:129]
	ds_read_b128 v[0:3], v57 offset:30752
	ds_write_b128 v58, v[40:43] offset:10240
	ds_write_b128 v58, v[44:47] offset:15360
	v_mfma_f32_32x32x16_bf16 v[130:145], v[4:7], v[8:11], v[130:145]
	v_mfma_f32_32x32x16_bf16 v[146:161], v[4:7], v[12:15], v[146:161]
	ds_write_b128 v58, v[48:51] offset:20480
	ds_write_b128 v58, v[52:55] offset:25600
	v_mfma_f32_32x32x16_bf16 v[162:177], v[4:7], v[16:19], v[162:177]
	v_mfma_f32_32x32x16_bf16 v[178:193], v[4:7], v[20:23], v[178:193]
	ds_read_b128 v[4:7], v57 offset:33312
	ds_read_b128 v[8:11], v57 offset:35872
	ds_read_b128 v[12:15], v57 offset:38432
	s_waitcnt lgkmcnt(2)
	v_mfma_f32_32x32x16_bf16 v[66:81], v[24:27], v[0:3], v[66:81]
	global_load_dwordx4 v[32:35], v[240:241], off offset:3200
	global_load_dwordx4 v[36:39], v[242:243], off offset:3200
	v_mfma_f32_32x32x16_bf16 v[82:97], v[24:27], v[4:7], v[82:97]
	s_waitcnt lgkmcnt(0)
	v_mfma_f32_32x32x16_bf16 v[98:113], v[24:27], v[8:11], v[98:113]
	global_load_dwordx4 v[40:43], v[244:245], off offset:1152
	global_load_dwordx4 v[44:47], v[246:247], off offset:1152
	v_mfma_f32_32x32x16_bf16 v[114:129], v[24:27], v[12:15], v[114:129]
	v_mfma_f32_32x32x16_bf16 v[130:145], v[28:31], v[0:3], v[130:145]
	global_load_dwordx4 v[48:51], v[248:249], off offset:1152
	global_load_dwordx4 v[52:55], v[250:251], off offset:1152
	v_mfma_f32_32x32x16_bf16 v[146:161], v[28:31], v[4:7], v[146:161]
	v_mfma_f32_32x32x16_bf16 v[162:177], v[28:31], v[8:11], v[162:177]
	v_mfma_f32_32x32x16_bf16 v[178:193], v[28:31], v[12:15], v[178:193]
	s_waitcnt lgkmcnt(0)
	s_barrier
; #define G_LOAD(S, kt_) do { G_LD1(S##a0, S##b0, 0, kt_); G_LD1(S##a1, S##b1, 1, kt_); G_LD1(S##a2, S##b2, 2, kt_); G_LD1(S##a3, S##b3, 3, kt_); } while (0)
; #define G_STORE(S, buf_) do { G_ST1(S##a0, S##b0, 0, buf_); G_ST1(S##a1, S##b1, 1, buf_); G_ST1(S##a2, S##b2, 2, buf_); G_ST1(S##a3, S##b3, 3, buf_); } while (0)
; template <class AL, class BL>
; DI void gemm_core(AL al, BL bl, int m0, int n0, int K, char* smem, f32x16 (&acc)[2][2]) {
;     ...
;   G_LOAD(x, 0);
;   G_STORE(x, 0);
;   G_LOAD(x, 1);
;   G_LOAD(y, (nk > 2) ? 2 : 1);
;   __syncthreads();
;   for (int kt = 0; kt < nk; kt += 2) {
;     G_TILE(0, x, true, (kt + 3 < nk), kt + 3);
;     __syncthreads();
;     G_TILE(1, y, (kt + 2 < nk), (kt + 4 < nk), kt + 4);
;     __syncthreads();
;   }
	ds_read_b128 v[0:3], v56 offset:0
	ds_read_b128 v[4:7], v56 offset:2560
	ds_read_b128 v[8:11], v57 offset:0
	ds_read_b128 v[12:15], v57 offset:2560
	ds_read_b128 v[16:19], v57 offset:5120
	ds_read_b128 v[20:23], v57 offset:7680
	ds_read_b128 v[24:27], v56 offset:32
	ds_read_b128 v[28:31], v56 offset:2592
	s_waitcnt lgkmcnt(4)
	v_mfma_f32_32x32x16_bf16 v[66:81], v[0:3], v[8:11], v[66:81]
	v_mfma_f32_32x32x16_bf16 v[82:97], v[0:3], v[12:15], v[82:97]
	s_waitcnt vmcnt(6)
	ds_write_b128 v58, v[214:217] offset:30720
	ds_write_b128 v58, v[218:221] offset:35840
	s_waitcnt lgkmcnt(4)
	v_mfma_f32_32x32x16_bf16 v[98:113], v[0:3], v[16:19], v[98:113]
	v_mfma_f32_32x32x16_bf16 v[114:129], v[0:3], v[20:23], v[114:129]
	ds_read_b128 v[0:3], v57 offset:32
	ds_write_b128 v58, v[222:225] offset:40960
	ds_write_b128 v58, v[228:231] offset:46080
	v_mfma_f32_32x32x16_bf16 v[130:145], v[4:7], v[8:11], v[130:145]
	v_mfma_f32_32x32x16_bf16 v[146:161], v[4:7], v[12:15], v[146:161]
	ds_write_b128 v58, v[232:235] offset:51200
	ds_write_b128 v58, v[236:239] offset:56320
	v_mfma_f32_32x32x16_bf16 v[162:177], v[4:7], v[16:19], v[162:177]
	v_mfma_f32_32x32x16_bf16 v[178:193], v[4:7], v[20:23], v[178:193]
	ds_read_b128 v[4:7], v57 offset:2592
	ds_read_b128 v[8:11], v57 offset:5152
	ds_read_b128 v[12:15], v57 offset:7712
	s_waitcnt lgkmcnt(2)
	v_mfma_f32_32x32x16_bf16 v[66:81], v[24:27], v[0:3], v[66:81]
	global_load_dwordx4 v[214:217], v[240:241], off offset:3264
	global_load_dwordx4 v[218:221], v[242:243], off offset:3264
	v_mfma_f32_32x32x16_bf16 v[82:97], v[24:27], v[4:7], v[82:97]
	s_waitcnt lgkmcnt(0)
	v_mfma_f32_32x32x16_bf16 v[98:113], v[24:27], v[8:11], v[98:113]
	global_load_dwordx4 v[222:225], v[244:245], off offset:1216
	global_load_dwordx4 v[228:231], v[246:247], off offset:1216
	v_mfma_f32_32x32x16_bf16 v[114:129], v[24:27], v[12:15], v[114:129]
	v_mfma_f32_32x32x16_bf16 v[130:145], v[28:31], v[0:3], v[130:145]
	global_load_dwordx4 v[232:235], v[248:249], off offset:1216
	global_load_dwordx4 v[236:239], v[250:251], off offset:1216
	v_mfma_f32_32x32x16_bf16 v[146:161], v[28:31], v[4:7], v[146:161]
	v_mfma_f32_32x32x16_bf16 v[162:177], v[28:31], v[8:11], v[162:177]
	v_mfma_f32_32x32x16_bf16 v[178:193], v[28:31], v[12:15], v[178:193]
	s_waitcnt lgkmcnt(0)
	s_barrier
	ds_read_b128 v[0:3], v56 offset:30720
	ds_read_b128 v[4:7], v56 offset:33280
	ds_read_b128 v[8:11], v57 offset:30720
	ds_read_b128 v[12:15], v57 offset:33280
	ds_read_b128 v[16:19], v57 offset:35840
	ds_read_b128 v[20:23], v57 offset:38400
	ds_read_b128 v[24:27], v56 offset:30752
	ds_read_b128 v[28:31], v56 offset:33312
	s_waitcnt lgkmcnt(4)
	v_mfma_f32_32x32x16_bf16 v[66:81], v[0:3], v[8:11], v[66:81]
	v_mfma_f32_32x32x16_bf16 v[82:97], v[0:3], v[12:15], v[82:97]
	s_waitcnt vmcnt(6)
	ds_write_b128 v58, v[32:35] offset:0
	ds_write_b128 v58, v[36:39] offset:5120
	s_waitcnt lgkmcnt(4)
	v_mfma_f32_32x32x16_bf16 v[98:113], v[0:3], v[16:19], v[98:113]
	v_mfma_f32_32x32x16_bf16 v[114:129], v[0:3], v[20:23], v[114:129]
	ds_read_b128 v[0:3], v57 offset:30752
	ds_write_b128 v58, v[40:43] offset:10240
	ds_write_b128 v58, v[44:47] offset:15360
	v_mfma_f32_32x32x16_bf16 v[130:145], v[4:7], v[8:11], v[130:145]
	v_mfma_f32_32x32x16_bf16 v[146:161], v[4:7], v[12:15], v[146:161]
	ds_write_b128 v58, v[48:51] offset:20480
	ds_write_b128 v58, v[52:55] offset:25600
	v_mfma_f32_32x32x16_bf16 v[162:177], v[4:7], v[16:19], v[162:177]
	v_mfma_f32_32x32x16_bf16 v[178:193], v[4:7], v[20:23], v[178:193]
	ds_read_b128 v[4:7], v57 offset:33312
	ds_read_b128 v[8:11], v57 offset:35872
	ds_read_b128 v[12:15], v57 offset:38432
	s_waitcnt lgkmcnt(2)
	v_mfma_f32_32x32x16_bf16 v[66:81], v[24:27], v[0:3], v[66:81]
	global_load_dwordx4 v[32:35], v[240:241], off offset:3328
	global_load_dwordx4 v[36:39], v[242:243], off offset:3328
	v_mfma_f32_32x32x16_bf16 v[82:97], v[24:27], v[4:7], v[82:97]
	s_waitcnt lgkmcnt(0)
	v_mfma_f32_32x32x16_bf16 v[98:113], v[24:27], v[8:11], v[98:113]
	global_load_dwordx4 v[40:43], v[244:245], off offset:1280
	global_load_dwordx4 v[44:47], v[246:247], off offset:1280
	v_mfma_f32_32x32x16_bf16 v[114:129], v[24:27], v[12:15], v[114:129]
	v_mfma_f32_32x32x16_bf16 v[130:145], v[28:31], v[0:3], v[130:145]
	global_load_dwordx4 v[48:51], v[248:249], off offset:1280
	global_load_dwordx4 v[52:55], v[250:251], off offset:1280
	v_mfma_f32_32x32x16_bf16 v[146:161], v[28:31], v[4:7], v[146:161]
	v_mfma_f32_32x32x16_bf16 v[162:177], v[28:31], v[8:11], v[162:177]
	v_mfma_f32_32x32x16_bf16 v[178:193], v[28:31], v[12:15], v[178:193]
	s_waitcnt lgkmcnt(0)
	s_barrier
; #define G_LOAD(S, kt_) do { G_LD1(S##a0, S##b0, 0, kt_); G_LD1(S##a1, S##b1, 1, kt_); G_LD1(S##a2, S##b2, 2, kt_); G_LD1(S##a3, S##b3, 3, kt_); } while (0)
; #define G_STORE(S, buf_) do { G_ST1(S##a0, S##b0, 0, buf_); G_ST1(S##a1, S##b1, 1, buf_); G_ST1(S##a2, S##b2, 2, buf_); G_ST1(S##a3, S##b3, 3, buf_); } while (0)
; template <class AL, class BL>
; DI void gemm_core(AL al, BL bl, int m0, int n0, int K, char* smem, f32x16 (&acc)[2][2]) {
;     ...
;   G_LOAD(x, 0);
;   G_STORE(x, 0);
;   G_LOAD(x, 1);
;   G_LOAD(y, (nk > 2) ? 2 : 1);
;   __syncthreads();
;   for (int kt = 0; kt < nk; kt += 2) {
;     G_TILE(0, x, true, (kt + 3 < nk), kt + 3);
;     __syncthreads();
;     G_TILE(1, y, (kt + 2 < nk), (kt + 4 < nk), kt + 4);
;     __syncthreads();
;   }
	ds_read_b128 v[0:3], v56 offset:0
	ds_read_b128 v[4:7], v56 offset:2560
	ds_read_b128 v[8:11], v57 offset:0
	ds_read_b128 v[12:15], v57 offset:2560
	ds_read_b128 v[16:19], v57 offset:5120
	ds_read_b128 v[20:23], v57 offset:7680
	ds_read_b128 v[24:27], v56 offset:32
	ds_read_b128 v[28:31], v56 offset:2592
	s_waitcnt lgkmcnt(4)
	v_mfma_f32_32x32x16_bf16 v[66:81], v[0:3], v[8:11], v[66:81]
	v_mfma_f32_32x32x16_bf16 v[82:97], v[0:3], v[12:15], v[82:97]
	s_waitcnt vmcnt(6)
	ds_write_b128 v58, v[214:217] offset:30720
	ds_write_b128 v58, v[218:221] offset:35840
	s_waitcnt lgkmcnt(4)
	v_mfma_f32_32x32x16_bf16 v[98:113], v[0:3], v[16:19], v[98:113]
	v_mfma_f32_32x32x16_bf16 v[114:129], v[0:3], v[20:23], v[114:129]
	ds_read_b128 v[0:3], v57 offset:32
	ds_write_b128 v58, v[222:225] offset:40960
	ds_write_b128 v58, v[228:231] offset:46080
	v_mfma_f32_32x32x16_bf16 v[130:145], v[4:7], v[8:11], v[130:145]
	v_mfma_f32_32x32x16_bf16 v[146:161], v[4:7], v[12:15], v[146:161]
	ds_write_b128 v58, v[232:235] offset:51200
	ds_write_b128 v58, v[236:239] offset:56320
	v_mfma_f32_32x32x16_bf16 v[162:177], v[4:7], v[16:19], v[162:177]
	v_mfma_f32_32x32x16_bf16 v[178:193], v[4:7], v[20:23], v[178:193]
	ds_read_b128 v[4:7], v57 offset:2592
	ds_read_b128 v[8:11], v57 offset:5152
	ds_read_b128 v[12:15], v57 offset:7712
	s_waitcnt lgkmcnt(2)
	v_mfma_f32_32x32x16_bf16 v[66:81], v[24:27], v[0:3], v[66:81]
	global_load_dwordx4 v[214:217], v[240:241], off offset:3392
	global_load_dwordx4 v[218:221], v[242:243], off offset:3392
	v_mfma_f32_32x32x16_bf16 v[82:97], v[24:27], v[4:7], v[82:97]
	s_waitcnt lgkmcnt(0)
	v_mfma_f32_32x32x16_bf16 v[98:113], v[24:27], v[8:11], v[98:113]
	global_load_dwordx4 v[222:225], v[244:245], off offset:1344
	global_load_dwordx4 v[228:231], v[246:247], off offset:1344
	v_mfma_f32_32x32x16_bf16 v[114:129], v[24:27], v[12:15], v[114:129]
	v_mfma_f32_32x32x16_bf16 v[130:145], v[28:31], v[0:3], v[130:145]
	global_load_dwordx4 v[232:235], v[248:249], off offset:1344
	global_load_dwordx4 v[236:239], v[250:251], off offset:1344
	v_mfma_f32_32x32x16_bf16 v[146:161], v[28:31], v[4:7], v[146:161]
	v_mfma_f32_32x32x16_bf16 v[162:177], v[28:31], v[8:11], v[162:177]
	v_mfma_f32_32x32x16_bf16 v[178:193], v[28:31], v[12:15], v[178:193]
	s_waitcnt lgkmcnt(0)
	s_barrier
	ds_read_b128 v[0:3], v56 offset:30720
	ds_read_b128 v[4:7], v56 offset:33280
	ds_read_b128 v[8:11], v57 offset:30720
	ds_read_b128 v[12:15], v57 offset:33280
	ds_read_b128 v[16:19], v57 offset:35840
	ds_read_b128 v[20:23], v57 offset:38400
	ds_read_b128 v[24:27], v56 offset:30752
	ds_read_b128 v[28:31], v56 offset:33312
	s_waitcnt lgkmcnt(4)
	v_mfma_f32_32x32x16_bf16 v[66:81], v[0:3], v[8:11], v[66:81]
	v_mfma_f32_32x32x16_bf16 v[82:97], v[0:3], v[12:15], v[82:97]
	s_waitcnt vmcnt(6)
	ds_write_b128 v58, v[32:35] offset:0
	ds_write_b128 v58, v[36:39] offset:5120
	s_waitcnt lgkmcnt(4)
	v_mfma_f32_32x32x16_bf16 v[98:113], v[0:3], v[16:19], v[98:113]
	v_mfma_f32_32x32x16_bf16 v[114:129], v[0:3], v[20:23], v[114:129]
	ds_read_b128 v[0:3], v57 offset:30752
	ds_write_b128 v58, v[40:43] offset:10240
	ds_write_b128 v58, v[44:47] offset:15360
	v_mfma_f32_32x32x16_bf16 v[130:145], v[4:7], v[8:11], v[130:145]
	v_mfma_f32_32x32x16_bf16 v[146:161], v[4:7], v[12:15], v[146:161]
	ds_write_b128 v58, v[48:51] offset:20480
	ds_write_b128 v58, v[52:55] offset:25600
	v_mfma_f32_32x32x16_bf16 v[162:177], v[4:7], v[16:19], v[162:177]
	v_mfma_f32_32x32x16_bf16 v[178:193], v[4:7], v[20:23], v[178:193]
	ds_read_b128 v[4:7], v57 offset:33312
	ds_read_b128 v[8:11], v57 offset:35872
	ds_read_b128 v[12:15], v57 offset:38432
	s_waitcnt lgkmcnt(2)
	v_mfma_f32_32x32x16_bf16 v[66:81], v[24:27], v[0:3], v[66:81]
	global_load_dwordx4 v[32:35], v[240:241], off offset:3456
	global_load_dwordx4 v[36:39], v[242:243], off offset:3456
	v_mfma_f32_32x32x16_bf16 v[82:97], v[24:27], v[4:7], v[82:97]
	s_waitcnt lgkmcnt(0)
	v_mfma_f32_32x32x16_bf16 v[98:113], v[24:27], v[8:11], v[98:113]
	global_load_dwordx4 v[40:43], v[244:245], off offset:1408
	global_load_dwordx4 v[44:47], v[246:247], off offset:1408
	v_mfma_f32_32x32x16_bf16 v[114:129], v[24:27], v[12:15], v[114:129]
	v_mfma_f32_32x32x16_bf16 v[130:145], v[28:31], v[0:3], v[130:145]
	global_load_dwordx4 v[48:51], v[248:249], off offset:1408
	global_load_dwordx4 v[52:55], v[250:251], off offset:1408
	v_mfma_f32_32x32x16_bf16 v[146:161], v[28:31], v[4:7], v[146:161]
	v_mfma_f32_32x32x16_bf16 v[162:177], v[28:31], v[8:11], v[162:177]
	v_mfma_f32_32x32x16_bf16 v[178:193], v[28:31], v[12:15], v[178:193]
	s_waitcnt lgkmcnt(0)
	s_barrier
; #define G_LOAD(S, kt_) do { G_LD1(S##a0, S##b0, 0, kt_); G_LD1(S##a1, S##b1, 1, kt_); G_LD1(S##a2, S##b2, 2, kt_); G_LD1(S##a3, S##b3, 3, kt_); } while (0)
; #define G_STORE(S, buf_) do { G_ST1(S##a0, S##b0, 0, buf_); G_ST1(S##a1, S##b1, 1, buf_); G_ST1(S##a2, S##b2, 2, buf_); G_ST1(S##a3, S##b3, 3, buf_); } while (0)
; template <class AL, class BL>
; DI void gemm_core(AL al, BL bl, int m0, int n0, int K, char* smem, f32x16 (&acc)[2][2]) {
;     ...
;   G_LOAD(x, 0);
;   G_STORE(x, 0);
;   G_LOAD(x, 1);
;   G_LOAD(y, (nk > 2) ? 2 : 1);
;   __syncthreads();
;   for (int kt = 0; kt < nk; kt += 2) {
;     G_TILE(0, x, true, (kt + 3 < nk), kt + 3);
;     __syncthreads();
;     G_TILE(1, y, (kt + 2 < nk), (kt + 4 < nk), kt + 4);
;     __syncthreads();
;   }
	ds_read_b128 v[0:3], v56 offset:0
	ds_read_b128 v[4:7], v56 offset:2560
	ds_read_b128 v[8:11], v57 offset:0
	ds_read_b128 v[12:15], v57 offset:2560
	ds_read_b128 v[16:19], v57 offset:5120
	ds_read_b128 v[20:23], v57 offset:7680
	ds_read_b128 v[24:27], v56 offset:32
	ds_read_b128 v[28:31], v56 offset:2592
	s_waitcnt lgkmcnt(4)
	v_mfma_f32_32x32x16_bf16 v[66:81], v[0:3], v[8:11], v[66:81]
	v_mfma_f32_32x32x16_bf16 v[82:97], v[0:3], v[12:15], v[82:97]
	s_waitcnt vmcnt(6)
	ds_write_b128 v58, v[214:217] offset:30720
	ds_write_b128 v58, v[218:221] offset:35840
	s_waitcnt lgkmcnt(4)
	v_mfma_f32_32x32x16_bf16 v[98:113], v[0:3], v[16:19], v[98:113]
	v_mfma_f32_32x32x16_bf16 v[114:129], v[0:3], v[20:23], v[114:129]
	ds_read_b128 v[0:3], v57 offset:32
	ds_write_b128 v58, v[222:225] offset:40960
	ds_write_b128 v58, v[228:231] offset:46080
	v_mfma_f32_32x32x16_bf16 v[130:145], v[4:7], v[8:11], v[130:145]
	v_mfma_f32_32x32x16_bf16 v[146:161], v[4:7], v[12:15], v[146:161]
	ds_write_b128 v58, v[232:235] offset:51200
	ds_write_b128 v58, v[236:239] offset:56320
	v_mfma_f32_32x32x16_bf16 v[162:177], v[4:7], v[16:19], v[162:177]
	v_mfma_f32_32x32x16_bf16 v[178:193], v[4:7], v[20:23], v[178:193]
	ds_read_b128 v[4:7], v57 offset:2592
	ds_read_b128 v[8:11], v57 offset:5152
	ds_read_b128 v[12:15], v57 offset:7712
	s_waitcnt lgkmcnt(2)
	v_mfma_f32_32x32x16_bf16 v[66:81], v[24:27], v[0:3], v[66:81]
	global_load_dwordx4 v[214:217], v[240:241], off offset:3520
	global_load_dwordx4 v[218:221], v[242:243], off offset:3520
	v_mfma_f32_32x32x16_bf16 v[82:97], v[24:27], v[4:7], v[82:97]
	s_waitcnt lgkmcnt(0)
	v_mfma_f32_32x32x16_bf16 v[98:113], v[24:27], v[8:11], v[98:113]
	global_load_dwordx4 v[222:225], v[244:245], off offset:1472
	global_load_dwordx4 v[228:231], v[246:247], off offset:1472
	v_mfma_f32_32x32x16_bf16 v[114:129], v[24:27], v[12:15], v[114:129]
	v_mfma_f32_32x32x16_bf16 v[130:145], v[28:31], v[0:3], v[130:145]
	global_load_dwordx4 v[232:235], v[248:249], off offset:1472
	global_load_dwordx4 v[236:239], v[250:251], off offset:1472
	v_mfma_f32_32x32x16_bf16 v[146:161], v[28:31], v[4:7], v[146:161]
	v_mfma_f32_32x32x16_bf16 v[162:177], v[28:31], v[8:11], v[162:177]
	v_mfma_f32_32x32x16_bf16 v[178:193], v[28:31], v[12:15], v[178:193]
	s_waitcnt lgkmcnt(0)
	s_barrier
	ds_read_b128 v[0:3], v56 offset:30720
	ds_read_b128 v[4:7], v56 offset:33280
	ds_read_b128 v[8:11], v57 offset:30720
	ds_read_b128 v[12:15], v57 offset:33280
	ds_read_b128 v[16:19], v57 offset:35840
	ds_read_b128 v[20:23], v57 offset:38400
	ds_read_b128 v[24:27], v56 offset:30752
	ds_read_b128 v[28:31], v56 offset:33312
	s_waitcnt lgkmcnt(4)
	v_mfma_f32_32x32x16_bf16 v[66:81], v[0:3], v[8:11], v[66:81]
	v_mfma_f32_32x32x16_bf16 v[82:97], v[0:3], v[12:15], v[82:97]
	s_waitcnt vmcnt(6)
	ds_write_b128 v58, v[32:35] offset:0
	ds_write_b128 v58, v[36:39] offset:5120
	s_waitcnt lgkmcnt(4)
	v_mfma_f32_32x32x16_bf16 v[98:113], v[0:3], v[16:19], v[98:113]
	v_mfma_f32_32x32x16_bf16 v[114:129], v[0:3], v[20:23], v[114:129]
	ds_read_b128 v[0:3], v57 offset:30752
	ds_write_b128 v58, v[40:43] offset:10240
	ds_write_b128 v58, v[44:47] offset:15360
	v_mfma_f32_32x32x16_bf16 v[130:145], v[4:7], v[8:11], v[130:145]
	v_mfma_f32_32x32x16_bf16 v[146:161], v[4:7], v[12:15], v[146:161]
	ds_write_b128 v58, v[48:51] offset:20480
	ds_write_b128 v58, v[52:55] offset:25600
	v_mfma_f32_32x32x16_bf16 v[162:177], v[4:7], v[16:19], v[162:177]
	v_mfma_f32_32x32x16_bf16 v[178:193], v[4:7], v[20:23], v[178:193]
	ds_read_b128 v[4:7], v57 offset:33312
	ds_read_b128 v[8:11], v57 offset:35872
	ds_read_b128 v[12:15], v57 offset:38432
	s_waitcnt lgkmcnt(2)
	v_mfma_f32_32x32x16_bf16 v[66:81], v[24:27], v[0:3], v[66:81]
	global_load_dwordx4 v[32:35], v[240:241], off offset:3584
	global_load_dwordx4 v[36:39], v[242:243], off offset:3584
	v_mfma_f32_32x32x16_bf16 v[82:97], v[24:27], v[4:7], v[82:97]
	s_waitcnt lgkmcnt(0)
	v_mfma_f32_32x32x16_bf16 v[98:113], v[24:27], v[8:11], v[98:113]
	global_load_dwordx4 v[40:43], v[244:245], off offset:1536
	global_load_dwordx4 v[44:47], v[246:247], off offset:1536
	v_mfma_f32_32x32x16_bf16 v[114:129], v[24:27], v[12:15], v[114:129]
	v_mfma_f32_32x32x16_bf16 v[130:145], v[28:31], v[0:3], v[130:145]
	global_load_dwordx4 v[48:51], v[248:249], off offset:1536
	global_load_dwordx4 v[52:55], v[250:251], off offset:1536
	v_mfma_f32_32x32x16_bf16 v[146:161], v[28:31], v[4:7], v[146:161]
	v_mfma_f32_32x32x16_bf16 v[162:177], v[28:31], v[8:11], v[162:177]
	v_mfma_f32_32x32x16_bf16 v[178:193], v[28:31], v[12:15], v[178:193]
	s_waitcnt lgkmcnt(0)
	s_barrier
; #define G_LOAD(S, kt_) do { G_LD1(S##a0, S##b0, 0, kt_); G_LD1(S##a1, S##b1, 1, kt_); G_LD1(S##a2, S##b2, 2, kt_); G_LD1(S##a3, S##b3, 3, kt_); } while (0)
; #define G_STORE(S, buf_) do { G_ST1(S##a0, S##b0, 0, buf_); G_ST1(S##a1, S##b1, 1, buf_); G_ST1(S##a2, S##b2, 2, buf_); G_ST1(S##a3, S##b3, 3, buf_); } while (0)
; template <class AL, class BL>
; DI void gemm_core(AL al, BL bl, int m0, int n0, int K, char* smem, f32x16 (&acc)[2][2]) {
;     ...
;   G_LOAD(x, 0);
;   G_STORE(x, 0);
;   G_LOAD(x, 1);
;   G_LOAD(y, (nk > 2) ? 2 : 1);
;   __syncthreads();
;   for (int kt = 0; kt < nk; kt += 2) {
;     G_TILE(0, x, true, (kt + 3 < nk), kt + 3);
;     __syncthreads();
;     G_TILE(1, y, (kt + 2 < nk), (kt + 4 < nk), kt + 4);
;     __syncthreads();
;   }
	ds_read_b128 v[0:3], v56 offset:0
	ds_read_b128 v[4:7], v56 offset:2560
	ds_read_b128 v[8:11], v57 offset:0
	ds_read_b128 v[12:15], v57 offset:2560
	ds_read_b128 v[16:19], v57 offset:5120
	ds_read_b128 v[20:23], v57 offset:7680
	ds_read_b128 v[24:27], v56 offset:32
	ds_read_b128 v[28:31], v56 offset:2592
	s_waitcnt lgkmcnt(4)
	v_mfma_f32_32x32x16_bf16 v[66:81], v[0:3], v[8:11], v[66:81]
	v_mfma_f32_32x32x16_bf16 v[82:97], v[0:3], v[12:15], v[82:97]
	s_waitcnt vmcnt(6)
	ds_write_b128 v58, v[214:217] offset:30720
	ds_write_b128 v58, v[218:221] offset:35840
	s_waitcnt lgkmcnt(4)
	v_mfma_f32_32x32x16_bf16 v[98:113], v[0:3], v[16:19], v[98:113]
	v_mfma_f32_32x32x16_bf16 v[114:129], v[0:3], v[20:23], v[114:129]
	ds_read_b128 v[0:3], v57 offset:32
	ds_write_b128 v58, v[222:225] offset:40960
	ds_write_b128 v58, v[228:231] offset:46080
	v_mfma_f32_32x32x16_bf16 v[130:145], v[4:7], v[8:11], v[130:145]
	v_mfma_f32_32x32x16_bf16 v[146:161], v[4:7], v[12:15], v[146:161]
	ds_write_b128 v58, v[232:235] offset:51200
	ds_write_b128 v58, v[236:239] offset:56320
	v_mfma_f32_32x32x16_bf16 v[162:177], v[4:7], v[16:19], v[162:177]
	v_mfma_f32_32x32x16_bf16 v[178:193], v[4:7], v[20:23], v[178:193]
	ds_read_b128 v[4:7], v57 offset:2592
	ds_read_b128 v[8:11], v57 offset:5152
	ds_read_b128 v[12:15], v57 offset:7712
	s_waitcnt lgkmcnt(2)
	v_mfma_f32_32x32x16_bf16 v[66:81], v[24:27], v[0:3], v[66:81]
	global_load_dwordx4 v[214:217], v[240:241], off offset:3648
	global_load_dwordx4 v[218:221], v[242:243], off offset:3648
	v_mfma_f32_32x32x16_bf16 v[82:97], v[24:27], v[4:7], v[82:97]
	s_waitcnt lgkmcnt(0)
	v_mfma_f32_32x32x16_bf16 v[98:113], v[24:27], v[8:11], v[98:113]
	global_load_dwordx4 v[222:225], v[244:245], off offset:1600
	global_load_dwordx4 v[228:231], v[246:247], off offset:1600
	v_mfma_f32_32x32x16_bf16 v[114:129], v[24:27], v[12:15], v[114:129]
	v_mfma_f32_32x32x16_bf16 v[130:145], v[28:31], v[0:3], v[130:145]
	global_load_dwordx4 v[232:235], v[248:249], off offset:1600
	global_load_dwordx4 v[236:239], v[250:251], off offset:1600
	v_mfma_f32_32x32x16_bf16 v[146:161], v[28:31], v[4:7], v[146:161]
	v_mfma_f32_32x32x16_bf16 v[162:177], v[28:31], v[8:11], v[162:177]
	v_mfma_f32_32x32x16_bf16 v[178:193], v[28:31], v[12:15], v[178:193]
	s_waitcnt lgkmcnt(0)
	s_barrier
	ds_read_b128 v[0:3], v56 offset:30720
	ds_read_b128 v[4:7], v56 offset:33280
	ds_read_b128 v[8:11], v57 offset:30720
	ds_read_b128 v[12:15], v57 offset:33280
	ds_read_b128 v[16:19], v57 offset:35840
	ds_read_b128 v[20:23], v57 offset:38400
	ds_read_b128 v[24:27], v56 offset:30752
	ds_read_b128 v[28:31], v56 offset:33312
	s_waitcnt lgkmcnt(4)
	v_mfma_f32_32x32x16_bf16 v[66:81], v[0:3], v[8:11], v[66:81]
	v_mfma_f32_32x32x16_bf16 v[82:97], v[0:3], v[12:15], v[82:97]
	s_waitcnt vmcnt(6)
	ds_write_b128 v58, v[32:35] offset:0
	ds_write_b128 v58, v[36:39] offset:5120
	s_waitcnt lgkmcnt(4)
	v_mfma_f32_32x32x16_bf16 v[98:113], v[0:3], v[16:19], v[98:113]
	v_mfma_f32_32x32x16_bf16 v[114:129], v[0:3], v[20:23], v[114:129]
	ds_read_b128 v[0:3], v57 offset:30752
	ds_write_b128 v58, v[40:43] offset:10240
	ds_write_b128 v58, v[44:47] offset:15360
	v_mfma_f32_32x32x16_bf16 v[130:145], v[4:7], v[8:11], v[130:145]
	v_mfma_f32_32x32x16_bf16 v[146:161], v[4:7], v[12:15], v[146:161]
	ds_write_b128 v58, v[48:51] offset:20480
	ds_write_b128 v58, v[52:55] offset:25600
	v_mfma_f32_32x32x16_bf16 v[162:177], v[4:7], v[16:19], v[162:177]
	v_mfma_f32_32x32x16_bf16 v[178:193], v[4:7], v[20:23], v[178:193]
	ds_read_b128 v[4:7], v57 offset:33312
	ds_read_b128 v[8:11], v57 offset:35872
	ds_read_b128 v[12:15], v57 offset:38432
	s_waitcnt lgkmcnt(2)
	v_mfma_f32_32x32x16_bf16 v[66:81], v[24:27], v[0:3], v[66:81]
	global_load_dwordx4 v[32:35], v[240:241], off offset:3712
	global_load_dwordx4 v[36:39], v[242:243], off offset:3712
	v_mfma_f32_32x32x16_bf16 v[82:97], v[24:27], v[4:7], v[82:97]
	s_waitcnt lgkmcnt(0)
	v_mfma_f32_32x32x16_bf16 v[98:113], v[24:27], v[8:11], v[98:113]
	global_load_dwordx4 v[40:43], v[244:245], off offset:1664
	global_load_dwordx4 v[44:47], v[246:247], off offset:1664
	v_mfma_f32_32x32x16_bf16 v[114:129], v[24:27], v[12:15], v[114:129]
	v_mfma_f32_32x32x16_bf16 v[130:145], v[28:31], v[0:3], v[130:145]
	global_load_dwordx4 v[48:51], v[248:249], off offset:1664
	global_load_dwordx4 v[52:55], v[250:251], off offset:1664
	v_mfma_f32_32x32x16_bf16 v[146:161], v[28:31], v[4:7], v[146:161]
	v_mfma_f32_32x32x16_bf16 v[162:177], v[28:31], v[8:11], v[162:177]
	v_mfma_f32_32x32x16_bf16 v[178:193], v[28:31], v[12:15], v[178:193]
	s_waitcnt lgkmcnt(0)
	s_barrier
; #define G_LOAD(S, kt_) do { G_LD1(S##a0, S##b0, 0, kt_); G_LD1(S##a1, S##b1, 1, kt_); G_LD1(S##a2, S##b2, 2, kt_); G_LD1(S##a3, S##b3, 3, kt_); } while (0)
; #define G_STORE(S, buf_) do { G_ST1(S##a0, S##b0, 0, buf_); G_ST1(S##a1, S##b1, 1, buf_); G_ST1(S##a2, S##b2, 2, buf_); G_ST1(S##a3, S##b3, 3, buf_); } while (0)
; template <class AL, class BL>
; DI void gemm_core(AL al, BL bl, int m0, int n0, int K, char* smem, f32x16 (&acc)[2][2]) {
;     ...
;   G_LOAD(x, 0);
;   G_STORE(x, 0);
;   G_LOAD(x, 1);
;   G_LOAD(y, (nk > 2) ? 2 : 1);
;   __syncthreads();
;   for (int kt = 0; kt < nk; kt += 2) {
;     G_TILE(0, x, true, (kt + 3 < nk), kt + 3);
;     __syncthreads();
;     G_TILE(1, y, (kt + 2 < nk), (kt + 4 < nk), kt + 4);
;     __syncthreads();
;   }
	ds_read_b128 v[0:3], v56 offset:0
	ds_read_b128 v[4:7], v56 offset:2560
	ds_read_b128 v[8:11], v57 offset:0
	ds_read_b128 v[12:15], v57 offset:2560
	ds_read_b128 v[16:19], v57 offset:5120
	ds_read_b128 v[20:23], v57 offset:7680
	ds_read_b128 v[24:27], v56 offset:32
	ds_read_b128 v[28:31], v56 offset:2592
	s_waitcnt lgkmcnt(4)
	v_mfma_f32_32x32x16_bf16 v[66:81], v[0:3], v[8:11], v[66:81]
	v_mfma_f32_32x32x16_bf16 v[82:97], v[0:3], v[12:15], v[82:97]
	s_waitcnt vmcnt(6)
	ds_write_b128 v58, v[214:217] offset:30720
	ds_write_b128 v58, v[218:221] offset:35840
	s_waitcnt lgkmcnt(4)
	v_mfma_f32_32x32x16_bf16 v[98:113], v[0:3], v[16:19], v[98:113]
	v_mfma_f32_32x32x16_bf16 v[114:129], v[0:3], v[20:23], v[114:129]
	ds_read_b128 v[0:3], v57 offset:32
	ds_write_b128 v58, v[222:225] offset:40960
	ds_write_b128 v58, v[228:231] offset:46080
	v_mfma_f32_32x32x16_bf16 v[130:145], v[4:7], v[8:11], v[130:145]
	v_mfma_f32_32x32x16_bf16 v[146:161], v[4:7], v[12:15], v[146:161]
	ds_write_b128 v58, v[232:235] offset:51200
	ds_write_b128 v58, v[236:239] offset:56320
	v_mfma_f32_32x32x16_bf16 v[162:177], v[4:7], v[16:19], v[162:177]
	v_mfma_f32_32x32x16_bf16 v[178:193], v[4:7], v[20:23], v[178:193]
	ds_read_b128 v[4:7], v57 offset:2592
	ds_read_b128 v[8:11], v57 offset:5152
	ds_read_b128 v[12:15], v57 offset:7712
	s_waitcnt lgkmcnt(2)
	v_mfma_f32_32x32x16_bf16 v[66:81], v[24:27], v[0:3], v[66:81]
	global_load_dwordx4 v[214:217], v[240:241], off offset:3776
	global_load_dwordx4 v[218:221], v[242:243], off offset:3776
	v_mfma_f32_32x32x16_bf16 v[82:97], v[24:27], v[4:7], v[82:97]
	s_waitcnt lgkmcnt(0)
	v_mfma_f32_32x32x16_bf16 v[98:113], v[24:27], v[8:11], v[98:113]
	global_load_dwordx4 v[222:225], v[244:245], off offset:1728
	global_load_dwordx4 v[228:231], v[246:247], off offset:1728
	v_mfma_f32_32x32x16_bf16 v[114:129], v[24:27], v[12:15], v[114:129]
	v_mfma_f32_32x32x16_bf16 v[130:145], v[28:31], v[0:3], v[130:145]
	global_load_dwordx4 v[232:235], v[248:249], off offset:1728
	global_load_dwordx4 v[236:239], v[250:251], off offset:1728
	v_mfma_f32_32x32x16_bf16 v[146:161], v[28:31], v[4:7], v[146:161]
	v_mfma_f32_32x32x16_bf16 v[162:177], v[28:31], v[8:11], v[162:177]
	v_mfma_f32_32x32x16_bf16 v[178:193], v[28:31], v[12:15], v[178:193]
	s_waitcnt lgkmcnt(0)
	s_barrier
	ds_read_b128 v[0:3], v56 offset:30720
	ds_read_b128 v[4:7], v56 offset:33280
	ds_read_b128 v[8:11], v57 offset:30720
	ds_read_b128 v[12:15], v57 offset:33280
	ds_read_b128 v[16:19], v57 offset:35840
	ds_read_b128 v[20:23], v57 offset:38400
	ds_read_b128 v[24:27], v56 offset:30752
	ds_read_b128 v[28:31], v56 offset:33312
	s_waitcnt lgkmcnt(4)
	v_mfma_f32_32x32x16_bf16 v[66:81], v[0:3], v[8:11], v[66:81]
	v_mfma_f32_32x32x16_bf16 v[82:97], v[0:3], v[12:15], v[82:97]
	s_waitcnt vmcnt(6)
	ds_write_b128 v58, v[32:35] offset:0
	ds_write_b128 v58, v[36:39] offset:5120
	s_waitcnt lgkmcnt(4)
	v_mfma_f32_32x32x16_bf16 v[98:113], v[0:3], v[16:19], v[98:113]
	v_mfma_f32_32x32x16_bf16 v[114:129], v[0:3], v[20:23], v[114:129]
	ds_read_b128 v[0:3], v57 offset:30752
	ds_write_b128 v58, v[40:43] offset:10240
	ds_write_b128 v58, v[44:47] offset:15360
	v_mfma_f32_32x32x16_bf16 v[130:145], v[4:7], v[8:11], v[130:145]
	v_mfma_f32_32x32x16_bf16 v[146:161], v[4:7], v[12:15], v[146:161]
	ds_write_b128 v58, v[48:51] offset:20480
	ds_write_b128 v58, v[52:55] offset:25600
	v_mfma_f32_32x32x16_bf16 v[162:177], v[4:7], v[16:19], v[162:177]
	v_mfma_f32_32x32x16_bf16 v[178:193], v[4:7], v[20:23], v[178:193]
	ds_read_b128 v[4:7], v57 offset:33312
	ds_read_b128 v[8:11], v57 offset:35872
	ds_read_b128 v[12:15], v57 offset:38432
	s_waitcnt lgkmcnt(2)
	v_mfma_f32_32x32x16_bf16 v[66:81], v[24:27], v[0:3], v[66:81]
	global_load_dwordx4 v[32:35], v[240:241], off offset:3840
	global_load_dwordx4 v[36:39], v[242:243], off offset:3840
	v_mfma_f32_32x32x16_bf16 v[82:97], v[24:27], v[4:7], v[82:97]
	s_waitcnt lgkmcnt(0)
	v_mfma_f32_32x32x16_bf16 v[98:113], v[24:27], v[8:11], v[98:113]
	global_load_dwordx4 v[40:43], v[244:245], off offset:1792
	global_load_dwordx4 v[44:47], v[246:247], off offset:1792
	v_mfma_f32_32x32x16_bf16 v[114:129], v[24:27], v[12:15], v[114:129]
	v_mfma_f32_32x32x16_bf16 v[130:145], v[28:31], v[0:3], v[130:145]
	global_load_dwordx4 v[48:51], v[248:249], off offset:1792
	global_load_dwordx4 v[52:55], v[250:251], off offset:1792
	v_mfma_f32_32x32x16_bf16 v[146:161], v[28:31], v[4:7], v[146:161]
	v_mfma_f32_32x32x16_bf16 v[162:177], v[28:31], v[8:11], v[162:177]
	v_mfma_f32_32x32x16_bf16 v[178:193], v[28:31], v[12:15], v[178:193]
	s_waitcnt lgkmcnt(0)
	s_barrier
; #define G_LOAD(S, kt_) do { G_LD1(S##a0, S##b0, 0, kt_); G_LD1(S##a1, S##b1, 1, kt_); G_LD1(S##a2, S##b2, 2, kt_); G_LD1(S##a3, S##b3, 3, kt_); } while (0)
; #define G_STORE(S, buf_) do { G_ST1(S##a0, S##b0, 0, buf_); G_ST1(S##a1, S##b1, 1, buf_); G_ST1(S##a2, S##b2, 2, buf_); G_ST1(S##a3, S##b3, 3, buf_); } while (0)
; template <class AL, class BL>
; DI void gemm_core(AL al, BL bl, int m0, int n0, int K, char* smem, f32x16 (&acc)[2][2]) {
;     ...
;   G_LOAD(x, 0);
;   G_STORE(x, 0);
;   G_LOAD(x, 1);
;   G_LOAD(y, (nk > 2) ? 2 : 1);
;   __syncthreads();
;   for (int kt = 0; kt < nk; kt += 2) {
;     G_TILE(0, x, true, (kt + 3 < nk), kt + 3);
;     __syncthreads();
;     G_TILE(1, y, (kt + 2 < nk), (kt + 4 < nk), kt + 4);
;     __syncthreads();
;   }
	ds_read_b128 v[0:3], v56 offset:0
	ds_read_b128 v[4:7], v56 offset:2560
	ds_read_b128 v[8:11], v57 offset:0
	ds_read_b128 v[12:15], v57 offset:2560
	ds_read_b128 v[16:19], v57 offset:5120
	ds_read_b128 v[20:23], v57 offset:7680
	ds_read_b128 v[24:27], v56 offset:32
	ds_read_b128 v[28:31], v56 offset:2592
	s_waitcnt lgkmcnt(4)
	v_mfma_f32_32x32x16_bf16 v[66:81], v[0:3], v[8:11], v[66:81]
	v_mfma_f32_32x32x16_bf16 v[82:97], v[0:3], v[12:15], v[82:97]
	s_waitcnt vmcnt(6)
	ds_write_b128 v58, v[214:217] offset:30720
	ds_write_b128 v58, v[218:221] offset:35840
	s_waitcnt lgkmcnt(4)
	v_mfma_f32_32x32x16_bf16 v[98:113], v[0:3], v[16:19], v[98:113]
	v_mfma_f32_32x32x16_bf16 v[114:129], v[0:3], v[20:23], v[114:129]
	ds_read_b128 v[0:3], v57 offset:32
	ds_write_b128 v58, v[222:225] offset:40960
	ds_write_b128 v58, v[228:231] offset:46080
	v_mfma_f32_32x32x16_bf16 v[130:145], v[4:7], v[8:11], v[130:145]
	v_mfma_f32_32x32x16_bf16 v[146:161], v[4:7], v[12:15], v[146:161]
	ds_write_b128 v58, v[232:235] offset:51200
	ds_write_b128 v58, v[236:239] offset:56320
	v_mfma_f32_32x32x16_bf16 v[162:177], v[4:7], v[16:19], v[162:177]
	v_mfma_f32_32x32x16_bf16 v[178:193], v[4:7], v[20:23], v[178:193]
	ds_read_b128 v[4:7], v57 offset:2592
	ds_read_b128 v[8:11], v57 offset:5152
	ds_read_b128 v[12:15], v57 offset:7712
	s_waitcnt lgkmcnt(2)
	v_mfma_f32_32x32x16_bf16 v[66:81], v[24:27], v[0:3], v[66:81]
	global_load_dwordx4 v[214:217], v[240:241], off offset:3904
	global_load_dwordx4 v[218:221], v[242:243], off offset:3904
	v_mfma_f32_32x32x16_bf16 v[82:97], v[24:27], v[4:7], v[82:97]
	s_waitcnt lgkmcnt(0)
	v_mfma_f32_32x32x16_bf16 v[98:113], v[24:27], v[8:11], v[98:113]
	global_load_dwordx4 v[222:225], v[244:245], off offset:1856
	global_load_dwordx4 v[228:231], v[246:247], off offset:1856
	v_mfma_f32_32x32x16_bf16 v[114:129], v[24:27], v[12:15], v[114:129]
	v_mfma_f32_32x32x16_bf16 v[130:145], v[28:31], v[0:3], v[130:145]
	global_load_dwordx4 v[232:235], v[248:249], off offset:1856
	global_load_dwordx4 v[236:239], v[250:251], off offset:1856
	v_mfma_f32_32x32x16_bf16 v[146:161], v[28:31], v[4:7], v[146:161]
	v_mfma_f32_32x32x16_bf16 v[162:177], v[28:31], v[8:11], v[162:177]
	v_mfma_f32_32x32x16_bf16 v[178:193], v[28:31], v[12:15], v[178:193]
	s_waitcnt lgkmcnt(0)
	s_barrier
	ds_read_b128 v[0:3], v56 offset:30720
	ds_read_b128 v[4:7], v56 offset:33280
	ds_read_b128 v[8:11], v57 offset:30720
	ds_read_b128 v[12:15], v57 offset:33280
	ds_read_b128 v[16:19], v57 offset:35840
	ds_read_b128 v[20:23], v57 offset:38400
	ds_read_b128 v[24:27], v56 offset:30752
	ds_read_b128 v[28:31], v56 offset:33312
	s_waitcnt lgkmcnt(4)
	v_mfma_f32_32x32x16_bf16 v[66:81], v[0:3], v[8:11], v[66:81]
	v_mfma_f32_32x32x16_bf16 v[82:97], v[0:3], v[12:15], v[82:97]
	s_waitcnt vmcnt(6)
	ds_write_b128 v58, v[32:35] offset:0
	ds_write_b128 v58, v[36:39] offset:5120
	s_waitcnt lgkmcnt(4)
	v_mfma_f32_32x32x16_bf16 v[98:113], v[0:3], v[16:19], v[98:113]
	v_mfma_f32_32x32x16_bf16 v[114:129], v[0:3], v[20:23], v[114:129]
	ds_read_b128 v[0:3], v57 offset:30752
	ds_write_b128 v58, v[40:43] offset:10240
	ds_write_b128 v58, v[44:47] offset:15360
	v_mfma_f32_32x32x16_bf16 v[130:145], v[4:7], v[8:11], v[130:145]
	v_mfma_f32_32x32x16_bf16 v[146:161], v[4:7], v[12:15], v[146:161]
	ds_write_b128 v58, v[48:51] offset:20480
	ds_write_b128 v58, v[52:55] offset:25600
	v_mfma_f32_32x32x16_bf16 v[162:177], v[4:7], v[16:19], v[162:177]
	v_mfma_f32_32x32x16_bf16 v[178:193], v[4:7], v[20:23], v[178:193]
	ds_read_b128 v[4:7], v57 offset:33312
	ds_read_b128 v[8:11], v57 offset:35872
	ds_read_b128 v[12:15], v57 offset:38432
	s_waitcnt lgkmcnt(2)
	v_mfma_f32_32x32x16_bf16 v[66:81], v[24:27], v[0:3], v[66:81]
	global_load_dwordx4 v[32:35], v[240:241], off offset:3968
	global_load_dwordx4 v[36:39], v[242:243], off offset:3968
	v_mfma_f32_32x32x16_bf16 v[82:97], v[24:27], v[4:7], v[82:97]
	s_waitcnt lgkmcnt(0)
	v_mfma_f32_32x32x16_bf16 v[98:113], v[24:27], v[8:11], v[98:113]
	global_load_dwordx4 v[40:43], v[244:245], off offset:1920
	global_load_dwordx4 v[44:47], v[246:247], off offset:1920
	v_mfma_f32_32x32x16_bf16 v[114:129], v[24:27], v[12:15], v[114:129]
	v_mfma_f32_32x32x16_bf16 v[130:145], v[28:31], v[0:3], v[130:145]
	global_load_dwordx4 v[48:51], v[248:249], off offset:1920
	global_load_dwordx4 v[52:55], v[250:251], off offset:1920
	v_mfma_f32_32x32x16_bf16 v[146:161], v[28:31], v[4:7], v[146:161]
	v_mfma_f32_32x32x16_bf16 v[162:177], v[28:31], v[8:11], v[162:177]
	v_mfma_f32_32x32x16_bf16 v[178:193], v[28:31], v[12:15], v[178:193]
	s_waitcnt lgkmcnt(0)
	s_barrier
; #define G_LOAD(S, kt_) do { G_LD1(S##a0, S##b0, 0, kt_); G_LD1(S##a1, S##b1, 1, kt_); G_LD1(S##a2, S##b2, 2, kt_); G_LD1(S##a3, S##b3, 3, kt_); } while (0)
; #define G_STORE(S, buf_) do { G_ST1(S##a0, S##b0, 0, buf_); G_ST1(S##a1, S##b1, 1, buf_); G_ST1(S##a2, S##b2, 2, buf_); G_ST1(S##a3, S##b3, 3, buf_); } while (0)
; template <class AL, class BL>
; DI void gemm_core(AL al, BL bl, int m0, int n0, int K, char* smem, f32x16 (&acc)[2][2]) {
;     ...
;   G_LOAD(x, 0);
;   G_STORE(x, 0);
;   G_LOAD(x, 1);
;   G_LOAD(y, (nk > 2) ? 2 : 1);
;   __syncthreads();
;   for (int kt = 0; kt < nk; kt += 2) {
;     G_TILE(0, x, true, (kt + 3 < nk), kt + 3);
;     __syncthreads();
;     G_TILE(1, y, (kt + 2 < nk), (kt + 4 < nk), kt + 4);
;     __syncthreads();
;   }
	ds_read_b128 v[0:3], v56 offset:0
	ds_read_b128 v[4:7], v56 offset:2560
	ds_read_b128 v[8:11], v57 offset:0
	ds_read_b128 v[12:15], v57 offset:2560
	ds_read_b128 v[16:19], v57 offset:5120
	ds_read_b128 v[20:23], v57 offset:7680
	ds_read_b128 v[24:27], v56 offset:32
	ds_read_b128 v[28:31], v56 offset:2592
	s_waitcnt lgkmcnt(4)
	v_mfma_f32_32x32x16_bf16 v[66:81], v[0:3], v[8:11], v[66:81]
	v_mfma_f32_32x32x16_bf16 v[82:97], v[0:3], v[12:15], v[82:97]
	s_waitcnt vmcnt(6)
	ds_write_b128 v58, v[214:217] offset:30720
	ds_write_b128 v58, v[218:221] offset:35840
	s_waitcnt lgkmcnt(4)
	v_mfma_f32_32x32x16_bf16 v[98:113], v[0:3], v[16:19], v[98:113]
	v_mfma_f32_32x32x16_bf16 v[114:129], v[0:3], v[20:23], v[114:129]
	ds_read_b128 v[0:3], v57 offset:32
	ds_write_b128 v58, v[222:225] offset:40960
	ds_write_b128 v58, v[228:231] offset:46080
	v_mfma_f32_32x32x16_bf16 v[130:145], v[4:7], v[8:11], v[130:145]
	v_mfma_f32_32x32x16_bf16 v[146:161], v[4:7], v[12:15], v[146:161]
	ds_write_b128 v58, v[232:235] offset:51200
	ds_write_b128 v58, v[236:239] offset:56320
	v_mfma_f32_32x32x16_bf16 v[162:177], v[4:7], v[16:19], v[162:177]
	v_mfma_f32_32x32x16_bf16 v[178:193], v[4:7], v[20:23], v[178:193]
	ds_read_b128 v[4:7], v57 offset:2592
	ds_read_b128 v[8:11], v57 offset:5152
	ds_read_b128 v[12:15], v57 offset:7712
	s_waitcnt lgkmcnt(2)
	v_mfma_f32_32x32x16_bf16 v[66:81], v[24:27], v[0:3], v[66:81]
	global_load_dwordx4 v[214:217], v[240:241], off offset:4032
	global_load_dwordx4 v[218:221], v[242:243], off offset:4032
	v_mfma_f32_32x32x16_bf16 v[82:97], v[24:27], v[4:7], v[82:97]
	s_waitcnt lgkmcnt(0)
	v_mfma_f32_32x32x16_bf16 v[98:113], v[24:27], v[8:11], v[98:113]
	global_load_dwordx4 v[222:225], v[244:245], off offset:1984
	global_load_dwordx4 v[228:231], v[246:247], off offset:1984
	v_mfma_f32_32x32x16_bf16 v[114:129], v[24:27], v[12:15], v[114:129]
	v_mfma_f32_32x32x16_bf16 v[130:145], v[28:31], v[0:3], v[130:145]
	global_load_dwordx4 v[232:235], v[248:249], off offset:1984
	global_load_dwordx4 v[236:239], v[250:251], off offset:1984
	v_mfma_f32_32x32x16_bf16 v[146:161], v[28:31], v[4:7], v[146:161]
	v_mfma_f32_32x32x16_bf16 v[162:177], v[28:31], v[8:11], v[162:177]
	v_mfma_f32_32x32x16_bf16 v[178:193], v[28:31], v[12:15], v[178:193]
	s_waitcnt lgkmcnt(0)
	s_barrier
	ds_read_b128 v[0:3], v56 offset:30720
	ds_read_b128 v[4:7], v56 offset:33280
	ds_read_b128 v[8:11], v57 offset:30720
	ds_read_b128 v[12:15], v57 offset:33280
	ds_read_b128 v[16:19], v57 offset:35840
	ds_read_b128 v[20:23], v57 offset:38400
	ds_read_b128 v[24:27], v56 offset:30752
	ds_read_b128 v[28:31], v56 offset:33312
	s_waitcnt lgkmcnt(4)
	v_mfma_f32_32x32x16_bf16 v[66:81], v[0:3], v[8:11], v[66:81]
	v_mfma_f32_32x32x16_bf16 v[82:97], v[0:3], v[12:15], v[82:97]
	s_waitcnt vmcnt(6)
	ds_write_b128 v58, v[32:35] offset:0
	ds_write_b128 v58, v[36:39] offset:5120
	s_waitcnt lgkmcnt(4)
	v_mfma_f32_32x32x16_bf16 v[98:113], v[0:3], v[16:19], v[98:113]
	v_mfma_f32_32x32x16_bf16 v[114:129], v[0:3], v[20:23], v[114:129]
	ds_read_b128 v[0:3], v57 offset:30752
	ds_write_b128 v58, v[40:43] offset:10240
	ds_write_b128 v58, v[44:47] offset:15360
	v_mfma_f32_32x32x16_bf16 v[130:145], v[4:7], v[8:11], v[130:145]
	v_mfma_f32_32x32x16_bf16 v[146:161], v[4:7], v[12:15], v[146:161]
	ds_write_b128 v58, v[48:51] offset:20480
	ds_write_b128 v58, v[52:55] offset:25600
	v_mfma_f32_32x32x16_bf16 v[162:177], v[4:7], v[16:19], v[162:177]
	v_mfma_f32_32x32x16_bf16 v[178:193], v[4:7], v[20:23], v[178:193]
	ds_read_b128 v[4:7], v57 offset:33312
	ds_read_b128 v[8:11], v57 offset:35872
	ds_read_b128 v[12:15], v57 offset:38432
	s_waitcnt lgkmcnt(2)
	v_mfma_f32_32x32x16_bf16 v[66:81], v[24:27], v[0:3], v[66:81]
	v_mfma_f32_32x32x16_bf16 v[82:97], v[24:27], v[4:7], v[82:97]
	s_waitcnt lgkmcnt(0)
	v_mfma_f32_32x32x16_bf16 v[98:113], v[24:27], v[8:11], v[98:113]
	v_mfma_f32_32x32x16_bf16 v[114:129], v[24:27], v[12:15], v[114:129]
	v_mfma_f32_32x32x16_bf16 v[130:145], v[28:31], v[0:3], v[130:145]
	v_mfma_f32_32x32x16_bf16 v[146:161], v[28:31], v[4:7], v[146:161]
	v_mfma_f32_32x32x16_bf16 v[162:177], v[28:31], v[8:11], v[162:177]
	v_mfma_f32_32x32x16_bf16 v[178:193], v[28:31], v[12:15], v[178:193]
	s_waitcnt lgkmcnt(0)
	s_barrier
	ds_read_b128 v[0:3], v56 offset:0
	ds_read_b128 v[4:7], v56 offset:2560
	ds_read_b128 v[8:11], v57 offset:0
	ds_read_b128 v[12:15], v57 offset:2560
	ds_read_b128 v[16:19], v57 offset:5120
	ds_read_b128 v[20:23], v57 offset:7680
	ds_read_b128 v[24:27], v56 offset:32
	ds_read_b128 v[28:31], v56 offset:2592
	s_waitcnt lgkmcnt(4)
	v_mfma_f32_32x32x16_bf16 v[66:81], v[0:3], v[8:11], v[66:81]
	v_mfma_f32_32x32x16_bf16 v[82:97], v[0:3], v[12:15], v[82:97]
	s_waitcnt vmcnt(0)
	ds_write_b128 v58, v[214:217] offset:30720
	ds_write_b128 v58, v[218:221] offset:35840
	s_waitcnt lgkmcnt(4)
	v_mfma_f32_32x32x16_bf16 v[98:113], v[0:3], v[16:19], v[98:113]
	v_mfma_f32_32x32x16_bf16 v[114:129], v[0:3], v[20:23], v[114:129]
	ds_read_b128 v[0:3], v57 offset:32
	ds_write_b128 v58, v[222:225] offset:40960
	ds_write_b128 v58, v[228:231] offset:46080
	v_mfma_f32_32x32x16_bf16 v[130:145], v[4:7], v[8:11], v[130:145]
	v_mfma_f32_32x32x16_bf16 v[146:161], v[4:7], v[12:15], v[146:161]
	ds_write_b128 v58, v[232:235] offset:51200
	ds_write_b128 v58, v[236:239] offset:56320
	v_mfma_f32_32x32x16_bf16 v[162:177], v[4:7], v[16:19], v[162:177]
	v_mfma_f32_32x32x16_bf16 v[178:193], v[4:7], v[20:23], v[178:193]
	ds_read_b128 v[4:7], v57 offset:2592
	ds_read_b128 v[8:11], v57 offset:5152
	ds_read_b128 v[12:15], v57 offset:7712
	s_waitcnt lgkmcnt(2)
	v_mfma_f32_32x32x16_bf16 v[66:81], v[24:27], v[0:3], v[66:81]
	v_mfma_f32_32x32x16_bf16 v[82:97], v[24:27], v[4:7], v[82:97]
	s_waitcnt lgkmcnt(0)
	v_mfma_f32_32x32x16_bf16 v[98:113], v[24:27], v[8:11], v[98:113]
	v_mfma_f32_32x32x16_bf16 v[114:129], v[24:27], v[12:15], v[114:129]
	v_mfma_f32_32x32x16_bf16 v[130:145], v[28:31], v[0:3], v[130:145]
	v_mfma_f32_32x32x16_bf16 v[146:161], v[28:31], v[4:7], v[146:161]
	v_mfma_f32_32x32x16_bf16 v[162:177], v[28:31], v[8:11], v[162:177]
	v_mfma_f32_32x32x16_bf16 v[178:193], v[28:31], v[12:15], v[178:193]
	s_waitcnt lgkmcnt(0)
	s_barrier
; template <class AL, class BL>
; DI void gemm_core(AL al, BL bl, int m0, int n0, int K, char* smem, f32x16 (&acc)[2][2]) {
;     ...
;   for (int kt = 0; kt < nk; kt += 2) {
;     G_TILE(0, x, true, (kt + 3 < nk), kt + 3);
;     __syncthreads();
;     G_TILE(1, y, (kt + 2 < nk), (kt + 4 < nk), kt + 4);
;     __syncthreads();
;   }
; DI void ffn_up_phase(const Params& p, const u16* xb, int ldx, const u16* wupT, u16* hid, char* smem) {
;     ...
;              [=](const f32x16 (&acc)[2][2], int m0, int n0) {
;                epi_bf16_tile(acc, m0, n0, hid + (long)m0 * 4096 + n0, 4096, smem, [=](int m, int n, float v) {
;                  const float a = fmaxf(v * rs[m], 0.f);
;                  return a * a;
;                });
	ds_read_b128 v[0:3], v56 offset:30720
	ds_read_b128 v[4:7], v56 offset:33280
	ds_read_b128 v[8:11], v57 offset:30720
	ds_read_b128 v[12:15], v57 offset:33280
	ds_read_b128 v[16:19], v57 offset:35840
	ds_read_b128 v[20:23], v57 offset:38400
	ds_read_b128 v[24:27], v56 offset:30752
	ds_read_b128 v[28:31], v56 offset:33312
	s_waitcnt lgkmcnt(4)
	v_mfma_f32_32x32x16_bf16 v[66:81], v[0:3], v[8:11], v[66:81]
	global_load_dword v32, v61, s[14:15] offset:0
	global_load_dword v33, v61, s[14:15] offset:4
	global_load_dword v34, v61, s[14:15] offset:8
	global_load_dword v35, v61, s[14:15] offset:12
	v_mfma_f32_32x32x16_bf16 v[82:97], v[0:3], v[12:15], v[82:97]
	s_waitcnt lgkmcnt(2)
	v_mfma_f32_32x32x16_bf16 v[98:113], v[0:3], v[16:19], v[98:113]
	global_load_dword v36, v61, s[14:15] offset:32
	global_load_dword v37, v61, s[14:15] offset:36
	global_load_dword v38, v61, s[14:15] offset:40
	global_load_dword v39, v61, s[14:15] offset:44
	v_mfma_f32_32x32x16_bf16 v[114:129], v[0:3], v[20:23], v[114:129]
	ds_read_b128 v[0:3], v57 offset:30752
	v_mfma_f32_32x32x16_bf16 v[130:145], v[4:7], v[8:11], v[130:145]
	global_load_dword v40, v61, s[14:15] offset:64
	global_load_dword v41, v61, s[14:15] offset:68
	global_load_dword v42, v61, s[14:15] offset:72
	global_load_dword v43, v61, s[14:15] offset:76
	v_mfma_f32_32x32x16_bf16 v[146:161], v[4:7], v[12:15], v[146:161]
	v_mfma_f32_32x32x16_bf16 v[162:177], v[4:7], v[16:19], v[162:177]
	global_load_dword v44, v61, s[14:15] offset:96
	global_load_dword v45, v61, s[14:15] offset:100
	global_load_dword v46, v61, s[14:15] offset:104
	global_load_dword v47, v61, s[14:15] offset:108
	v_mfma_f32_32x32x16_bf16 v[178:193], v[4:7], v[20:23], v[178:193]
	ds_read_b128 v[4:7], v57 offset:33312
	ds_read_b128 v[8:11], v57 offset:35872
	ds_read_b128 v[12:15], v57 offset:38432
	s_waitcnt lgkmcnt(2)
	v_mfma_f32_32x32x16_bf16 v[66:81], v[24:27], v[0:3], v[66:81]
	global_load_dword v48, v61, s[14:15] offset:128
	global_load_dword v49, v61, s[14:15] offset:132
	global_load_dword v50, v61, s[14:15] offset:136
	global_load_dword v51, v61, s[14:15] offset:140
	v_mfma_f32_32x32x16_bf16 v[82:97], v[24:27], v[4:7], v[82:97]
	s_waitcnt lgkmcnt(0)
	v_mfma_f32_32x32x16_bf16 v[98:113], v[24:27], v[8:11], v[98:113]
	global_load_dword v52, v61, s[14:15] offset:160
	global_load_dword v53, v61, s[14:15] offset:164
	global_load_dword v54, v61, s[14:15] offset:168
	global_load_dword v55, v61, s[14:15] offset:172
	v_mfma_f32_32x32x16_bf16 v[114:129], v[24:27], v[12:15], v[114:129]
	v_mfma_f32_32x32x16_bf16 v[130:145], v[28:31], v[0:3], v[130:145]
	global_load_dword v214, v61, s[14:15] offset:192
	global_load_dword v215, v61, s[14:15] offset:196
	global_load_dword v216, v61, s[14:15] offset:200
	global_load_dword v217, v61, s[14:15] offset:204
	v_mfma_f32_32x32x16_bf16 v[146:161], v[28:31], v[4:7], v[146:161]
	v_mfma_f32_32x32x16_bf16 v[162:177], v[28:31], v[8:11], v[162:177]
	global_load_dword v218, v61, s[14:15] offset:224
	global_load_dword v219, v61, s[14:15] offset:228
	global_load_dword v220, v61, s[14:15] offset:232
	global_load_dword v221, v61, s[14:15] offset:236
	v_mfma_f32_32x32x16_bf16 v[178:193], v[28:31], v[12:15], v[178:193]
	s_waitcnt lgkmcnt(0)
	s_barrier
	s_nop 7
	s_nop 3
	s_waitcnt vmcnt(0)
	v_mov_b32_e32 v0, v32
	v_mov_b32_e32 v1, v33
	v_mov_b32_e32 v2, v34
	v_mov_b32_e32 v3, v35
	v_mov_b32_e32 v4, v36
	v_mov_b32_e32 v5, v37
	v_mov_b32_e32 v6, v38
	v_mov_b32_e32 v7, v39
	v_mov_b32_e32 v8, v40
	v_mov_b32_e32 v9, v41
	v_mov_b32_e32 v10, v42
	v_mov_b32_e32 v11, v43
	v_mov_b32_e32 v12, v44
	v_mov_b32_e32 v13, v45
	v_mov_b32_e32 v14, v46
	v_mov_b32_e32 v15, v47
	v_mov_b32_e32 v16, v48
	v_mov_b32_e32 v17, v49
	v_mov_b32_e32 v18, v50
	v_mov_b32_e32 v19, v51
	v_mov_b32_e32 v20, v52
	v_mov_b32_e32 v21, v53
	v_mov_b32_e32 v22, v54
	v_mov_b32_e32 v23, v55
	v_mov_b32_e32 v24, v214
	v_mov_b32_e32 v25, v215
	v_mov_b32_e32 v26, v216
	v_mov_b32_e32 v27, v217
	v_mov_b32_e32 v28, v218
	v_mov_b32_e32 v29, v219
	v_mov_b32_e32 v30, v220
	v_mov_b32_e32 v31, v221
	s_add_u32 s98, s98, s50
	s_cmpk_lt_u32 s98, 2048
	s_cbranch_scc0 .Lfu0_nonext
	s_cmpk_lt_u32 s98, 2016
	s_cbranch_scc1 .Lfu0_m1
	s_sub_u32 s34, s98, 2016
	s_mov_b32 s35, 14
	s_branch .Lfu0_g1

; DI u16 f2bf(float x) { return (u16)(pack2(x, 0.f) & 0xffffu); }
; DI int opaque_tid() { int t = threadIdx.x; asm volatile("" : "+v"(t)); return t; }
; DI int crow(int i, int h) { return (i & 3) + 8 * (i >> 2) + 4 * h; }
; template <class F>
; DI void epi_bf16_tile(const f32x16 (&acc)[2][2], int m0, int n0, u16* dst0, long ld, char* smem, F f) {
;   const int tid = opaque_tid(), lane = tid & 63, w = tid >> 6, wm = w >> 1, wn = w & 1, h = lane >> 5;
;   u16* T = (u16*)smem;
; #pragma unroll
;   for (int mt = 0; mt < 2; mt++)
; #pragma unroll
;     for (int nt = 0; nt < 2; nt++)
; #pragma unroll
;       for (int i = 0; i < 16; i++) {
;         const int ml = wm * 64 + mt * 32 + crow(i, h), nl = wn * 64 + nt * 32 + (lane & 31);
;         T[ml * 136 + nl] = f2bf(f(m0 + ml, n0 + nl, acc[mt][nt][i]));
;       }
;   __syncthreads();
; DI void ffn_up_phase(const Params& p, const u16* xb, int ldx, const u16* wupT, u16* hid, char* smem) {
;     ...
;                epi_bf16_tile(acc, m0, n0, hid + (long)m0 * 4096 + n0, 4096, smem, [=](int m, int n, float v) {
;                  const float a = fmaxf(v * rs[m], 0.f);
;                  return a * a;
.Lfu0_nonext:
	v_mul_f32_e32 v62, v66, v0
	v_max_f32_e32 v62, 0, v62
	v_mul_f32_e32 v62, v62, v62
	v_cvt_pk_bf16_f32 v62, v62, v62
	ds_write_b16 v59, v62 offset:0
	v_mul_f32_e32 v63, v67, v1
	v_max_f32_e32 v63, 0, v63
	v_mul_f32_e32 v63, v63, v63
	v_cvt_pk_bf16_f32 v63, v63, v63
	ds_write_b16 v59, v63 offset:528
	v_mul_f32_e32 v64, v68, v2
	v_max_f32_e32 v64, 0, v64
	v_mul_f32_e32 v64, v64, v64
	v_cvt_pk_bf16_f32 v64, v64, v64
	ds_write_b16 v59, v64 offset:1056
	v_mul_f32_e32 v62, v69, v3
	v_max_f32_e32 v62, 0, v62
	v_mul_f32_e32 v62, v62, v62
	v_cvt_pk_bf16_f32 v62, v62, v62
	ds_write_b16 v59, v62 offset:1584
	v_mul_f32_e32 v63, v70, v4
	v_max_f32_e32 v63, 0, v63
	v_mul_f32_e32 v63, v63, v63
	v_cvt_pk_bf16_f32 v63, v63, v63
	ds_write_b16 v59, v63 offset:4224
	v_mul_f32_e32 v64, v71, v5
	v_max_f32_e32 v64, 0, v64
	v_mul_f32_e32 v64, v64, v64
	v_cvt_pk_bf16_f32 v64, v64, v64
	ds_write_b16 v59, v64 offset:4752
	v_mul_f32_e32 v62, v72, v6
	v_max_f32_e32 v62, 0, v62
	v_mul_f32_e32 v62, v62, v62
	v_cvt_pk_bf16_f32 v62, v62, v62
	ds_write_b16 v59, v62 offset:5280
	v_mul_f32_e32 v63, v73, v7
	v_max_f32_e32 v63, 0, v63
	v_mul_f32_e32 v63, v63, v63
	v_cvt_pk_bf16_f32 v63, v63, v63
	ds_write_b16 v59, v63 offset:5808
	v_mul_f32_e32 v64, v74, v8
	v_max_f32_e32 v64, 0, v64
	v_mul_f32_e32 v64, v64, v64
	v_cvt_pk_bf16_f32 v64, v64, v64
	ds_write_b16 v59, v64 offset:8448
	v_mul_f32_e32 v62, v75, v9
	v_max_f32_e32 v62, 0, v62
	v_mul_f32_e32 v62, v62, v62
	v_cvt_pk_bf16_f32 v62, v62, v62
	ds_write_b16 v59, v62 offset:8976
	v_mul_f32_e32 v63, v76, v10
	v_max_f32_e32 v63, 0, v63
	v_mul_f32_e32 v63, v63, v63
	v_cvt_pk_bf16_f32 v63, v63, v63
	ds_write_b16 v59, v63 offset:9504
	v_mul_f32_e32 v64, v77, v11
	v_max_f32_e32 v64, 0, v64
	v_mul_f32_e32 v64, v64, v64
	v_cvt_pk_bf16_f32 v64, v64, v64
	ds_write_b16 v59, v64 offset:10032
	v_mul_f32_e32 v62, v78, v12
	v_max_f32_e32 v62, 0, v62
	v_mul_f32_e32 v62, v62, v62
	v_cvt_pk_bf16_f32 v62, v62, v62
	ds_write_b16 v59, v62 offset:12672
	v_mul_f32_e32 v63, v79, v13
	v_max_f32_e32 v63, 0, v63
	v_mul_f32_e32 v63, v63, v63
	v_cvt_pk_bf16_f32 v63, v63, v63
	ds_write_b16 v59, v63 offset:13200
	v_mul_f32_e32 v64, v80, v14
	v_max_f32_e32 v64, 0, v64
	v_mul_f32_e32 v64, v64, v64
	v_cvt_pk_bf16_f32 v64, v64, v64
	ds_write_b16 v59, v64 offset:13728
	v_mul_f32_e32 v62, v81, v15
	v_max_f32_e32 v62, 0, v62
	v_mul_f32_e32 v62, v62, v62
	v_cvt_pk_bf16_f32 v62, v62, v62
	ds_write_b16 v59, v62 offset:14256
	v_mul_f32_e32 v62, v82, v0
	v_max_f32_e32 v62, 0, v62
	v_mul_f32_e32 v62, v62, v62
	v_cvt_pk_bf16_f32 v62, v62, v62
	ds_write_b16 v59, v62 offset:64
	v_mul_f32_e32 v63, v83, v1
	v_max_f32_e32 v63, 0, v63
	v_mul_f32_e32 v63, v63, v63
	v_cvt_pk_bf16_f32 v63, v63, v63
	ds_write_b16 v59, v63 offset:592
	v_mul_f32_e32 v64, v84, v2
	v_max_f32_e32 v64, 0, v64
	v_mul_f32_e32 v64, v64, v64
	v_cvt_pk_bf16_f32 v64, v64, v64
	ds_write_b16 v59, v64 offset:1120
	v_mul_f32_e32 v62, v85, v3
	v_max_f32_e32 v62, 0, v62
	v_mul_f32_e32 v62, v62, v62
	v_cvt_pk_bf16_f32 v62, v62, v62
	ds_write_b16 v59, v62 offset:1648
	v_mul_f32_e32 v63, v86, v4
	v_max_f32_e32 v63, 0, v63
	v_mul_f32_e32 v63, v63, v63
	v_cvt_pk_bf16_f32 v63, v63, v63
	ds_write_b16 v59, v63 offset:4288
	v_mul_f32_e32 v64, v87, v5
	v_max_f32_e32 v64, 0, v64
	v_mul_f32_e32 v64, v64, v64
	v_cvt_pk_bf16_f32 v64, v64, v64
	ds_write_b16 v59, v64 offset:4816
	v_mul_f32_e32 v62, v88, v6
	v_max_f32_e32 v62, 0, v62
	v_mul_f32_e32 v62, v62, v62
	v_cvt_pk_bf16_f32 v62, v62, v62
	ds_write_b16 v59, v62 offset:5344
	v_mul_f32_e32 v63, v89, v7
	v_max_f32_e32 v63, 0, v63
	v_mul_f32_e32 v63, v63, v63
	v_cvt_pk_bf16_f32 v63, v63, v63
	ds_write_b16 v59, v63 offset:5872
	v_mul_f32_e32 v64, v90, v8
	v_max_f32_e32 v64, 0, v64
	v_mul_f32_e32 v64, v64, v64
	v_cvt_pk_bf16_f32 v64, v64, v64
	ds_write_b16 v59, v64 offset:8512
	v_mul_f32_e32 v62, v91, v9
	v_max_f32_e32 v62, 0, v62
	v_mul_f32_e32 v62, v62, v62
	v_cvt_pk_bf16_f32 v62, v62, v62
	ds_write_b16 v59, v62 offset:9040
	v_mul_f32_e32 v63, v92, v10
	v_max_f32_e32 v63, 0, v63
	v_mul_f32_e32 v63, v63, v63
	v_cvt_pk_bf16_f32 v63, v63, v63
	ds_write_b16 v59, v63 offset:9568
	v_mul_f32_e32 v64, v93, v11
	v_max_f32_e32 v64, 0, v64
	v_mul_f32_e32 v64, v64, v64
	v_cvt_pk_bf16_f32 v64, v64, v64
	ds_write_b16 v59, v64 offset:10096
	v_mul_f32_e32 v62, v94, v12
	v_max_f32_e32 v62, 0, v62
	v_mul_f32_e32 v62, v62, v62
	v_cvt_pk_bf16_f32 v62, v62, v62
	ds_write_b16 v59, v62 offset:12736
	v_mul_f32_e32 v63, v95, v13
	v_max_f32_e32 v63, 0, v63
	v_mul_f32_e32 v63, v63, v63
	v_cvt_pk_bf16_f32 v63, v63, v63
	ds_write_b16 v59, v63 offset:13264
	v_mul_f32_e32 v64, v96, v14
	v_max_f32_e32 v64, 0, v64
	v_mul_f32_e32 v64, v64, v64
	v_cvt_pk_bf16_f32 v64, v64, v64
	ds_write_b16 v59, v64 offset:13792
	v_mul_f32_e32 v62, v97, v15
	v_max_f32_e32 v62, 0, v62
	v_mul_f32_e32 v62, v62, v62
	v_cvt_pk_bf16_f32 v62, v62, v62
	ds_write_b16 v59, v62 offset:14320
	v_mul_f32_e32 v62, v98, v0
	v_max_f32_e32 v62, 0, v62
	v_mul_f32_e32 v62, v62, v62
	v_cvt_pk_bf16_f32 v62, v62, v62
	ds_write_b16 v59, v62 offset:128
	v_mul_f32_e32 v63, v99, v1
	v_max_f32_e32 v63, 0, v63
	v_mul_f32_e32 v63, v63, v63
	v_cvt_pk_bf16_f32 v63, v63, v63
	ds_write_b16 v59, v63 offset:656
	v_mul_f32_e32 v64, v100, v2
	v_max_f32_e32 v64, 0, v64
	v_mul_f32_e32 v64, v64, v64
	v_cvt_pk_bf16_f32 v64, v64, v64
	ds_write_b16 v59, v64 offset:1184
	v_mul_f32_e32 v62, v101, v3
	v_max_f32_e32 v62, 0, v62
	v_mul_f32_e32 v62, v62, v62
	v_cvt_pk_bf16_f32 v62, v62, v62
	ds_write_b16 v59, v62 offset:1712
	v_mul_f32_e32 v63, v102, v4
	v_max_f32_e32 v63, 0, v63
	v_mul_f32_e32 v63, v63, v63
	v_cvt_pk_bf16_f32 v63, v63, v63
	ds_write_b16 v59, v63 offset:4352
; DI u16 f2bf(float x) { return (u16)(pack2(x, 0.f) & 0xffffu); }
; DI int opaque_tid() { int t = threadIdx.x; asm volatile("" : "+v"(t)); return t; }
; DI int crow(int i, int h) { return (i & 3) + 8 * (i >> 2) + 4 * h; }
; template <class F>
; DI void epi_bf16_tile(const f32x16 (&acc)[2][2], int m0, int n0, u16* dst0, long ld, char* smem, F f) {
;   const int tid = opaque_tid(), lane = tid & 63, w = tid >> 6, wm = w >> 1, wn = w & 1, h = lane >> 5;
;   u16* T = (u16*)smem;
; #pragma unroll
;   for (int mt = 0; mt < 2; mt++)
; #pragma unroll
;     for (int nt = 0; nt < 2; nt++)
; #pragma unroll
;       for (int i = 0; i < 16; i++) {
;         const int ml = wm * 64 + mt * 32 + crow(i, h), nl = wn * 64 + nt * 32 + (lane & 31);
;         T[ml * 136 + nl] = f2bf(f(m0 + ml, n0 + nl, acc[mt][nt][i]));
;       }
;   __syncthreads();
; DI void ffn_up_phase(const Params& p, const u16* xb, int ldx, const u16* wupT, u16* hid, char* smem) {
;     ...
;                epi_bf16_tile(acc, m0, n0, hid + (long)m0 * 4096 + n0, 4096, smem, [=](int m, int n, float v) {
;                  const float a = fmaxf(v * rs[m], 0.f);
;                  return a * a;
	v_mul_f32_e32 v64, v103, v5
	v_max_f32_e32 v64, 0, v64
	v_mul_f32_e32 v64, v64, v64
	v_cvt_pk_bf16_f32 v64, v64, v64
	ds_write_b16 v59, v64 offset:4880
	v_mul_f32_e32 v62, v104, v6
	v_max_f32_e32 v62, 0, v62
	v_mul_f32_e32 v62, v62, v62
	v_cvt_pk_bf16_f32 v62, v62, v62
	ds_write_b16 v59, v62 offset:5408
	v_mul_f32_e32 v63, v105, v7
	v_max_f32_e32 v63, 0, v63
	v_mul_f32_e32 v63, v63, v63
	v_cvt_pk_bf16_f32 v63, v63, v63
	ds_write_b16 v59, v63 offset:5936
	v_mul_f32_e32 v64, v106, v8
	v_max_f32_e32 v64, 0, v64
	v_mul_f32_e32 v64, v64, v64
	v_cvt_pk_bf16_f32 v64, v64, v64
	ds_write_b16 v59, v64 offset:8576
	v_mul_f32_e32 v62, v107, v9
	v_max_f32_e32 v62, 0, v62
	v_mul_f32_e32 v62, v62, v62
	v_cvt_pk_bf16_f32 v62, v62, v62
	ds_write_b16 v59, v62 offset:9104
	v_mul_f32_e32 v63, v108, v10
	v_max_f32_e32 v63, 0, v63
	v_mul_f32_e32 v63, v63, v63
	v_cvt_pk_bf16_f32 v63, v63, v63
	ds_write_b16 v59, v63 offset:9632
	v_mul_f32_e32 v64, v109, v11
	v_max_f32_e32 v64, 0, v64
	v_mul_f32_e32 v64, v64, v64
	v_cvt_pk_bf16_f32 v64, v64, v64
	ds_write_b16 v59, v64 offset:10160
	v_mul_f32_e32 v62, v110, v12
	v_max_f32_e32 v62, 0, v62
	v_mul_f32_e32 v62, v62, v62
	v_cvt_pk_bf16_f32 v62, v62, v62
	ds_write_b16 v59, v62 offset:12800
	v_mul_f32_e32 v63, v111, v13
	v_max_f32_e32 v63, 0, v63
	v_mul_f32_e32 v63, v63, v63
	v_cvt_pk_bf16_f32 v63, v63, v63
	ds_write_b16 v59, v63 offset:13328
	v_mul_f32_e32 v64, v112, v14
	v_max_f32_e32 v64, 0, v64
	v_mul_f32_e32 v64, v64, v64
	v_cvt_pk_bf16_f32 v64, v64, v64
	ds_write_b16 v59, v64 offset:13856
	v_mul_f32_e32 v62, v113, v15
	v_max_f32_e32 v62, 0, v62
	v_mul_f32_e32 v62, v62, v62
	v_cvt_pk_bf16_f32 v62, v62, v62
	ds_write_b16 v59, v62 offset:14384
	v_mul_f32_e32 v62, v114, v0
	v_max_f32_e32 v62, 0, v62
	v_mul_f32_e32 v62, v62, v62
	v_cvt_pk_bf16_f32 v62, v62, v62
	ds_write_b16 v59, v62 offset:192
	v_mul_f32_e32 v63, v115, v1
	v_max_f32_e32 v63, 0, v63
	v_mul_f32_e32 v63, v63, v63
	v_cvt_pk_bf16_f32 v63, v63, v63
	ds_write_b16 v59, v63 offset:720
	v_mul_f32_e32 v64, v116, v2
	v_max_f32_e32 v64, 0, v64
	v_mul_f32_e32 v64, v64, v64
	v_cvt_pk_bf16_f32 v64, v64, v64
	ds_write_b16 v59, v64 offset:1248
	v_mul_f32_e32 v62, v117, v3
	v_max_f32_e32 v62, 0, v62
	v_mul_f32_e32 v62, v62, v62
	v_cvt_pk_bf16_f32 v62, v62, v62
	ds_write_b16 v59, v62 offset:1776
	v_mul_f32_e32 v63, v118, v4
	v_max_f32_e32 v63, 0, v63
	v_mul_f32_e32 v63, v63, v63
	v_cvt_pk_bf16_f32 v63, v63, v63
	ds_write_b16 v59, v63 offset:4416
	v_mul_f32_e32 v64, v119, v5
	v_max_f32_e32 v64, 0, v64
	v_mul_f32_e32 v64, v64, v64
	v_cvt_pk_bf16_f32 v64, v64, v64
	ds_write_b16 v59, v64 offset:4944
	v_mul_f32_e32 v62, v120, v6
	v_max_f32_e32 v62, 0, v62
	v_mul_f32_e32 v62, v62, v62
	v_cvt_pk_bf16_f32 v62, v62, v62
	ds_write_b16 v59, v62 offset:5472
	v_mul_f32_e32 v63, v121, v7
	v_max_f32_e32 v63, 0, v63
	v_mul_f32_e32 v63, v63, v63
	v_cvt_pk_bf16_f32 v63, v63, v63
	ds_write_b16 v59, v63 offset:6000
	v_mul_f32_e32 v64, v122, v8
	v_max_f32_e32 v64, 0, v64
	v_mul_f32_e32 v64, v64, v64
	v_cvt_pk_bf16_f32 v64, v64, v64
	ds_write_b16 v59, v64 offset:8640
	v_mul_f32_e32 v62, v123, v9
	v_max_f32_e32 v62, 0, v62
	v_mul_f32_e32 v62, v62, v62
	v_cvt_pk_bf16_f32 v62, v62, v62
	ds_write_b16 v59, v62 offset:9168
	v_mul_f32_e32 v63, v124, v10
	v_max_f32_e32 v63, 0, v63
	v_mul_f32_e32 v63, v63, v63
	v_cvt_pk_bf16_f32 v63, v63, v63
	ds_write_b16 v59, v63 offset:9696
	v_mul_f32_e32 v64, v125, v11
	v_max_f32_e32 v64, 0, v64
	v_mul_f32_e32 v64, v64, v64
	v_cvt_pk_bf16_f32 v64, v64, v64
	ds_write_b16 v59, v64 offset:10224
	v_mul_f32_e32 v62, v126, v12
	v_max_f32_e32 v62, 0, v62
	v_mul_f32_e32 v62, v62, v62
	v_cvt_pk_bf16_f32 v62, v62, v62
	ds_write_b16 v59, v62 offset:12864
	v_mul_f32_e32 v63, v127, v13
	v_max_f32_e32 v63, 0, v63
	v_mul_f32_e32 v63, v63, v63
	v_cvt_pk_bf16_f32 v63, v63, v63
	ds_write_b16 v59, v63 offset:13392
	v_mul_f32_e32 v64, v128, v14
	v_max_f32_e32 v64, 0, v64
	v_mul_f32_e32 v64, v64, v64
	v_cvt_pk_bf16_f32 v64, v64, v64
	ds_write_b16 v59, v64 offset:13920
	v_mul_f32_e32 v62, v129, v15
	v_max_f32_e32 v62, 0, v62
	v_mul_f32_e32 v62, v62, v62
	v_cvt_pk_bf16_f32 v62, v62, v62
	ds_write_b16 v59, v62 offset:14448
	v_mul_f32_e32 v62, v130, v16
	v_max_f32_e32 v62, 0, v62
	v_mul_f32_e32 v62, v62, v62
	v_cvt_pk_bf16_f32 v62, v62, v62
	ds_write_b16 v59, v62 offset:16896
	v_mul_f32_e32 v63, v131, v17
	v_max_f32_e32 v63, 0, v63
	v_mul_f32_e32 v63, v63, v63
	v_cvt_pk_bf16_f32 v63, v63, v63
	ds_write_b16 v59, v63 offset:17424
	v_mul_f32_e32 v64, v132, v18
	v_max_f32_e32 v64, 0, v64
	v_mul_f32_e32 v64, v64, v64
	v_cvt_pk_bf16_f32 v64, v64, v64
	ds_write_b16 v59, v64 offset:17952
	v_mul_f32_e32 v62, v133, v19
	v_max_f32_e32 v62, 0, v62
	v_mul_f32_e32 v62, v62, v62
	v_cvt_pk_bf16_f32 v62, v62, v62
	ds_write_b16 v59, v62 offset:18480
	v_mul_f32_e32 v63, v134, v20
	v_max_f32_e32 v63, 0, v63
	v_mul_f32_e32 v63, v63, v63
	v_cvt_pk_bf16_f32 v63, v63, v63
	ds_write_b16 v59, v63 offset:21120
	v_mul_f32_e32 v64, v135, v21
	v_max_f32_e32 v64, 0, v64
	v_mul_f32_e32 v64, v64, v64
	v_cvt_pk_bf16_f32 v64, v64, v64
	ds_write_b16 v59, v64 offset:21648
	v_mul_f32_e32 v62, v136, v22
	v_max_f32_e32 v62, 0, v62
	v_mul_f32_e32 v62, v62, v62
	v_cvt_pk_bf16_f32 v62, v62, v62
	ds_write_b16 v59, v62 offset:22176
	v_mul_f32_e32 v63, v137, v23
	v_max_f32_e32 v63, 0, v63
	v_mul_f32_e32 v63, v63, v63
	v_cvt_pk_bf16_f32 v63, v63, v63
	ds_write_b16 v59, v63 offset:22704
	v_mul_f32_e32 v64, v138, v24
	v_max_f32_e32 v64, 0, v64
	v_mul_f32_e32 v64, v64, v64
	v_cvt_pk_bf16_f32 v64, v64, v64
	ds_write_b16 v59, v64 offset:25344
	v_mul_f32_e32 v62, v139, v25
	v_max_f32_e32 v62, 0, v62
	v_mul_f32_e32 v62, v62, v62
; DI u16 f2bf(float x) { return (u16)(pack2(x, 0.f) & 0xffffu); }
; DI int opaque_tid() { int t = threadIdx.x; asm volatile("" : "+v"(t)); return t; }
; DI int crow(int i, int h) { return (i & 3) + 8 * (i >> 2) + 4 * h; }
; template <class F>
; DI void epi_bf16_tile(const f32x16 (&acc)[2][2], int m0, int n0, u16* dst0, long ld, char* smem, F f) {
;   const int tid = opaque_tid(), lane = tid & 63, w = tid >> 6, wm = w >> 1, wn = w & 1, h = lane >> 5;
;   u16* T = (u16*)smem;
; #pragma unroll
;   for (int mt = 0; mt < 2; mt++)
; #pragma unroll
;     for (int nt = 0; nt < 2; nt++)
; #pragma unroll
;       for (int i = 0; i < 16; i++) {
;         const int ml = wm * 64 + mt * 32 + crow(i, h), nl = wn * 64 + nt * 32 + (lane & 31);
;         T[ml * 136 + nl] = f2bf(f(m0 + ml, n0 + nl, acc[mt][nt][i]));
;       }
;   __syncthreads();
; DI void ffn_up_phase(const Params& p, const u16* xb, int ldx, const u16* wupT, u16* hid, char* smem) {
;     ...
;                epi_bf16_tile(acc, m0, n0, hid + (long)m0 * 4096 + n0, 4096, smem, [=](int m, int n, float v) {
;                  const float a = fmaxf(v * rs[m], 0.f);
;                  return a * a;
	v_cvt_pk_bf16_f32 v62, v62, v62
	ds_write_b16 v59, v62 offset:25872
	v_mul_f32_e32 v63, v140, v26
	v_max_f32_e32 v63, 0, v63
	v_mul_f32_e32 v63, v63, v63
	v_cvt_pk_bf16_f32 v63, v63, v63
	ds_write_b16 v59, v63 offset:26400
	v_mul_f32_e32 v64, v141, v27
	v_max_f32_e32 v64, 0, v64
	v_mul_f32_e32 v64, v64, v64
	v_cvt_pk_bf16_f32 v64, v64, v64
	ds_write_b16 v59, v64 offset:26928
	v_mul_f32_e32 v62, v142, v28
	v_max_f32_e32 v62, 0, v62
	v_mul_f32_e32 v62, v62, v62
	v_cvt_pk_bf16_f32 v62, v62, v62
	ds_write_b16 v59, v62 offset:29568
	v_mul_f32_e32 v63, v143, v29
	v_max_f32_e32 v63, 0, v63
	v_mul_f32_e32 v63, v63, v63
	v_cvt_pk_bf16_f32 v63, v63, v63
	ds_write_b16 v59, v63 offset:30096
	v_mul_f32_e32 v64, v144, v30
	v_max_f32_e32 v64, 0, v64
	v_mul_f32_e32 v64, v64, v64
	v_cvt_pk_bf16_f32 v64, v64, v64
	ds_write_b16 v59, v64 offset:30624
	v_mul_f32_e32 v62, v145, v31
	v_max_f32_e32 v62, 0, v62
	v_mul_f32_e32 v62, v62, v62
	v_cvt_pk_bf16_f32 v62, v62, v62
	ds_write_b16 v59, v62 offset:31152
	v_mul_f32_e32 v62, v146, v16
	v_max_f32_e32 v62, 0, v62
	v_mul_f32_e32 v62, v62, v62
	v_cvt_pk_bf16_f32 v62, v62, v62
	ds_write_b16 v59, v62 offset:16960
	v_mul_f32_e32 v63, v147, v17
	v_max_f32_e32 v63, 0, v63
	v_mul_f32_e32 v63, v63, v63
	v_cvt_pk_bf16_f32 v63, v63, v63
	ds_write_b16 v59, v63 offset:17488
	v_mul_f32_e32 v64, v148, v18
	v_max_f32_e32 v64, 0, v64
	v_mul_f32_e32 v64, v64, v64
	v_cvt_pk_bf16_f32 v64, v64, v64
	ds_write_b16 v59, v64 offset:18016
	v_mul_f32_e32 v62, v149, v19
	v_max_f32_e32 v62, 0, v62
	v_mul_f32_e32 v62, v62, v62
	v_cvt_pk_bf16_f32 v62, v62, v62
	ds_write_b16 v59, v62 offset:18544
	v_mul_f32_e32 v63, v150, v20
	v_max_f32_e32 v63, 0, v63
	v_mul_f32_e32 v63, v63, v63
	v_cvt_pk_bf16_f32 v63, v63, v63
	ds_write_b16 v59, v63 offset:21184
	v_mul_f32_e32 v64, v151, v21
	v_max_f32_e32 v64, 0, v64
	v_mul_f32_e32 v64, v64, v64
	v_cvt_pk_bf16_f32 v64, v64, v64
	ds_write_b16 v59, v64 offset:21712
	v_mul_f32_e32 v62, v152, v22
	v_max_f32_e32 v62, 0, v62
	v_mul_f32_e32 v62, v62, v62
	v_cvt_pk_bf16_f32 v62, v62, v62
	ds_write_b16 v59, v62 offset:22240
	v_mul_f32_e32 v63, v153, v23
	v_max_f32_e32 v63, 0, v63
	v_mul_f32_e32 v63, v63, v63
	v_cvt_pk_bf16_f32 v63, v63, v63
	ds_write_b16 v59, v63 offset:22768
	v_mul_f32_e32 v64, v154, v24
	v_max_f32_e32 v64, 0, v64
	v_mul_f32_e32 v64, v64, v64
	v_cvt_pk_bf16_f32 v64, v64, v64
	ds_write_b16 v59, v64 offset:25408
	v_mul_f32_e32 v62, v155, v25
	v_max_f32_e32 v62, 0, v62
	v_mul_f32_e32 v62, v62, v62
	v_cvt_pk_bf16_f32 v62, v62, v62
	ds_write_b16 v59, v62 offset:25936
	v_mul_f32_e32 v63, v156, v26
	v_max_f32_e32 v63, 0, v63
	v_mul_f32_e32 v63, v63, v63
	v_cvt_pk_bf16_f32 v63, v63, v63
	ds_write_b16 v59, v63 offset:26464
	v_mul_f32_e32 v64, v157, v27
	v_max_f32_e32 v64, 0, v64
	v_mul_f32_e32 v64, v64, v64
	v_cvt_pk_bf16_f32 v64, v64, v64
	ds_write_b16 v59, v64 offset:26992
	v_mul_f32_e32 v62, v158, v28
	v_max_f32_e32 v62, 0, v62
	v_mul_f32_e32 v62, v62, v62
	v_cvt_pk_bf16_f32 v62, v62, v62
	ds_write_b16 v59, v62 offset:29632
	v_mul_f32_e32 v63, v159, v29
	v_max_f32_e32 v63, 0, v63
	v_mul_f32_e32 v63, v63, v63
	v_cvt_pk_bf16_f32 v63, v63, v63
	ds_write_b16 v59, v63 offset:30160
	v_mul_f32_e32 v64, v160, v30
	v_max_f32_e32 v64, 0, v64
	v_mul_f32_e32 v64, v64, v64
	v_cvt_pk_bf16_f32 v64, v64, v64
	ds_write_b16 v59, v64 offset:30688
	v_mul_f32_e32 v62, v161, v31
	v_max_f32_e32 v62, 0, v62
	v_mul_f32_e32 v62, v62, v62
	v_cvt_pk_bf16_f32 v62, v62, v62
	ds_write_b16 v59, v62 offset:31216
	v_mul_f32_e32 v62, v162, v16
	v_max_f32_e32 v62, 0, v62
	v_mul_f32_e32 v62, v62, v62
	v_cvt_pk_bf16_f32 v62, v62, v62
	ds_write_b16 v59, v62 offset:17024
	v_mul_f32_e32 v63, v163, v17
	v_max_f32_e32 v63, 0, v63
	v_mul_f32_e32 v63, v63, v63
	v_cvt_pk_bf16_f32 v63, v63, v63
	ds_write_b16 v59, v63 offset:17552
	v_mul_f32_e32 v64, v164, v18
	v_max_f32_e32 v64, 0, v64
	v_mul_f32_e32 v64, v64, v64
	v_cvt_pk_bf16_f32 v64, v64, v64
	ds_write_b16 v59, v64 offset:18080
	v_mul_f32_e32 v62, v165, v19
	v_max_f32_e32 v62, 0, v62
	v_mul_f32_e32 v62, v62, v62
	v_cvt_pk_bf16_f32 v62, v62, v62
	ds_write_b16 v59, v62 offset:18608
	v_mul_f32_e32 v63, v166, v20
	v_max_f32_e32 v63, 0, v63
	v_mul_f32_e32 v63, v63, v63
	v_cvt_pk_bf16_f32 v63, v63, v63
	ds_write_b16 v59, v63 offset:21248
	v_mul_f32_e32 v64, v167, v21
	v_max_f32_e32 v64, 0, v64
	v_mul_f32_e32 v64, v64, v64
	v_cvt_pk_bf16_f32 v64, v64, v64
	ds_write_b16 v59, v64 offset:21776
	v_mul_f32_e32 v62, v168, v22
	v_max_f32_e32 v62, 0, v62
	v_mul_f32_e32 v62, v62, v62
	v_cvt_pk_bf16_f32 v62, v62, v62
	ds_write_b16 v59, v62 offset:22304
	v_mul_f32_e32 v63, v169, v23
	v_max_f32_e32 v63, 0, v63
	v_mul_f32_e32 v63, v63, v63
	v_cvt_pk_bf16_f32 v63, v63, v63
	ds_write_b16 v59, v63 offset:22832
	v_mul_f32_e32 v64, v170, v24
	v_max_f32_e32 v64, 0, v64
	v_mul_f32_e32 v64, v64, v64
	v_cvt_pk_bf16_f32 v64, v64, v64
	ds_write_b16 v59, v64 offset:25472
	v_mul_f32_e32 v62, v171, v25
	v_max_f32_e32 v62, 0, v62
	v_mul_f32_e32 v62, v62, v62
	v_cvt_pk_bf16_f32 v62, v62, v62
	ds_write_b16 v59, v62 offset:26000
	v_mul_f32_e32 v63, v172, v26
	v_max_f32_e32 v63, 0, v63
	v_mul_f32_e32 v63, v63, v63
	v_cvt_pk_bf16_f32 v63, v63, v63
	ds_write_b16 v59, v63 offset:26528
	v_mul_f32_e32 v64, v173, v27
	v_max_f32_e32 v64, 0, v64
	v_mul_f32_e32 v64, v64, v64
	v_cvt_pk_bf16_f32 v64, v64, v64
	ds_write_b16 v59, v64 offset:27056
	v_mul_f32_e32 v62, v174, v28
	v_max_f32_e32 v62, 0, v62
	v_mul_f32_e32 v62, v62, v62
	v_cvt_pk_bf16_f32 v62, v62, v62
	ds_write_b16 v59, v62 offset:29696
	v_mul_f32_e32 v63, v175, v29
	v_max_f32_e32 v63, 0, v63
	v_mul_f32_e32 v63, v63, v63
	v_cvt_pk_bf16_f32 v63, v63, v63
; DI u16 f2bf(float x) { return (u16)(pack2(x, 0.f) & 0xffffu); }
; DI int crow(int i, int h) { return (i & 3) + 8 * (i >> 2) + 4 * h; }
; template <class F>
; DI void epi_bf16_tile(const f32x16 (&acc)[2][2], int m0, int n0, u16* dst0, long ld, char* smem, F f) {
;     ...
;       for (int i = 0; i < 16; i++) {
;         const int ml = wm * 64 + mt * 32 + crow(i, h), nl = wn * 64 + nt * 32 + (lane & 31);
;         T[ml * 136 + nl] = f2bf(f(m0 + ml, n0 + nl, acc[mt][nt][i]));
;       }
;   __syncthreads();
; #pragma unroll
;   for (int j = 0; j < 8; j++) {
;     const int idx = tid + 256 * j, row = idx >> 4, ch = idx & 15;
;     *(uint4*)(dst0 + (long)row * ld + ch * 8) = *(const uint4*)(T + row * 136 + ch * 8);
;   }
;   __syncthreads();
; template <class AL, class BL, class EP>
; DI void gemm_phase(int MT, int NTL, int K, AL al, BL bl, EP ep, char* smem) {
;   for (int t = blockIdx.x; t < MT * NTL; t += gridDim.x) {
;     const int tm = t % MT, tn = t / MT;
;     f32x16 acc[2][2];
;     gemm_core(al, bl, tm * 128, tn * 128, K, smem, acc);
;     ep(acc, tm * 128, tn * 128);
;   }
	ds_write_b16 v59, v63 offset:30224
	v_mul_f32_e32 v64, v176, v30
	v_max_f32_e32 v64, 0, v64
	v_mul_f32_e32 v64, v64, v64
	v_cvt_pk_bf16_f32 v64, v64, v64
	ds_write_b16 v59, v64 offset:30752
	v_mul_f32_e32 v62, v177, v31
	v_max_f32_e32 v62, 0, v62
	v_mul_f32_e32 v62, v62, v62
	v_cvt_pk_bf16_f32 v62, v62, v62
	ds_write_b16 v59, v62 offset:31280
	v_mul_f32_e32 v62, v178, v16
	v_max_f32_e32 v62, 0, v62
	v_mul_f32_e32 v62, v62, v62
	v_cvt_pk_bf16_f32 v62, v62, v62
	ds_write_b16 v59, v62 offset:17088
	v_mul_f32_e32 v63, v179, v17
	v_max_f32_e32 v63, 0, v63
	v_mul_f32_e32 v63, v63, v63
	v_cvt_pk_bf16_f32 v63, v63, v63
	ds_write_b16 v59, v63 offset:17616
	v_mul_f32_e32 v64, v180, v18
	v_max_f32_e32 v64, 0, v64
	v_mul_f32_e32 v64, v64, v64
	v_cvt_pk_bf16_f32 v64, v64, v64
	ds_write_b16 v59, v64 offset:18144
	v_mul_f32_e32 v62, v181, v19
	v_max_f32_e32 v62, 0, v62
	v_mul_f32_e32 v62, v62, v62
	v_cvt_pk_bf16_f32 v62, v62, v62
	ds_write_b16 v59, v62 offset:18672
	v_mul_f32_e32 v63, v182, v20
	v_max_f32_e32 v63, 0, v63
	v_mul_f32_e32 v63, v63, v63
	v_cvt_pk_bf16_f32 v63, v63, v63
	ds_write_b16 v59, v63 offset:21312
	v_mul_f32_e32 v64, v183, v21
	v_max_f32_e32 v64, 0, v64
	v_mul_f32_e32 v64, v64, v64
	v_cvt_pk_bf16_f32 v64, v64, v64
	ds_write_b16 v59, v64 offset:21840
	v_mul_f32_e32 v62, v184, v22
	v_max_f32_e32 v62, 0, v62
	v_mul_f32_e32 v62, v62, v62
	v_cvt_pk_bf16_f32 v62, v62, v62
	ds_write_b16 v59, v62 offset:22368
	v_mul_f32_e32 v63, v185, v23
	v_max_f32_e32 v63, 0, v63
	v_mul_f32_e32 v63, v63, v63
	v_cvt_pk_bf16_f32 v63, v63, v63
	ds_write_b16 v59, v63 offset:22896
	v_mul_f32_e32 v64, v186, v24
	v_max_f32_e32 v64, 0, v64
	v_mul_f32_e32 v64, v64, v64
	v_cvt_pk_bf16_f32 v64, v64, v64
	ds_write_b16 v59, v64 offset:25536
	v_mul_f32_e32 v62, v187, v25
	v_max_f32_e32 v62, 0, v62
	v_mul_f32_e32 v62, v62, v62
	v_cvt_pk_bf16_f32 v62, v62, v62
	ds_write_b16 v59, v62 offset:26064
	v_mul_f32_e32 v63, v188, v26
	v_max_f32_e32 v63, 0, v63
	v_mul_f32_e32 v63, v63, v63
	v_cvt_pk_bf16_f32 v63, v63, v63
	ds_write_b16 v59, v63 offset:26592
	v_mul_f32_e32 v64, v189, v27
	v_max_f32_e32 v64, 0, v64
	v_mul_f32_e32 v64, v64, v64
	v_cvt_pk_bf16_f32 v64, v64, v64
	ds_write_b16 v59, v64 offset:27120
	v_mul_f32_e32 v62, v190, v28
	v_max_f32_e32 v62, 0, v62
	v_mul_f32_e32 v62, v62, v62
	v_cvt_pk_bf16_f32 v62, v62, v62
	ds_write_b16 v59, v62 offset:29760
	v_mul_f32_e32 v63, v191, v29
	v_max_f32_e32 v63, 0, v63
	v_mul_f32_e32 v63, v63, v63
	v_cvt_pk_bf16_f32 v63, v63, v63
	ds_write_b16 v59, v63 offset:30288
	v_mul_f32_e32 v64, v192, v30
	v_max_f32_e32 v64, 0, v64
	v_mul_f32_e32 v64, v64, v64
	v_cvt_pk_bf16_f32 v64, v64, v64
	ds_write_b16 v59, v64 offset:30816
	v_mul_f32_e32 v62, v193, v31
	v_max_f32_e32 v62, 0, v62
	v_mul_f32_e32 v62, v62, v62
	v_cvt_pk_bf16_f32 v62, v62, v62
	ds_write_b16 v59, v62 offset:31344
	s_waitcnt lgkmcnt(0)
	s_barrier
	ds_read_b128 v[0:3], v60 offset:0
	ds_read_b128 v[4:7], v60 offset:4224
	ds_read_b128 v[8:11], v60 offset:8448
	ds_read_b128 v[12:15], v60 offset:12672
	ds_read_b128 v[16:19], v60 offset:16896
	ds_read_b128 v[20:23], v60 offset:21120
	ds_read_b128 v[24:27], v60 offset:25344
	ds_read_b128 v[28:31], v60 offset:29568
	s_waitcnt lgkmcnt(7)
	global_store_dwordx4 v227, v[0:3], s[20:21]
	s_add_u32 s20, s20, 65536
	s_addc_u32 s21, s21, 0
	ds_read_b128 v[0:3], v60 offset:33792
	s_waitcnt lgkmcnt(7)
	global_store_dwordx4 v227, v[4:7], s[20:21]
	s_add_u32 s20, s20, 65536
	s_addc_u32 s21, s21, 0
	ds_read_b128 v[4:7], v60 offset:38016
	s_waitcnt lgkmcnt(7)
	global_store_dwordx4 v227, v[8:11], s[20:21]
	s_add_u32 s20, s20, 65536
	s_addc_u32 s21, s21, 0
	ds_read_b128 v[8:11], v60 offset:42240
	s_waitcnt lgkmcnt(7)
	global_store_dwordx4 v227, v[12:15], s[20:21]
	s_add_u32 s20, s20, 65536
	s_addc_u32 s21, s21, 0
	ds_read_b128 v[12:15], v60 offset:46464
	s_waitcnt lgkmcnt(7)
	global_store_dwordx4 v227, v[16:19], s[20:21]
	s_add_u32 s20, s20, 65536
	s_addc_u32 s21, s21, 0
	ds_read_b128 v[16:19], v60 offset:50688
	s_waitcnt lgkmcnt(7)
	global_store_dwordx4 v227, v[20:23], s[20:21]
	s_add_u32 s20, s20, 65536
	s_addc_u32 s21, s21, 0
	ds_read_b128 v[20:23], v60 offset:54912
	s_waitcnt lgkmcnt(7)
	global_store_dwordx4 v227, v[24:27], s[20:21]
	s_add_u32 s20, s20, 65536
	s_addc_u32 s21, s21, 0
	ds_read_b128 v[24:27], v60 offset:59136
	s_waitcnt lgkmcnt(7)
	global_store_dwordx4 v227, v[28:31], s[20:21]
	s_add_u32 s20, s20, 65536
	s_addc_u32 s21, s21, 0
	ds_read_b128 v[28:31], v60 offset:63360
	s_waitcnt lgkmcnt(7)
	global_store_dwordx4 v227, v[0:3], s[20:21]
	s_add_u32 s20, s20, 65536
	s_addc_u32 s21, s21, 0
	s_waitcnt lgkmcnt(6)
	global_store_dwordx4 v227, v[4:7], s[20:21]
	s_add_u32 s20, s20, 65536
	s_addc_u32 s21, s21, 0
	s_waitcnt lgkmcnt(5)
	global_store_dwordx4 v227, v[8:11], s[20:21]
	s_add_u32 s20, s20, 65536
	s_addc_u32 s21, s21, 0
	s_waitcnt lgkmcnt(4)
	global_store_dwordx4 v227, v[12:15], s[20:21]
	s_add_u32 s20, s20, 65536
	s_addc_u32 s21, s21, 0
	s_waitcnt lgkmcnt(3)
	global_store_dwordx4 v227, v[16:19], s[20:21]
	s_add_u32 s20, s20, 65536
	s_addc_u32 s21, s21, 0
	s_waitcnt lgkmcnt(2)
	global_store_dwordx4 v227, v[20:23], s[20:21]
	s_add_u32 s20, s20, 65536
	s_addc_u32 s21, s21, 0
	s_waitcnt lgkmcnt(1)
	global_store_dwordx4 v227, v[24:27], s[20:21]
	s_add_u32 s20, s20, 65536
	s_addc_u32 s21, s21, 0
	s_waitcnt lgkmcnt(0)
	global_store_dwordx4 v227, v[28:31], s[20:21]
	s_barrier
	s_cmpk_lt_u32 s98, 2048
	s_cbranch_scc1 .Lfu0_tile
	s_cmpk_lt_u32 s78, 0xe0
	s_cbranch_scc0 .Lfu0_s2
	s_cmpk_ge_u32 s78, 0x70
	s_cselect_b32 s0, 1, 0
	s_mul_i32 s1, s0, 0x70
	s_sub_u32 s1, s78, s1
	s_add_u32 s1, s1, 32
	s_add_u32 s0, s0, 28
	s_branch .Lfu0_s3

; template <class AL, class BL, class EP>
; DI void gemm_phase(int MT, int NTL, int K, AL al, BL bl, EP ep, char* smem) {
;   for (int t = blockIdx.x; t < MT * NTL; t += gridDim.x) {
;     const int tm = t % MT, tn = t / MT;
;     f32x16 acc[2][2];
;     gemm_core(al, bl, tm * 128, tn * 128, K, smem, acc);
; DI void ffn_up_phase(const Params& p, const u16* xb, int ldx, const u16* wupT, u16* hid, char* smem) {
;   const float* rs = (const float*)(p.ws + W_RS);
;   gemm_phase(NT / 128, 32, 1024,
;              [=](int m, int k) { return xb + (long)m * ldx + k; },
;              [=](int n, int k) { return wupT + (long)n * 1024 + k; },
.LBB0_1672:
	s_or_b64 exec, exec, s[0:1]
	s_andn2_b64 vcc, exec, s[58:59]
	s_waitcnt lgkmcnt(0)
	s_barrier
	s_cbranch_vccnz .LBB0_1676
	s_add_u32 s6, s70, 0x7000000
	s_addc_u32 s7, s71, 0
	s_add_u32 s20, s70, 0x8000000
	s_addc_u32 s21, s71, 0
	s_add_u32 s12, s70, 0x10000
	s_mov_b64 s[10:11], 0x10000
	s_addc_u32 s13, s71, 0
	s_add_i32 s22, s67, 48
	s_lshl_b32 s23, s50, 7
	v_mov_b32_e32 v65, 0
	s_mov_b32 s24, 0x10000
	s_mov_b64 s[14:15], 0x20000
	s_mov_b32 s25, 0x20000
	s_mov_b64 s[16:17], 0x30000
	s_mov_b32 s26, 0x30000
	s_movk_i32 s27, 0x90
	s_mov_b32 s28, 0xfffffc0
	s_movk_i32 s29, 0x110
	s_mov_b32 s30, s78
	v_bfe_u32 v62, v202, 5, 1
	v_and_b32_e32 v63, 31, v202
	v_lshrrev_b32_e32 v64, 7, v202
	v_bfe_u32 v254, v202, 6, 1
	v_lshlrev_b32_e32 v253, 2, v62
	v_lshl_add_u32 v253, v64, 6, v253
	v_mul_u32_u24_e32 v59, 528, v253
	v_lshlrev_b32_e32 v252, 2, v253
	v_lshl_add_u32 v253, v254, 7, v63
	v_lshl_add_u32 v59, v253, 1, v59
	v_mul_u32_u24_e32 v57, 80, v253
	v_lshl_add_u32 v57, v62, 4, v57
	v_add_u32_e32 v57, 10240, v57
	v_lshl_add_u32 v253, v64, 6, v63
	v_mul_u32_u24_e32 v56, 80, v253
	v_lshl_add_u32 v56, v62, 4, v56
	v_lshrrev_b32_e32 v253, 5, v202
	v_mul_u32_u24_e32 v60, 528, v253
	v_lshl_add_u32 v60, v63, 4, v60
	v_mul_u32_u24_e32 v227, 8192, v253
	v_lshl_add_u32 v227, v63, 4, v227
	v_lshrrev_b32_e32 v253, 2, v202
	v_and_b32_e32 v254, 3, v202
	v_lshlrev_b32_e32 v254, 4, v254
	v_mov_b32_e32 v255, 0
	v_mul_u32_u24_e32 v58, 80, v253
	v_add_u32_e32 v58, v58, v254
	s_mov_b32 s98, s78
	s_cmpk_lt_u32 s98, 2016
	s_cbranch_scc1 .Lfu1_m0
	s_sub_u32 s31, s98, 2016
	s_mov_b32 s33, 14
	s_branch .Lfu1_g0

; #define G_LOAD(S, kt_) do { G_LD1(S##a0, S##b0, 0, kt_); G_LD1(S##a1, S##b1, 1, kt_); G_LD1(S##a2, S##b2, 2, kt_); G_LD1(S##a3, S##b3, 3, kt_); } while (0)
; #define G_STORE(S, buf_) do { G_ST1(S##a0, S##b0, 0, buf_); G_ST1(S##a1, S##b1, 1, buf_); G_ST1(S##a2, S##b2, 2, buf_); G_ST1(S##a3, S##b3, 3, buf_); } while (0)
; template <class AL, class BL>
; DI void gemm_core(AL al, BL bl, int m0, int n0, int K, char* smem, f32x16 (&acc)[2][2]) {
;     ...
;   const int srow = tid >> 3, sch = tid & 7;
;     ...
;   G_LOAD(x, 0);
;   G_STORE(x, 0);
;   G_LOAD(x, 1);
;   G_LOAD(y, (nk > 2) ? 2 : 1);
;   __syncthreads();
;   for (int kt = 0; kt < nk; kt += 2) {
;     G_TILE(0, x, true, (kt + 3 < nk), kt + 3);
;     __syncthreads();
;     G_TILE(1, y, (kt + 2 < nk), (kt + 4 < nk), kt + 4);
;     __syncthreads();
;   }
; template <class AL, class BL, class EP>
; DI void gemm_phase(int MT, int NTL, int K, AL al, BL bl, EP ep, char* smem) {
;   for (int t = blockIdx.x; t < MT * NTL; t += gridDim.x) {
;     const int tm = t % MT, tn = t / MT;
;     f32x16 acc[2][2];
;     gemm_core(al, bl, tm * 128, tn * 128, K, smem, acc);
.Lfu1_g0:
	s_lshl_b32 s0, s31, 7
	v_add_u32_e32 v62, s0, v253
	v_mov_b32_e32 v63, 4096
	v_mad_u64_u32 v[240:241], s[0:1], v62, v63, v[254:255]
	v_lshl_add_u64 v[240:241], v[240:241], 0, s[68:69]
	s_mov_b32 s0, 262144
	s_mov_b32 s1, 0
	v_lshl_add_u64 v[242:243], v[240:241], 0, s[0:1]
	s_lshl_b32 s0, s33, 8
	v_add_u32_e32 v62, s0, v253
	v_mov_b32_e32 v63, 2048
	v_mad_u64_u32 v[244:245], s[0:1], v62, v63, v[254:255]
	v_lshl_add_u64 v[244:245], v[244:245], 0, s[6:7]
	s_mov_b32 s0, 131072
	s_mov_b32 s1, 0
	v_lshl_add_u64 v[246:247], v[244:245], 0, s[0:1]
	v_lshl_add_u64 v[248:249], v[246:247], 0, s[0:1]
	v_lshl_add_u64 v[250:251], v[248:249], 0, s[0:1]
	global_load_dwordx4 v[32:35], v[240:241], off offset:2048
	global_load_dwordx4 v[36:39], v[242:243], off offset:2048
	global_load_dwordx4 v[40:43], v[244:245], off offset:0
	global_load_dwordx4 v[44:47], v[246:247], off offset:0
	global_load_dwordx4 v[48:51], v[248:249], off offset:0
	global_load_dwordx4 v[52:55], v[250:251], off offset:0
	global_load_dwordx4 v[214:217], v[240:241], off offset:2112
	global_load_dwordx4 v[218:221], v[242:243], off offset:2112
	global_load_dwordx4 v[222:225], v[244:245], off offset:64
	global_load_dwordx4 v[228:231], v[246:247], off offset:64
	global_load_dwordx4 v[232:235], v[248:249], off offset:64
	global_load_dwordx4 v[236:239], v[250:251], off offset:64
.Lfu1_tile:
	s_lshl_b32 s0, s31, 9
	v_add_u32_e32 v61, s0, v252
	s_lshl_b32 s0, s31, 7
	s_mul_i32 s1, s0, 8192
	s_mul_hi_u32 s2, s0, 8192
	s_add_u32 s18, s20, s1
	s_addc_u32 s19, s21, s2
	s_lshl_b32 s1, s33, 9
	s_add_u32 s18, s18, s1
	s_addc_u32 s19, s19, 0
	s_waitcnt vmcnt(6)
	ds_write_b128 v58, v[32:35] offset:0
	ds_write_b128 v58, v[36:39] offset:5120
	ds_write_b128 v58, v[40:43] offset:10240
	ds_write_b128 v58, v[44:47] offset:15360
	ds_write_b128 v58, v[48:51] offset:20480
	ds_write_b128 v58, v[52:55] offset:25600
	global_load_dwordx4 v[32:35], v[240:241], off offset:2176
	global_load_dwordx4 v[36:39], v[242:243], off offset:2176
	global_load_dwordx4 v[40:43], v[244:245], off offset:128
	global_load_dwordx4 v[44:47], v[246:247], off offset:128
	global_load_dwordx4 v[48:51], v[248:249], off offset:128
	global_load_dwordx4 v[52:55], v[250:251], off offset:128
	s_waitcnt lgkmcnt(0)
	s_barrier
	ds_read_b128 v[0:3], v56 offset:0
	ds_read_b128 v[4:7], v56 offset:2560
	ds_read_b128 v[8:11], v57 offset:0
	ds_read_b128 v[12:15], v57 offset:2560
	ds_read_b128 v[16:19], v57 offset:5120
	ds_read_b128 v[20:23], v57 offset:7680
	ds_read_b128 v[24:27], v56 offset:32
	ds_read_b128 v[28:31], v56 offset:2592
	s_waitcnt lgkmcnt(4)
	v_mfma_f32_32x32x16_bf16 v[66:81], v[0:3], v[8:11], 0
	v_mfma_f32_32x32x16_bf16 v[82:97], v[0:3], v[12:15], 0
	s_waitcnt vmcnt(6)
	ds_write_b128 v58, v[214:217] offset:30720
	ds_write_b128 v58, v[218:221] offset:35840
	s_waitcnt lgkmcnt(4)
	v_mfma_f32_32x32x16_bf16 v[98:113], v[0:3], v[16:19], 0
	v_mfma_f32_32x32x16_bf16 v[114:129], v[0:3], v[20:23], 0
	ds_read_b128 v[0:3], v57 offset:32
	ds_write_b128 v58, v[222:225] offset:40960
	ds_write_b128 v58, v[228:231] offset:46080
	v_mfma_f32_32x32x16_bf16 v[130:145], v[4:7], v[8:11], 0
	v_mfma_f32_32x32x16_bf16 v[146:161], v[4:7], v[12:15], 0
	ds_write_b128 v58, v[232:235] offset:51200
	ds_write_b128 v58, v[236:239] offset:56320
	v_mfma_f32_32x32x16_bf16 v[162:177], v[4:7], v[16:19], 0
	v_mfma_f32_32x32x16_bf16 v[178:193], v[4:7], v[20:23], 0
	ds_read_b128 v[4:7], v57 offset:2592
	ds_read_b128 v[8:11], v57 offset:5152
	ds_read_b128 v[12:15], v57 offset:7712
	s_waitcnt lgkmcnt(2)
	v_mfma_f32_32x32x16_bf16 v[66:81], v[24:27], v[0:3], v[66:81]
	global_load_dwordx4 v[214:217], v[240:241], off offset:2240
	global_load_dwordx4 v[218:221], v[242:243], off offset:2240
	v_mfma_f32_32x32x16_bf16 v[82:97], v[24:27], v[4:7], v[82:97]
	s_waitcnt lgkmcnt(0)
	v_mfma_f32_32x32x16_bf16 v[98:113], v[24:27], v[8:11], v[98:113]
	global_load_dwordx4 v[222:225], v[244:245], off offset:192
	global_load_dwordx4 v[228:231], v[246:247], off offset:192
	v_mfma_f32_32x32x16_bf16 v[114:129], v[24:27], v[12:15], v[114:129]
	v_mfma_f32_32x32x16_bf16 v[130:145], v[28:31], v[0:3], v[130:145]
	global_load_dwordx4 v[232:235], v[248:249], off offset:192
	global_load_dwordx4 v[236:239], v[250:251], off offset:192
	v_mfma_f32_32x32x16_bf16 v[146:161], v[28:31], v[4:7], v[146:161]
	v_mfma_f32_32x32x16_bf16 v[162:177], v[28:31], v[8:11], v[162:177]
	v_mfma_f32_32x32x16_bf16 v[178:193], v[28:31], v[12:15], v[178:193]
	s_waitcnt lgkmcnt(0)
	s_barrier
	ds_read_b128 v[0:3], v56 offset:30720
	ds_read_b128 v[4:7], v56 offset:33280
	ds_read_b128 v[8:11], v57 offset:30720
	ds_read_b128 v[12:15], v57 offset:33280
	ds_read_b128 v[16:19], v57 offset:35840
	ds_read_b128 v[20:23], v57 offset:38400
	ds_read_b128 v[24:27], v56 offset:30752
	ds_read_b128 v[28:31], v56 offset:33312
	s_waitcnt lgkmcnt(4)
	v_mfma_f32_32x32x16_bf16 v[66:81], v[0:3], v[8:11], v[66:81]
	v_mfma_f32_32x32x16_bf16 v[82:97], v[0:3], v[12:15], v[82:97]
	s_waitcnt vmcnt(6)
	ds_write_b128 v58, v[32:35] offset:0
	ds_write_b128 v58, v[36:39] offset:5120
	s_waitcnt lgkmcnt(4)
	v_mfma_f32_32x32x16_bf16 v[98:113], v[0:3], v[16:19], v[98:113]
	v_mfma_f32_32x32x16_bf16 v[114:129], v[0:3], v[20:23], v[114:129]
	ds_read_b128 v[0:3], v57 offset:30752
	ds_write_b128 v58, v[40:43] offset:10240
	ds_write_b128 v58, v[44:47] offset:15360
	v_mfma_f32_32x32x16_bf16 v[130:145], v[4:7], v[8:11], v[130:145]
	v_mfma_f32_32x32x16_bf16 v[146:161], v[4:7], v[12:15], v[146:161]
	ds_write_b128 v58, v[48:51] offset:20480
	ds_write_b128 v58, v[52:55] offset:25600
	v_mfma_f32_32x32x16_bf16 v[162:177], v[4:7], v[16:19], v[162:177]
	v_mfma_f32_32x32x16_bf16 v[178:193], v[4:7], v[20:23], v[178:193]
	ds_read_b128 v[4:7], v57 offset:33312
	ds_read_b128 v[8:11], v57 offset:35872
	ds_read_b128 v[12:15], v57 offset:38432
	s_waitcnt lgkmcnt(2)
	v_mfma_f32_32x32x16_bf16 v[66:81], v[24:27], v[0:3], v[66:81]
	global_load_dwordx4 v[32:35], v[240:241], off offset:2304
	global_load_dwordx4 v[36:39], v[242:243], off offset:2304
	v_mfma_f32_32x32x16_bf16 v[82:97], v[24:27], v[4:7], v[82:97]
	s_waitcnt lgkmcnt(0)
	v_mfma_f32_32x32x16_bf16 v[98:113], v[24:27], v[8:11], v[98:113]
	global_load_dwordx4 v[40:43], v[244:245], off offset:256
	global_load_dwordx4 v[44:47], v[246:247], off offset:256
	v_mfma_f32_32x32x16_bf16 v[114:129], v[24:27], v[12:15], v[114:129]
	v_mfma_f32_32x32x16_bf16 v[130:145], v[28:31], v[0:3], v[130:145]
	global_load_dwordx4 v[48:51], v[248:249], off offset:256
	global_load_dwordx4 v[52:55], v[250:251], off offset:256
	v_mfma_f32_32x32x16_bf16 v[146:161], v[28:31], v[4:7], v[146:161]
	v_mfma_f32_32x32x16_bf16 v[162:177], v[28:31], v[8:11], v[162:177]
	v_mfma_f32_32x32x16_bf16 v[178:193], v[28:31], v[12:15], v[178:193]
	s_waitcnt lgkmcnt(0)
	s_barrier
; #define G_LOAD(S, kt_) do { G_LD1(S##a0, S##b0, 0, kt_); G_LD1(S##a1, S##b1, 1, kt_); G_LD1(S##a2, S##b2, 2, kt_); G_LD1(S##a3, S##b3, 3, kt_); } while (0)
; #define G_STORE(S, buf_) do { G_ST1(S##a0, S##b0, 0, buf_); G_ST1(S##a1, S##b1, 1, buf_); G_ST1(S##a2, S##b2, 2, buf_); G_ST1(S##a3, S##b3, 3, buf_); } while (0)
; template <class AL, class BL>
; DI void gemm_core(AL al, BL bl, int m0, int n0, int K, char* smem, f32x16 (&acc)[2][2]) {
;     ...
;   G_LOAD(x, 0);
;   G_STORE(x, 0);
;   G_LOAD(x, 1);
;   G_LOAD(y, (nk > 2) ? 2 : 1);
;   __syncthreads();
;   for (int kt = 0; kt < nk; kt += 2) {
;     G_TILE(0, x, true, (kt + 3 < nk), kt + 3);
;     __syncthreads();
;     G_TILE(1, y, (kt + 2 < nk), (kt + 4 < nk), kt + 4);
;     __syncthreads();
;   }
	ds_read_b128 v[0:3], v56 offset:0
	ds_read_b128 v[4:7], v56 offset:2560
	ds_read_b128 v[8:11], v57 offset:0
	ds_read_b128 v[12:15], v57 offset:2560
	ds_read_b128 v[16:19], v57 offset:5120
	ds_read_b128 v[20:23], v57 offset:7680
	ds_read_b128 v[24:27], v56 offset:32
	ds_read_b128 v[28:31], v56 offset:2592
	s_waitcnt lgkmcnt(4)
	v_mfma_f32_32x32x16_bf16 v[66:81], v[0:3], v[8:11], v[66:81]
	v_mfma_f32_32x32x16_bf16 v[82:97], v[0:3], v[12:15], v[82:97]
	s_waitcnt vmcnt(6)
	ds_write_b128 v58, v[214:217] offset:30720
	ds_write_b128 v58, v[218:221] offset:35840
	s_waitcnt lgkmcnt(4)
	v_mfma_f32_32x32x16_bf16 v[98:113], v[0:3], v[16:19], v[98:113]
	v_mfma_f32_32x32x16_bf16 v[114:129], v[0:3], v[20:23], v[114:129]
	ds_read_b128 v[0:3], v57 offset:32
	ds_write_b128 v58, v[222:225] offset:40960
	ds_write_b128 v58, v[228:231] offset:46080
	v_mfma_f32_32x32x16_bf16 v[130:145], v[4:7], v[8:11], v[130:145]
	v_mfma_f32_32x32x16_bf16 v[146:161], v[4:7], v[12:15], v[146:161]
	ds_write_b128 v58, v[232:235] offset:51200
	ds_write_b128 v58, v[236:239] offset:56320
	v_mfma_f32_32x32x16_bf16 v[162:177], v[4:7], v[16:19], v[162:177]
	v_mfma_f32_32x32x16_bf16 v[178:193], v[4:7], v[20:23], v[178:193]
	ds_read_b128 v[4:7], v57 offset:2592
	ds_read_b128 v[8:11], v57 offset:5152
	ds_read_b128 v[12:15], v57 offset:7712
	s_waitcnt lgkmcnt(2)
	v_mfma_f32_32x32x16_bf16 v[66:81], v[24:27], v[0:3], v[66:81]
	global_load_dwordx4 v[214:217], v[240:241], off offset:2368
	global_load_dwordx4 v[218:221], v[242:243], off offset:2368
	v_mfma_f32_32x32x16_bf16 v[82:97], v[24:27], v[4:7], v[82:97]
	s_waitcnt lgkmcnt(0)
	v_mfma_f32_32x32x16_bf16 v[98:113], v[24:27], v[8:11], v[98:113]
	global_load_dwordx4 v[222:225], v[244:245], off offset:320
	global_load_dwordx4 v[228:231], v[246:247], off offset:320
	v_mfma_f32_32x32x16_bf16 v[114:129], v[24:27], v[12:15], v[114:129]
	v_mfma_f32_32x32x16_bf16 v[130:145], v[28:31], v[0:3], v[130:145]
	global_load_dwordx4 v[232:235], v[248:249], off offset:320
	global_load_dwordx4 v[236:239], v[250:251], off offset:320
	v_mfma_f32_32x32x16_bf16 v[146:161], v[28:31], v[4:7], v[146:161]
	v_mfma_f32_32x32x16_bf16 v[162:177], v[28:31], v[8:11], v[162:177]
	v_mfma_f32_32x32x16_bf16 v[178:193], v[28:31], v[12:15], v[178:193]
	s_waitcnt lgkmcnt(0)
	s_barrier
	ds_read_b128 v[0:3], v56 offset:30720
	ds_read_b128 v[4:7], v56 offset:33280
	ds_read_b128 v[8:11], v57 offset:30720
	ds_read_b128 v[12:15], v57 offset:33280
	ds_read_b128 v[16:19], v57 offset:35840
	ds_read_b128 v[20:23], v57 offset:38400
	ds_read_b128 v[24:27], v56 offset:30752
	ds_read_b128 v[28:31], v56 offset:33312
	s_waitcnt lgkmcnt(4)
	v_mfma_f32_32x32x16_bf16 v[66:81], v[0:3], v[8:11], v[66:81]
	v_mfma_f32_32x32x16_bf16 v[82:97], v[0:3], v[12:15], v[82:97]
	s_waitcnt vmcnt(6)
	ds_write_b128 v58, v[32:35] offset:0
	ds_write_b128 v58, v[36:39] offset:5120
	s_waitcnt lgkmcnt(4)
	v_mfma_f32_32x32x16_bf16 v[98:113], v[0:3], v[16:19], v[98:113]
	v_mfma_f32_32x32x16_bf16 v[114:129], v[0:3], v[20:23], v[114:129]
	ds_read_b128 v[0:3], v57 offset:30752
	ds_write_b128 v58, v[40:43] offset:10240
	ds_write_b128 v58, v[44:47] offset:15360
	v_mfma_f32_32x32x16_bf16 v[130:145], v[4:7], v[8:11], v[130:145]
	v_mfma_f32_32x32x16_bf16 v[146:161], v[4:7], v[12:15], v[146:161]
	ds_write_b128 v58, v[48:51] offset:20480
	ds_write_b128 v58, v[52:55] offset:25600
	v_mfma_f32_32x32x16_bf16 v[162:177], v[4:7], v[16:19], v[162:177]
	v_mfma_f32_32x32x16_bf16 v[178:193], v[4:7], v[20:23], v[178:193]
	ds_read_b128 v[4:7], v57 offset:33312
	ds_read_b128 v[8:11], v57 offset:35872
	ds_read_b128 v[12:15], v57 offset:38432
	s_waitcnt lgkmcnt(2)
	v_mfma_f32_32x32x16_bf16 v[66:81], v[24:27], v[0:3], v[66:81]
	global_load_dwordx4 v[32:35], v[240:241], off offset:2432
	global_load_dwordx4 v[36:39], v[242:243], off offset:2432
	v_mfma_f32_32x32x16_bf16 v[82:97], v[24:27], v[4:7], v[82:97]
	s_waitcnt lgkmcnt(0)
	v_mfma_f32_32x32x16_bf16 v[98:113], v[24:27], v[8:11], v[98:113]
	global_load_dwordx4 v[40:43], v[244:245], off offset:384
	global_load_dwordx4 v[44:47], v[246:247], off offset:384
	v_mfma_f32_32x32x16_bf16 v[114:129], v[24:27], v[12:15], v[114:129]
	v_mfma_f32_32x32x16_bf16 v[130:145], v[28:31], v[0:3], v[130:145]
	global_load_dwordx4 v[48:51], v[248:249], off offset:384
	global_load_dwordx4 v[52:55], v[250:251], off offset:384
	v_mfma_f32_32x32x16_bf16 v[146:161], v[28:31], v[4:7], v[146:161]
	v_mfma_f32_32x32x16_bf16 v[162:177], v[28:31], v[8:11], v[162:177]
	v_mfma_f32_32x32x16_bf16 v[178:193], v[28:31], v[12:15], v[178:193]
	s_waitcnt lgkmcnt(0)
	s_barrier
; #define G_LOAD(S, kt_) do { G_LD1(S##a0, S##b0, 0, kt_); G_LD1(S##a1, S##b1, 1, kt_); G_LD1(S##a2, S##b2, 2, kt_); G_LD1(S##a3, S##b3, 3, kt_); } while (0)
; #define G_STORE(S, buf_) do { G_ST1(S##a0, S##b0, 0, buf_); G_ST1(S##a1, S##b1, 1, buf_); G_ST1(S##a2, S##b2, 2, buf_); G_ST1(S##a3, S##b3, 3, buf_); } while (0)
; template <class AL, class BL>
; DI void gemm_core(AL al, BL bl, int m0, int n0, int K, char* smem, f32x16 (&acc)[2][2]) {
;     ...
;   G_LOAD(x, 0);
;   G_STORE(x, 0);
;   G_LOAD(x, 1);
;   G_LOAD(y, (nk > 2) ? 2 : 1);
;   __syncthreads();
;   for (int kt = 0; kt < nk; kt += 2) {
;     G_TILE(0, x, true, (kt + 3 < nk), kt + 3);
;     __syncthreads();
;     G_TILE(1, y, (kt + 2 < nk), (kt + 4 < nk), kt + 4);
;     __syncthreads();
;   }
	ds_read_b128 v[0:3], v56 offset:0
	ds_read_b128 v[4:7], v56 offset:2560
	ds_read_b128 v[8:11], v57 offset:0
	ds_read_b128 v[12:15], v57 offset:2560
	ds_read_b128 v[16:19], v57 offset:5120
	ds_read_b128 v[20:23], v57 offset:7680
	ds_read_b128 v[24:27], v56 offset:32
	ds_read_b128 v[28:31], v56 offset:2592
	s_waitcnt lgkmcnt(4)
	v_mfma_f32_32x32x16_bf16 v[66:81], v[0:3], v[8:11], v[66:81]
	v_mfma_f32_32x32x16_bf16 v[82:97], v[0:3], v[12:15], v[82:97]
	s_waitcnt vmcnt(6)
	ds_write_b128 v58, v[214:217] offset:30720
	ds_write_b128 v58, v[218:221] offset:35840
	s_waitcnt lgkmcnt(4)
	v_mfma_f32_32x32x16_bf16 v[98:113], v[0:3], v[16:19], v[98:113]
	v_mfma_f32_32x32x16_bf16 v[114:129], v[0:3], v[20:23], v[114:129]
	ds_read_b128 v[0:3], v57 offset:32
	ds_write_b128 v58, v[222:225] offset:40960
	ds_write_b128 v58, v[228:231] offset:46080
	v_mfma_f32_32x32x16_bf16 v[130:145], v[4:7], v[8:11], v[130:145]
	v_mfma_f32_32x32x16_bf16 v[146:161], v[4:7], v[12:15], v[146:161]
	ds_write_b128 v58, v[232:235] offset:51200
	ds_write_b128 v58, v[236:239] offset:56320
	v_mfma_f32_32x32x16_bf16 v[162:177], v[4:7], v[16:19], v[162:177]
	v_mfma_f32_32x32x16_bf16 v[178:193], v[4:7], v[20:23], v[178:193]
	ds_read_b128 v[4:7], v57 offset:2592
	ds_read_b128 v[8:11], v57 offset:5152
	ds_read_b128 v[12:15], v57 offset:7712
	s_waitcnt lgkmcnt(2)
	v_mfma_f32_32x32x16_bf16 v[66:81], v[24:27], v[0:3], v[66:81]
	global_load_dwordx4 v[214:217], v[240:241], off offset:2496
	global_load_dwordx4 v[218:221], v[242:243], off offset:2496
	v_mfma_f32_32x32x16_bf16 v[82:97], v[24:27], v[4:7], v[82:97]
	s_waitcnt lgkmcnt(0)
	v_mfma_f32_32x32x16_bf16 v[98:113], v[24:27], v[8:11], v[98:113]
	global_load_dwordx4 v[222:225], v[244:245], off offset:448
	global_load_dwordx4 v[228:231], v[246:247], off offset:448
	v_mfma_f32_32x32x16_bf16 v[114:129], v[24:27], v[12:15], v[114:129]
	v_mfma_f32_32x32x16_bf16 v[130:145], v[28:31], v[0:3], v[130:145]
	global_load_dwordx4 v[232:235], v[248:249], off offset:448
	global_load_dwordx4 v[236:239], v[250:251], off offset:448
	v_mfma_f32_32x32x16_bf16 v[146:161], v[28:31], v[4:7], v[146:161]
	v_mfma_f32_32x32x16_bf16 v[162:177], v[28:31], v[8:11], v[162:177]
	v_mfma_f32_32x32x16_bf16 v[178:193], v[28:31], v[12:15], v[178:193]
	s_waitcnt lgkmcnt(0)
	s_barrier
	ds_read_b128 v[0:3], v56 offset:30720
	ds_read_b128 v[4:7], v56 offset:33280
	ds_read_b128 v[8:11], v57 offset:30720
	ds_read_b128 v[12:15], v57 offset:33280
	ds_read_b128 v[16:19], v57 offset:35840
	ds_read_b128 v[20:23], v57 offset:38400
	ds_read_b128 v[24:27], v56 offset:30752
	ds_read_b128 v[28:31], v56 offset:33312
	s_waitcnt lgkmcnt(4)
	v_mfma_f32_32x32x16_bf16 v[66:81], v[0:3], v[8:11], v[66:81]
	v_mfma_f32_32x32x16_bf16 v[82:97], v[0:3], v[12:15], v[82:97]
	s_waitcnt vmcnt(6)
	ds_write_b128 v58, v[32:35] offset:0
	ds_write_b128 v58, v[36:39] offset:5120
	s_waitcnt lgkmcnt(4)
	v_mfma_f32_32x32x16_bf16 v[98:113], v[0:3], v[16:19], v[98:113]
	v_mfma_f32_32x32x16_bf16 v[114:129], v[0:3], v[20:23], v[114:129]
	ds_read_b128 v[0:3], v57 offset:30752
	ds_write_b128 v58, v[40:43] offset:10240
	ds_write_b128 v58, v[44:47] offset:15360
	v_mfma_f32_32x32x16_bf16 v[130:145], v[4:7], v[8:11], v[130:145]
	v_mfma_f32_32x32x16_bf16 v[146:161], v[4:7], v[12:15], v[146:161]
	ds_write_b128 v58, v[48:51] offset:20480
	ds_write_b128 v58, v[52:55] offset:25600
	v_mfma_f32_32x32x16_bf16 v[162:177], v[4:7], v[16:19], v[162:177]
	v_mfma_f32_32x32x16_bf16 v[178:193], v[4:7], v[20:23], v[178:193]
	ds_read_b128 v[4:7], v57 offset:33312
	ds_read_b128 v[8:11], v57 offset:35872
	ds_read_b128 v[12:15], v57 offset:38432
	s_waitcnt lgkmcnt(2)
	v_mfma_f32_32x32x16_bf16 v[66:81], v[24:27], v[0:3], v[66:81]
	global_load_dwordx4 v[32:35], v[240:241], off offset:2560
	global_load_dwordx4 v[36:39], v[242:243], off offset:2560
	v_mfma_f32_32x32x16_bf16 v[82:97], v[24:27], v[4:7], v[82:97]
	s_waitcnt lgkmcnt(0)
	v_mfma_f32_32x32x16_bf16 v[98:113], v[24:27], v[8:11], v[98:113]
	global_load_dwordx4 v[40:43], v[244:245], off offset:512
	global_load_dwordx4 v[44:47], v[246:247], off offset:512
	v_mfma_f32_32x32x16_bf16 v[114:129], v[24:27], v[12:15], v[114:129]
	v_mfma_f32_32x32x16_bf16 v[130:145], v[28:31], v[0:3], v[130:145]
	global_load_dwordx4 v[48:51], v[248:249], off offset:512
	global_load_dwordx4 v[52:55], v[250:251], off offset:512
	v_mfma_f32_32x32x16_bf16 v[146:161], v[28:31], v[4:7], v[146:161]
	v_mfma_f32_32x32x16_bf16 v[162:177], v[28:31], v[8:11], v[162:177]
	v_mfma_f32_32x32x16_bf16 v[178:193], v[28:31], v[12:15], v[178:193]
	s_waitcnt lgkmcnt(0)
	s_barrier
; #define G_LOAD(S, kt_) do { G_LD1(S##a0, S##b0, 0, kt_); G_LD1(S##a1, S##b1, 1, kt_); G_LD1(S##a2, S##b2, 2, kt_); G_LD1(S##a3, S##b3, 3, kt_); } while (0)
; #define G_STORE(S, buf_) do { G_ST1(S##a0, S##b0, 0, buf_); G_ST1(S##a1, S##b1, 1, buf_); G_ST1(S##a2, S##b2, 2, buf_); G_ST1(S##a3, S##b3, 3, buf_); } while (0)
; template <class AL, class BL>
; DI void gemm_core(AL al, BL bl, int m0, int n0, int K, char* smem, f32x16 (&acc)[2][2]) {
;     ...
;   G_LOAD(x, 0);
;   G_STORE(x, 0);
;   G_LOAD(x, 1);
;   G_LOAD(y, (nk > 2) ? 2 : 1);
;   __syncthreads();
;   for (int kt = 0; kt < nk; kt += 2) {
;     G_TILE(0, x, true, (kt + 3 < nk), kt + 3);
;     __syncthreads();
;     G_TILE(1, y, (kt + 2 < nk), (kt + 4 < nk), kt + 4);
;     __syncthreads();
	ds_read_b128 v[0:3], v56 offset:0
	ds_read_b128 v[4:7], v56 offset:2560
	ds_read_b128 v[8:11], v57 offset:0
	ds_read_b128 v[12:15], v57 offset:2560
	ds_read_b128 v[16:19], v57 offset:5120
	ds_read_b128 v[20:23], v57 offset:7680
	ds_read_b128 v[24:27], v56 offset:32
	ds_read_b128 v[28:31], v56 offset:2592
	s_waitcnt lgkmcnt(4)
	v_mfma_f32_32x32x16_bf16 v[66:81], v[0:3], v[8:11], v[66:81]
	v_mfma_f32_32x32x16_bf16 v[82:97], v[0:3], v[12:15], v[82:97]
	s_waitcnt vmcnt(6)
	ds_write_b128 v58, v[214:217] offset:30720
	ds_write_b128 v58, v[218:221] offset:35840
	s_waitcnt lgkmcnt(4)
	v_mfma_f32_32x32x16_bf16 v[98:113], v[0:3], v[16:19], v[98:113]
	v_mfma_f32_32x32x16_bf16 v[114:129], v[0:3], v[20:23], v[114:129]
	ds_read_b128 v[0:3], v57 offset:32
	ds_write_b128 v58, v[222:225] offset:40960
	ds_write_b128 v58, v[228:231] offset:46080
	v_mfma_f32_32x32x16_bf16 v[130:145], v[4:7], v[8:11], v[130:145]
	v_mfma_f32_32x32x16_bf16 v[146:161], v[4:7], v[12:15], v[146:161]
	ds_write_b128 v58, v[232:235] offset:51200
	ds_write_b128 v58, v[236:239] offset:56320
	v_mfma_f32_32x32x16_bf16 v[162:177], v[4:7], v[16:19], v[162:177]
	v_mfma_f32_32x32x16_bf16 v[178:193], v[4:7], v[20:23], v[178:193]
	ds_read_b128 v[4:7], v57 offset:2592
	ds_read_b128 v[8:11], v57 offset:5152
	ds_read_b128 v[12:15], v57 offset:7712
	s_waitcnt lgkmcnt(2)
	v_mfma_f32_32x32x16_bf16 v[66:81], v[24:27], v[0:3], v[66:81]
	global_load_dwordx4 v[214:217], v[240:241], off offset:2624
	global_load_dwordx4 v[218:221], v[242:243], off offset:2624
	v_mfma_f32_32x32x16_bf16 v[82:97], v[24:27], v[4:7], v[82:97]
	s_waitcnt lgkmcnt(0)
	v_mfma_f32_32x32x16_bf16 v[98:113], v[24:27], v[8:11], v[98:113]
	global_load_dwordx4 v[222:225], v[244:245], off offset:576
	global_load_dwordx4 v[228:231], v[246:247], off offset:576
	v_mfma_f32_32x32x16_bf16 v[114:129], v[24:27], v[12:15], v[114:129]
	v_mfma_f32_32x32x16_bf16 v[130:145], v[28:31], v[0:3], v[130:145]
	global_load_dwordx4 v[232:235], v[248:249], off offset:576
	global_load_dwordx4 v[236:239], v[250:251], off offset:576
	v_mfma_f32_32x32x16_bf16 v[146:161], v[28:31], v[4:7], v[146:161]
	v_mfma_f32_32x32x16_bf16 v[162:177], v[28:31], v[8:11], v[162:177]
	v_mfma_f32_32x32x16_bf16 v[178:193], v[28:31], v[12:15], v[178:193]
	s_waitcnt lgkmcnt(0)
	s_barrier
	ds_read_b128 v[0:3], v56 offset:30720
	ds_read_b128 v[4:7], v56 offset:33280
	ds_read_b128 v[8:11], v57 offset:30720
	ds_read_b128 v[12:15], v57 offset:33280
	ds_read_b128 v[16:19], v57 offset:35840
	ds_read_b128 v[20:23], v57 offset:38400
	ds_read_b128 v[24:27], v56 offset:30752
	ds_read_b128 v[28:31], v56 offset:33312
	s_waitcnt lgkmcnt(4)
	v_mfma_f32_32x32x16_bf16 v[66:81], v[0:3], v[8:11], v[66:81]
	v_mfma_f32_32x32x16_bf16 v[82:97], v[0:3], v[12:15], v[82:97]
	s_waitcnt vmcnt(6)
	ds_write_b128 v58, v[32:35] offset:0
	ds_write_b128 v58, v[36:39] offset:5120
	s_waitcnt lgkmcnt(4)
	v_mfma_f32_32x32x16_bf16 v[98:113], v[0:3], v[16:19], v[98:113]
	v_mfma_f32_32x32x16_bf16 v[114:129], v[0:3], v[20:23], v[114:129]
	ds_read_b128 v[0:3], v57 offset:30752
	ds_write_b128 v58, v[40:43] offset:10240
	ds_write_b128 v58, v[44:47] offset:15360
	v_mfma_f32_32x32x16_bf16 v[130:145], v[4:7], v[8:11], v[130:145]
	v_mfma_f32_32x32x16_bf16 v[146:161], v[4:7], v[12:15], v[146:161]
	ds_write_b128 v58, v[48:51] offset:20480
	ds_write_b128 v58, v[52:55] offset:25600
	v_mfma_f32_32x32x16_bf16 v[162:177], v[4:7], v[16:19], v[162:177]
	v_mfma_f32_32x32x16_bf16 v[178:193], v[4:7], v[20:23], v[178:193]
	ds_read_b128 v[4:7], v57 offset:33312
	ds_read_b128 v[8:11], v57 offset:35872
	ds_read_b128 v[12:15], v57 offset:38432
	s_waitcnt lgkmcnt(2)
	v_mfma_f32_32x32x16_bf16 v[66:81], v[24:27], v[0:3], v[66:81]
	global_load_dwordx4 v[32:35], v[240:241], off offset:2688
	global_load_dwordx4 v[36:39], v[242:243], off offset:2688
	v_mfma_f32_32x32x16_bf16 v[82:97], v[24:27], v[4:7], v[82:97]
	s_waitcnt lgkmcnt(0)
	v_mfma_f32_32x32x16_bf16 v[98:113], v[24:27], v[8:11], v[98:113]
	global_load_dwordx4 v[40:43], v[244:245], off offset:640
	global_load_dwordx4 v[44:47], v[246:247], off offset:640
	v_mfma_f32_32x32x16_bf16 v[114:129], v[24:27], v[12:15], v[114:129]
	v_mfma_f32_32x32x16_bf16 v[130:145], v[28:31], v[0:3], v[130:145]
	global_load_dwordx4 v[48:51], v[248:249], off offset:640
	global_load_dwordx4 v[52:55], v[250:251], off offset:640
	v_mfma_f32_32x32x16_bf16 v[146:161], v[28:31], v[4:7], v[146:161]
	v_mfma_f32_32x32x16_bf16 v[162:177], v[28:31], v[8:11], v[162:177]
	v_mfma_f32_32x32x16_bf16 v[178:193], v[28:31], v[12:15], v[178:193]
	s_waitcnt lgkmcnt(0)
	s_barrier
; #define G_LOAD(S, kt_) do { G_LD1(S##a0, S##b0, 0, kt_); G_LD1(S##a1, S##b1, 1, kt_); G_LD1(S##a2, S##b2, 2, kt_); G_LD1(S##a3, S##b3, 3, kt_); } while (0)
; #define G_STORE(S, buf_) do { G_ST1(S##a0, S##b0, 0, buf_); G_ST1(S##a1, S##b1, 1, buf_); G_ST1(S##a2, S##b2, 2, buf_); G_ST1(S##a3, S##b3, 3, buf_); } while (0)
; template <class AL, class BL>
; DI void gemm_core(AL al, BL bl, int m0, int n0, int K, char* smem, f32x16 (&acc)[2][2]) {
;     ...
;   G_LOAD(x, 0);
;   G_STORE(x, 0);
;   G_LOAD(x, 1);
;   G_LOAD(y, (nk > 2) ? 2 : 1);
;   __syncthreads();
;   for (int kt = 0; kt < nk; kt += 2) {
;     G_TILE(0, x, true, (kt + 3 < nk), kt + 3);
;     __syncthreads();
;     G_TILE(1, y, (kt + 2 < nk), (kt + 4 < nk), kt + 4);
;     __syncthreads();
	ds_read_b128 v[0:3], v56 offset:0
	ds_read_b128 v[4:7], v56 offset:2560
	ds_read_b128 v[8:11], v57 offset:0
	ds_read_b128 v[12:15], v57 offset:2560
	ds_read_b128 v[16:19], v57 offset:5120
	ds_read_b128 v[20:23], v57 offset:7680
	ds_read_b128 v[24:27], v56 offset:32
	ds_read_b128 v[28:31], v56 offset:2592
	s_waitcnt lgkmcnt(4)
	v_mfma_f32_32x32x16_bf16 v[66:81], v[0:3], v[8:11], v[66:81]
	v_mfma_f32_32x32x16_bf16 v[82:97], v[0:3], v[12:15], v[82:97]
	s_waitcnt vmcnt(6)
	ds_write_b128 v58, v[214:217] offset:30720
	ds_write_b128 v58, v[218:221] offset:35840
	s_waitcnt lgkmcnt(4)
	v_mfma_f32_32x32x16_bf16 v[98:113], v[0:3], v[16:19], v[98:113]
	v_mfma_f32_32x32x16_bf16 v[114:129], v[0:3], v[20:23], v[114:129]
	ds_read_b128 v[0:3], v57 offset:32
	ds_write_b128 v58, v[222:225] offset:40960
	ds_write_b128 v58, v[228:231] offset:46080
	v_mfma_f32_32x32x16_bf16 v[130:145], v[4:7], v[8:11], v[130:145]
	v_mfma_f32_32x32x16_bf16 v[146:161], v[4:7], v[12:15], v[146:161]
	ds_write_b128 v58, v[232:235] offset:51200
	ds_write_b128 v58, v[236:239] offset:56320
	v_mfma_f32_32x32x16_bf16 v[162:177], v[4:7], v[16:19], v[162:177]
	v_mfma_f32_32x32x16_bf16 v[178:193], v[4:7], v[20:23], v[178:193]
	ds_read_b128 v[4:7], v57 offset:2592
	ds_read_b128 v[8:11], v57 offset:5152
	ds_read_b128 v[12:15], v57 offset:7712
	s_waitcnt lgkmcnt(2)
	v_mfma_f32_32x32x16_bf16 v[66:81], v[24:27], v[0:3], v[66:81]
	global_load_dwordx4 v[214:217], v[240:241], off offset:2752
	global_load_dwordx4 v[218:221], v[242:243], off offset:2752
	v_mfma_f32_32x32x16_bf16 v[82:97], v[24:27], v[4:7], v[82:97]
	s_waitcnt lgkmcnt(0)
	v_mfma_f32_32x32x16_bf16 v[98:113], v[24:27], v[8:11], v[98:113]
	global_load_dwordx4 v[222:225], v[244:245], off offset:704
	global_load_dwordx4 v[228:231], v[246:247], off offset:704
	v_mfma_f32_32x32x16_bf16 v[114:129], v[24:27], v[12:15], v[114:129]
	v_mfma_f32_32x32x16_bf16 v[130:145], v[28:31], v[0:3], v[130:145]
	global_load_dwordx4 v[232:235], v[248:249], off offset:704
	global_load_dwordx4 v[236:239], v[250:251], off offset:704
	v_mfma_f32_32x32x16_bf16 v[146:161], v[28:31], v[4:7], v[146:161]
	v_mfma_f32_32x32x16_bf16 v[162:177], v[28:31], v[8:11], v[162:177]
	v_mfma_f32_32x32x16_bf16 v[178:193], v[28:31], v[12:15], v[178:193]
	s_waitcnt lgkmcnt(0)
	s_barrier
	ds_read_b128 v[0:3], v56 offset:30720
	ds_read_b128 v[4:7], v56 offset:33280
	ds_read_b128 v[8:11], v57 offset:30720
	ds_read_b128 v[12:15], v57 offset:33280
	ds_read_b128 v[16:19], v57 offset:35840
	ds_read_b128 v[20:23], v57 offset:38400
	ds_read_b128 v[24:27], v56 offset:30752
	ds_read_b128 v[28:31], v56 offset:33312
	s_waitcnt lgkmcnt(4)
	v_mfma_f32_32x32x16_bf16 v[66:81], v[0:3], v[8:11], v[66:81]
	v_mfma_f32_32x32x16_bf16 v[82:97], v[0:3], v[12:15], v[82:97]
	s_waitcnt vmcnt(6)
	ds_write_b128 v58, v[32:35] offset:0
	ds_write_b128 v58, v[36:39] offset:5120
	s_waitcnt lgkmcnt(4)
	v_mfma_f32_32x32x16_bf16 v[98:113], v[0:3], v[16:19], v[98:113]
	v_mfma_f32_32x32x16_bf16 v[114:129], v[0:3], v[20:23], v[114:129]
	ds_read_b128 v[0:3], v57 offset:30752
	ds_write_b128 v58, v[40:43] offset:10240
	ds_write_b128 v58, v[44:47] offset:15360
	v_mfma_f32_32x32x16_bf16 v[130:145], v[4:7], v[8:11], v[130:145]
	v_mfma_f32_32x32x16_bf16 v[146:161], v[4:7], v[12:15], v[146:161]
	ds_write_b128 v58, v[48:51] offset:20480
	ds_write_b128 v58, v[52:55] offset:25600
	v_mfma_f32_32x32x16_bf16 v[162:177], v[4:7], v[16:19], v[162:177]
	v_mfma_f32_32x32x16_bf16 v[178:193], v[4:7], v[20:23], v[178:193]
	ds_read_b128 v[4:7], v57 offset:33312
	ds_read_b128 v[8:11], v57 offset:35872
	ds_read_b128 v[12:15], v57 offset:38432
	s_waitcnt lgkmcnt(2)
	v_mfma_f32_32x32x16_bf16 v[66:81], v[24:27], v[0:3], v[66:81]
	global_load_dwordx4 v[32:35], v[240:241], off offset:2816
	global_load_dwordx4 v[36:39], v[242:243], off offset:2816
	v_mfma_f32_32x32x16_bf16 v[82:97], v[24:27], v[4:7], v[82:97]
	s_waitcnt lgkmcnt(0)
	v_mfma_f32_32x32x16_bf16 v[98:113], v[24:27], v[8:11], v[98:113]
	global_load_dwordx4 v[40:43], v[244:245], off offset:768
	global_load_dwordx4 v[44:47], v[246:247], off offset:768
	v_mfma_f32_32x32x16_bf16 v[114:129], v[24:27], v[12:15], v[114:129]
	v_mfma_f32_32x32x16_bf16 v[130:145], v[28:31], v[0:3], v[130:145]
	global_load_dwordx4 v[48:51], v[248:249], off offset:768
	global_load_dwordx4 v[52:55], v[250:251], off offset:768
	v_mfma_f32_32x32x16_bf16 v[146:161], v[28:31], v[4:7], v[146:161]
	v_mfma_f32_32x32x16_bf16 v[162:177], v[28:31], v[8:11], v[162:177]
	v_mfma_f32_32x32x16_bf16 v[178:193], v[28:31], v[12:15], v[178:193]
	s_waitcnt lgkmcnt(0)
	s_barrier
; #define G_LOAD(S, kt_) do { G_LD1(S##a0, S##b0, 0, kt_); G_LD1(S##a1, S##b1, 1, kt_); G_LD1(S##a2, S##b2, 2, kt_); G_LD1(S##a3, S##b3, 3, kt_); } while (0)
; #define G_STORE(S, buf_) do { G_ST1(S##a0, S##b0, 0, buf_); G_ST1(S##a1, S##b1, 1, buf_); G_ST1(S##a2, S##b2, 2, buf_); G_ST1(S##a3, S##b3, 3, buf_); } while (0)
; template <class AL, class BL>
; DI void gemm_core(AL al, BL bl, int m0, int n0, int K, char* smem, f32x16 (&acc)[2][2]) {
;     ...
;   G_LOAD(x, 0);
;   G_STORE(x, 0);
;   G_LOAD(x, 1);
;   G_LOAD(y, (nk > 2) ? 2 : 1);
;   __syncthreads();
;   for (int kt = 0; kt < nk; kt += 2) {
;     G_TILE(0, x, true, (kt + 3 < nk), kt + 3);
;     __syncthreads();
;     G_TILE(1, y, (kt + 2 < nk), (kt + 4 < nk), kt + 4);
;     __syncthreads();
	ds_read_b128 v[0:3], v56 offset:0
	ds_read_b128 v[4:7], v56 offset:2560
	ds_read_b128 v[8:11], v57 offset:0
	ds_read_b128 v[12:15], v57 offset:2560
	ds_read_b128 v[16:19], v57 offset:5120
	ds_read_b128 v[20:23], v57 offset:7680
	ds_read_b128 v[24:27], v56 offset:32
	ds_read_b128 v[28:31], v56 offset:2592
	s_waitcnt lgkmcnt(4)
	v_mfma_f32_32x32x16_bf16 v[66:81], v[0:3], v[8:11], v[66:81]
	v_mfma_f32_32x32x16_bf16 v[82:97], v[0:3], v[12:15], v[82:97]
	s_waitcnt vmcnt(6)
	ds_write_b128 v58, v[214:217] offset:30720
	ds_write_b128 v58, v[218:221] offset:35840
	s_waitcnt lgkmcnt(4)
	v_mfma_f32_32x32x16_bf16 v[98:113], v[0:3], v[16:19], v[98:113]
	v_mfma_f32_32x32x16_bf16 v[114:129], v[0:3], v[20:23], v[114:129]
	ds_read_b128 v[0:3], v57 offset:32
	ds_write_b128 v58, v[222:225] offset:40960
	ds_write_b128 v58, v[228:231] offset:46080
	v_mfma_f32_32x32x16_bf16 v[130:145], v[4:7], v[8:11], v[130:145]
	v_mfma_f32_32x32x16_bf16 v[146:161], v[4:7], v[12:15], v[146:161]
	ds_write_b128 v58, v[232:235] offset:51200
	ds_write_b128 v58, v[236:239] offset:56320
	v_mfma_f32_32x32x16_bf16 v[162:177], v[4:7], v[16:19], v[162:177]
	v_mfma_f32_32x32x16_bf16 v[178:193], v[4:7], v[20:23], v[178:193]
	ds_read_b128 v[4:7], v57 offset:2592
	ds_read_b128 v[8:11], v57 offset:5152
	ds_read_b128 v[12:15], v57 offset:7712
	s_waitcnt lgkmcnt(2)
	v_mfma_f32_32x32x16_bf16 v[66:81], v[24:27], v[0:3], v[66:81]
	global_load_dwordx4 v[214:217], v[240:241], off offset:2880
	global_load_dwordx4 v[218:221], v[242:243], off offset:2880
	v_mfma_f32_32x32x16_bf16 v[82:97], v[24:27], v[4:7], v[82:97]
	s_waitcnt lgkmcnt(0)
	v_mfma_f32_32x32x16_bf16 v[98:113], v[24:27], v[8:11], v[98:113]
	global_load_dwordx4 v[222:225], v[244:245], off offset:832
	global_load_dwordx4 v[228:231], v[246:247], off offset:832
	v_mfma_f32_32x32x16_bf16 v[114:129], v[24:27], v[12:15], v[114:129]
	v_mfma_f32_32x32x16_bf16 v[130:145], v[28:31], v[0:3], v[130:145]
	global_load_dwordx4 v[232:235], v[248:249], off offset:832
	global_load_dwordx4 v[236:239], v[250:251], off offset:832
	v_mfma_f32_32x32x16_bf16 v[146:161], v[28:31], v[4:7], v[146:161]
	v_mfma_f32_32x32x16_bf16 v[162:177], v[28:31], v[8:11], v[162:177]
	v_mfma_f32_32x32x16_bf16 v[178:193], v[28:31], v[12:15], v[178:193]
	s_waitcnt lgkmcnt(0)
	s_barrier
	ds_read_b128 v[0:3], v56 offset:30720
	ds_read_b128 v[4:7], v56 offset:33280
	ds_read_b128 v[8:11], v57 offset:30720
	ds_read_b128 v[12:15], v57 offset:33280
	ds_read_b128 v[16:19], v57 offset:35840
	ds_read_b128 v[20:23], v57 offset:38400
	ds_read_b128 v[24:27], v56 offset:30752
	ds_read_b128 v[28:31], v56 offset:33312
	s_waitcnt lgkmcnt(4)
	v_mfma_f32_32x32x16_bf16 v[66:81], v[0:3], v[8:11], v[66:81]
	v_mfma_f32_32x32x16_bf16 v[82:97], v[0:3], v[12:15], v[82:97]
	s_waitcnt vmcnt(6)
	ds_write_b128 v58, v[32:35] offset:0
	ds_write_b128 v58, v[36:39] offset:5120
	s_waitcnt lgkmcnt(4)
	v_mfma_f32_32x32x16_bf16 v[98:113], v[0:3], v[16:19], v[98:113]
	v_mfma_f32_32x32x16_bf16 v[114:129], v[0:3], v[20:23], v[114:129]
	ds_read_b128 v[0:3], v57 offset:30752
	ds_write_b128 v58, v[40:43] offset:10240
	ds_write_b128 v58, v[44:47] offset:15360
	v_mfma_f32_32x32x16_bf16 v[130:145], v[4:7], v[8:11], v[130:145]
	v_mfma_f32_32x32x16_bf16 v[146:161], v[4:7], v[12:15], v[146:161]
	ds_write_b128 v58, v[48:51] offset:20480
	ds_write_b128 v58, v[52:55] offset:25600
	v_mfma_f32_32x32x16_bf16 v[162:177], v[4:7], v[16:19], v[162:177]
	v_mfma_f32_32x32x16_bf16 v[178:193], v[4:7], v[20:23], v[178:193]
	ds_read_b128 v[4:7], v57 offset:33312
	ds_read_b128 v[8:11], v57 offset:35872
	ds_read_b128 v[12:15], v57 offset:38432
	s_waitcnt lgkmcnt(2)
	v_mfma_f32_32x32x16_bf16 v[66:81], v[24:27], v[0:3], v[66:81]
	global_load_dwordx4 v[32:35], v[240:241], off offset:2944
	global_load_dwordx4 v[36:39], v[242:243], off offset:2944
	v_mfma_f32_32x32x16_bf16 v[82:97], v[24:27], v[4:7], v[82:97]
	s_waitcnt lgkmcnt(0)
	v_mfma_f32_32x32x16_bf16 v[98:113], v[24:27], v[8:11], v[98:113]
	global_load_dwordx4 v[40:43], v[244:245], off offset:896
	global_load_dwordx4 v[44:47], v[246:247], off offset:896
	v_mfma_f32_32x32x16_bf16 v[114:129], v[24:27], v[12:15], v[114:129]
	v_mfma_f32_32x32x16_bf16 v[130:145], v[28:31], v[0:3], v[130:145]
	global_load_dwordx4 v[48:51], v[248:249], off offset:896
	global_load_dwordx4 v[52:55], v[250:251], off offset:896
	v_mfma_f32_32x32x16_bf16 v[146:161], v[28:31], v[4:7], v[146:161]
	v_mfma_f32_32x32x16_bf16 v[162:177], v[28:31], v[8:11], v[162:177]
	v_mfma_f32_32x32x16_bf16 v[178:193], v[28:31], v[12:15], v[178:193]
	s_waitcnt lgkmcnt(0)
	s_barrier
; #define G_LOAD(S, kt_) do { G_LD1(S##a0, S##b0, 0, kt_); G_LD1(S##a1, S##b1, 1, kt_); G_LD1(S##a2, S##b2, 2, kt_); G_LD1(S##a3, S##b3, 3, kt_); } while (0)
; #define G_STORE(S, buf_) do { G_ST1(S##a0, S##b0, 0, buf_); G_ST1(S##a1, S##b1, 1, buf_); G_ST1(S##a2, S##b2, 2, buf_); G_ST1(S##a3, S##b3, 3, buf_); } while (0)
; template <class AL, class BL>
; DI void gemm_core(AL al, BL bl, int m0, int n0, int K, char* smem, f32x16 (&acc)[2][2]) {
;     ...
;   G_LOAD(x, 0);
;   G_STORE(x, 0);
;   G_LOAD(x, 1);
;   G_LOAD(y, (nk > 2) ? 2 : 1);
;   __syncthreads();
;   for (int kt = 0; kt < nk; kt += 2) {
;     G_TILE(0, x, true, (kt + 3 < nk), kt + 3);
;     __syncthreads();
;     G_TILE(1, y, (kt + 2 < nk), (kt + 4 < nk), kt + 4);
;     __syncthreads();
	ds_read_b128 v[0:3], v56 offset:0
	ds_read_b128 v[4:7], v56 offset:2560
	ds_read_b128 v[8:11], v57 offset:0
	ds_read_b128 v[12:15], v57 offset:2560
	ds_read_b128 v[16:19], v57 offset:5120
	ds_read_b128 v[20:23], v57 offset:7680
	ds_read_b128 v[24:27], v56 offset:32
	ds_read_b128 v[28:31], v56 offset:2592
	s_waitcnt lgkmcnt(4)
	v_mfma_f32_32x32x16_bf16 v[66:81], v[0:3], v[8:11], v[66:81]
	v_mfma_f32_32x32x16_bf16 v[82:97], v[0:3], v[12:15], v[82:97]
	s_waitcnt vmcnt(6)
	ds_write_b128 v58, v[214:217] offset:30720
	ds_write_b128 v58, v[218:221] offset:35840
	s_waitcnt lgkmcnt(4)
	v_mfma_f32_32x32x16_bf16 v[98:113], v[0:3], v[16:19], v[98:113]
	v_mfma_f32_32x32x16_bf16 v[114:129], v[0:3], v[20:23], v[114:129]
	ds_read_b128 v[0:3], v57 offset:32
	ds_write_b128 v58, v[222:225] offset:40960
	ds_write_b128 v58, v[228:231] offset:46080
	v_mfma_f32_32x32x16_bf16 v[130:145], v[4:7], v[8:11], v[130:145]
	v_mfma_f32_32x32x16_bf16 v[146:161], v[4:7], v[12:15], v[146:161]
	ds_write_b128 v58, v[232:235] offset:51200
	ds_write_b128 v58, v[236:239] offset:56320
	v_mfma_f32_32x32x16_bf16 v[162:177], v[4:7], v[16:19], v[162:177]
	v_mfma_f32_32x32x16_bf16 v[178:193], v[4:7], v[20:23], v[178:193]
	ds_read_b128 v[4:7], v57 offset:2592
	ds_read_b128 v[8:11], v57 offset:5152
	ds_read_b128 v[12:15], v57 offset:7712
	s_waitcnt lgkmcnt(2)
	v_mfma_f32_32x32x16_bf16 v[66:81], v[24:27], v[0:3], v[66:81]
	global_load_dwordx4 v[214:217], v[240:241], off offset:3008
	global_load_dwordx4 v[218:221], v[242:243], off offset:3008
	v_mfma_f32_32x32x16_bf16 v[82:97], v[24:27], v[4:7], v[82:97]
	s_waitcnt lgkmcnt(0)
	v_mfma_f32_32x32x16_bf16 v[98:113], v[24:27], v[8:11], v[98:113]
	global_load_dwordx4 v[222:225], v[244:245], off offset:960
	global_load_dwordx4 v[228:231], v[246:247], off offset:960
	v_mfma_f32_32x32x16_bf16 v[114:129], v[24:27], v[12:15], v[114:129]
	v_mfma_f32_32x32x16_bf16 v[130:145], v[28:31], v[0:3], v[130:145]
	global_load_dwordx4 v[232:235], v[248:249], off offset:960
	global_load_dwordx4 v[236:239], v[250:251], off offset:960
	v_mfma_f32_32x32x16_bf16 v[146:161], v[28:31], v[4:7], v[146:161]
	v_mfma_f32_32x32x16_bf16 v[162:177], v[28:31], v[8:11], v[162:177]
	v_mfma_f32_32x32x16_bf16 v[178:193], v[28:31], v[12:15], v[178:193]
	s_waitcnt lgkmcnt(0)
	s_barrier
	ds_read_b128 v[0:3], v56 offset:30720
	ds_read_b128 v[4:7], v56 offset:33280
	ds_read_b128 v[8:11], v57 offset:30720
	ds_read_b128 v[12:15], v57 offset:33280
	ds_read_b128 v[16:19], v57 offset:35840
	ds_read_b128 v[20:23], v57 offset:38400
	ds_read_b128 v[24:27], v56 offset:30752
	ds_read_b128 v[28:31], v56 offset:33312
	s_waitcnt lgkmcnt(4)
	v_mfma_f32_32x32x16_bf16 v[66:81], v[0:3], v[8:11], v[66:81]
	v_mfma_f32_32x32x16_bf16 v[82:97], v[0:3], v[12:15], v[82:97]
	s_waitcnt vmcnt(6)
	ds_write_b128 v58, v[32:35] offset:0
	ds_write_b128 v58, v[36:39] offset:5120
	s_waitcnt lgkmcnt(4)
	v_mfma_f32_32x32x16_bf16 v[98:113], v[0:3], v[16:19], v[98:113]
	v_mfma_f32_32x32x16_bf16 v[114:129], v[0:3], v[20:23], v[114:129]
	ds_read_b128 v[0:3], v57 offset:30752
	ds_write_b128 v58, v[40:43] offset:10240
	ds_write_b128 v58, v[44:47] offset:15360
	v_mfma_f32_32x32x16_bf16 v[130:145], v[4:7], v[8:11], v[130:145]
	v_mfma_f32_32x32x16_bf16 v[146:161], v[4:7], v[12:15], v[146:161]
	ds_write_b128 v58, v[48:51] offset:20480
	ds_write_b128 v58, v[52:55] offset:25600
	v_mfma_f32_32x32x16_bf16 v[162:177], v[4:7], v[16:19], v[162:177]
	v_mfma_f32_32x32x16_bf16 v[178:193], v[4:7], v[20:23], v[178:193]
	ds_read_b128 v[4:7], v57 offset:33312
	ds_read_b128 v[8:11], v57 offset:35872
	ds_read_b128 v[12:15], v57 offset:38432
	s_waitcnt lgkmcnt(2)
	v_mfma_f32_32x32x16_bf16 v[66:81], v[24:27], v[0:3], v[66:81]
	global_load_dwordx4 v[32:35], v[240:241], off offset:3072
	global_load_dwordx4 v[36:39], v[242:243], off offset:3072
	v_mfma_f32_32x32x16_bf16 v[82:97], v[24:27], v[4:7], v[82:97]
	s_waitcnt lgkmcnt(0)
	v_mfma_f32_32x32x16_bf16 v[98:113], v[24:27], v[8:11], v[98:113]
	global_load_dwordx4 v[40:43], v[244:245], off offset:1024
	global_load_dwordx4 v[44:47], v[246:247], off offset:1024
	v_mfma_f32_32x32x16_bf16 v[114:129], v[24:27], v[12:15], v[114:129]
	v_mfma_f32_32x32x16_bf16 v[130:145], v[28:31], v[0:3], v[130:145]
	global_load_dwordx4 v[48:51], v[248:249], off offset:1024
	global_load_dwordx4 v[52:55], v[250:251], off offset:1024
	v_mfma_f32_32x32x16_bf16 v[146:161], v[28:31], v[4:7], v[146:161]
	v_mfma_f32_32x32x16_bf16 v[162:177], v[28:31], v[8:11], v[162:177]
	v_mfma_f32_32x32x16_bf16 v[178:193], v[28:31], v[12:15], v[178:193]
	s_waitcnt lgkmcnt(0)
	s_barrier
; #define G_LOAD(S, kt_) do { G_LD1(S##a0, S##b0, 0, kt_); G_LD1(S##a1, S##b1, 1, kt_); G_LD1(S##a2, S##b2, 2, kt_); G_LD1(S##a3, S##b3, 3, kt_); } while (0)
; #define G_STORE(S, buf_) do { G_ST1(S##a0, S##b0, 0, buf_); G_ST1(S##a1, S##b1, 1, buf_); G_ST1(S##a2, S##b2, 2, buf_); G_ST1(S##a3, S##b3, 3, buf_); } while (0)
; template <class AL, class BL>
; DI void gemm_core(AL al, BL bl, int m0, int n0, int K, char* smem, f32x16 (&acc)[2][2]) {
;     ...
;   G_LOAD(x, 0);
;   G_STORE(x, 0);
;   G_LOAD(x, 1);
;   G_LOAD(y, (nk > 2) ? 2 : 1);
;   __syncthreads();
;   for (int kt = 0; kt < nk; kt += 2) {
;     G_TILE(0, x, true, (kt + 3 < nk), kt + 3);
;     __syncthreads();
;     G_TILE(1, y, (kt + 2 < nk), (kt + 4 < nk), kt + 4);
;     __syncthreads();
	ds_read_b128 v[0:3], v56 offset:0
	ds_read_b128 v[4:7], v56 offset:2560
	ds_read_b128 v[8:11], v57 offset:0
	ds_read_b128 v[12:15], v57 offset:2560
	ds_read_b128 v[16:19], v57 offset:5120
	ds_read_b128 v[20:23], v57 offset:7680
	ds_read_b128 v[24:27], v56 offset:32
	ds_read_b128 v[28:31], v56 offset:2592
	s_waitcnt lgkmcnt(4)
	v_mfma_f32_32x32x16_bf16 v[66:81], v[0:3], v[8:11], v[66:81]
	v_mfma_f32_32x32x16_bf16 v[82:97], v[0:3], v[12:15], v[82:97]
	s_waitcnt vmcnt(6)
	ds_write_b128 v58, v[214:217] offset:30720
	ds_write_b128 v58, v[218:221] offset:35840
	s_waitcnt lgkmcnt(4)
	v_mfma_f32_32x32x16_bf16 v[98:113], v[0:3], v[16:19], v[98:113]
	v_mfma_f32_32x32x16_bf16 v[114:129], v[0:3], v[20:23], v[114:129]
	ds_read_b128 v[0:3], v57 offset:32
	ds_write_b128 v58, v[222:225] offset:40960
	ds_write_b128 v58, v[228:231] offset:46080
	v_mfma_f32_32x32x16_bf16 v[130:145], v[4:7], v[8:11], v[130:145]
	v_mfma_f32_32x32x16_bf16 v[146:161], v[4:7], v[12:15], v[146:161]
	ds_write_b128 v58, v[232:235] offset:51200
	ds_write_b128 v58, v[236:239] offset:56320
	v_mfma_f32_32x32x16_bf16 v[162:177], v[4:7], v[16:19], v[162:177]
	v_mfma_f32_32x32x16_bf16 v[178:193], v[4:7], v[20:23], v[178:193]
	ds_read_b128 v[4:7], v57 offset:2592
	ds_read_b128 v[8:11], v57 offset:5152
	ds_read_b128 v[12:15], v57 offset:7712
	s_waitcnt lgkmcnt(2)
	v_mfma_f32_32x32x16_bf16 v[66:81], v[24:27], v[0:3], v[66:81]
	global_load_dwordx4 v[214:217], v[240:241], off offset:3136
	global_load_dwordx4 v[218:221], v[242:243], off offset:3136
	v_mfma_f32_32x32x16_bf16 v[82:97], v[24:27], v[4:7], v[82:97]
	s_waitcnt lgkmcnt(0)
	v_mfma_f32_32x32x16_bf16 v[98:113], v[24:27], v[8:11], v[98:113]
	global_load_dwordx4 v[222:225], v[244:245], off offset:1088
	global_load_dwordx4 v[228:231], v[246:247], off offset:1088
	v_mfma_f32_32x32x16_bf16 v[114:129], v[24:27], v[12:15], v[114:129]
	v_mfma_f32_32x32x16_bf16 v[130:145], v[28:31], v[0:3], v[130:145]
	global_load_dwordx4 v[232:235], v[248:249], off offset:1088
	global_load_dwordx4 v[236:239], v[250:251], off offset:1088
	v_mfma_f32_32x32x16_bf16 v[146:161], v[28:31], v[4:7], v[146:161]
	v_mfma_f32_32x32x16_bf16 v[162:177], v[28:31], v[8:11], v[162:177]
	v_mfma_f32_32x32x16_bf16 v[178:193], v[28:31], v[12:15], v[178:193]
	s_waitcnt lgkmcnt(0)
	s_barrier
	ds_read_b128 v[0:3], v56 offset:30720
	ds_read_b128 v[4:7], v56 offset:33280
	ds_read_b128 v[8:11], v57 offset:30720
	ds_read_b128 v[12:15], v57 offset:33280
	ds_read_b128 v[16:19], v57 offset:35840
	ds_read_b128 v[20:23], v57 offset:38400
	ds_read_b128 v[24:27], v56 offset:30752
	ds_read_b128 v[28:31], v56 offset:33312
	s_waitcnt lgkmcnt(4)
	v_mfma_f32_32x32x16_bf16 v[66:81], v[0:3], v[8:11], v[66:81]
	v_mfma_f32_32x32x16_bf16 v[82:97], v[0:3], v[12:15], v[82:97]
	s_waitcnt vmcnt(6)
	ds_write_b128 v58, v[32:35] offset:0
	ds_write_b128 v58, v[36:39] offset:5120
	s_waitcnt lgkmcnt(4)
	v_mfma_f32_32x32x16_bf16 v[98:113], v[0:3], v[16:19], v[98:113]
	v_mfma_f32_32x32x16_bf16 v[114:129], v[0:3], v[20:23], v[114:129]
	ds_read_b128 v[0:3], v57 offset:30752
	ds_write_b128 v58, v[40:43] offset:10240
	ds_write_b128 v58, v[44:47] offset:15360
	v_mfma_f32_32x32x16_bf16 v[130:145], v[4:7], v[8:11], v[130:145]
	v_mfma_f32_32x32x16_bf16 v[146:161], v[4:7], v[12:15], v[146:161]
	ds_write_b128 v58, v[48:51] offset:20480
	ds_write_b128 v58, v[52:55] offset:25600
	v_mfma_f32_32x32x16_bf16 v[162:177], v[4:7], v[16:19], v[162:177]
	v_mfma_f32_32x32x16_bf16 v[178:193], v[4:7], v[20:23], v[178:193]
	ds_read_b128 v[4:7], v57 offset:33312
	ds_read_b128 v[8:11], v57 offset:35872
	ds_read_b128 v[12:15], v57 offset:38432
	s_waitcnt lgkmcnt(2)
	v_mfma_f32_32x32x16_bf16 v[66:81], v[24:27], v[0:3], v[66:81]
	global_load_dwordx4 v[32:35], v[240:241], off offset:3200
	global_load_dwordx4 v[36:39], v[242:243], off offset:3200
	v_mfma_f32_32x32x16_bf16 v[82:97], v[24:27], v[4:7], v[82:97]
	s_waitcnt lgkmcnt(0)
	v_mfma_f32_32x32x16_bf16 v[98:113], v[24:27], v[8:11], v[98:113]
	global_load_dwordx4 v[40:43], v[244:245], off offset:1152
	global_load_dwordx4 v[44:47], v[246:247], off offset:1152
	v_mfma_f32_32x32x16_bf16 v[114:129], v[24:27], v[12:15], v[114:129]
	v_mfma_f32_32x32x16_bf16 v[130:145], v[28:31], v[0:3], v[130:145]
	global_load_dwordx4 v[48:51], v[248:249], off offset:1152
	global_load_dwordx4 v[52:55], v[250:251], off offset:1152
	v_mfma_f32_32x32x16_bf16 v[146:161], v[28:31], v[4:7], v[146:161]
	v_mfma_f32_32x32x16_bf16 v[162:177], v[28:31], v[8:11], v[162:177]
	v_mfma_f32_32x32x16_bf16 v[178:193], v[28:31], v[12:15], v[178:193]
	s_waitcnt lgkmcnt(0)
	s_barrier
; #define G_LOAD(S, kt_) do { G_LD1(S##a0, S##b0, 0, kt_); G_LD1(S##a1, S##b1, 1, kt_); G_LD1(S##a2, S##b2, 2, kt_); G_LD1(S##a3, S##b3, 3, kt_); } while (0)
; #define G_STORE(S, buf_) do { G_ST1(S##a0, S##b0, 0, buf_); G_ST1(S##a1, S##b1, 1, buf_); G_ST1(S##a2, S##b2, 2, buf_); G_ST1(S##a3, S##b3, 3, buf_); } while (0)
; template <class AL, class BL>
; DI void gemm_core(AL al, BL bl, int m0, int n0, int K, char* smem, f32x16 (&acc)[2][2]) {
;     ...
;   G_LOAD(x, 0);
;   G_STORE(x, 0);
;   G_LOAD(x, 1);
;   G_LOAD(y, (nk > 2) ? 2 : 1);
;   __syncthreads();
;   for (int kt = 0; kt < nk; kt += 2) {
;     G_TILE(0, x, true, (kt + 3 < nk), kt + 3);
;     __syncthreads();
;     G_TILE(1, y, (kt + 2 < nk), (kt + 4 < nk), kt + 4);
;     __syncthreads();
	ds_read_b128 v[0:3], v56 offset:0
	ds_read_b128 v[4:7], v56 offset:2560
	ds_read_b128 v[8:11], v57 offset:0
	ds_read_b128 v[12:15], v57 offset:2560
	ds_read_b128 v[16:19], v57 offset:5120
	ds_read_b128 v[20:23], v57 offset:7680
	ds_read_b128 v[24:27], v56 offset:32
	ds_read_b128 v[28:31], v56 offset:2592
	s_waitcnt lgkmcnt(4)
	v_mfma_f32_32x32x16_bf16 v[66:81], v[0:3], v[8:11], v[66:81]
	v_mfma_f32_32x32x16_bf16 v[82:97], v[0:3], v[12:15], v[82:97]
	s_waitcnt vmcnt(6)
	ds_write_b128 v58, v[214:217] offset:30720
	ds_write_b128 v58, v[218:221] offset:35840
	s_waitcnt lgkmcnt(4)
	v_mfma_f32_32x32x16_bf16 v[98:113], v[0:3], v[16:19], v[98:113]
	v_mfma_f32_32x32x16_bf16 v[114:129], v[0:3], v[20:23], v[114:129]
	ds_read_b128 v[0:3], v57 offset:32
	ds_write_b128 v58, v[222:225] offset:40960
	ds_write_b128 v58, v[228:231] offset:46080
	v_mfma_f32_32x32x16_bf16 v[130:145], v[4:7], v[8:11], v[130:145]
	v_mfma_f32_32x32x16_bf16 v[146:161], v[4:7], v[12:15], v[146:161]
	ds_write_b128 v58, v[232:235] offset:51200
	ds_write_b128 v58, v[236:239] offset:56320
	v_mfma_f32_32x32x16_bf16 v[162:177], v[4:7], v[16:19], v[162:177]
	v_mfma_f32_32x32x16_bf16 v[178:193], v[4:7], v[20:23], v[178:193]
	ds_read_b128 v[4:7], v57 offset:2592
	ds_read_b128 v[8:11], v57 offset:5152
	ds_read_b128 v[12:15], v57 offset:7712
	s_waitcnt lgkmcnt(2)
	v_mfma_f32_32x32x16_bf16 v[66:81], v[24:27], v[0:3], v[66:81]
	global_load_dwordx4 v[214:217], v[240:241], off offset:3264
	global_load_dwordx4 v[218:221], v[242:243], off offset:3264
	v_mfma_f32_32x32x16_bf16 v[82:97], v[24:27], v[4:7], v[82:97]
	s_waitcnt lgkmcnt(0)
	v_mfma_f32_32x32x16_bf16 v[98:113], v[24:27], v[8:11], v[98:113]
	global_load_dwordx4 v[222:225], v[244:245], off offset:1216
	global_load_dwordx4 v[228:231], v[246:247], off offset:1216
	v_mfma_f32_32x32x16_bf16 v[114:129], v[24:27], v[12:15], v[114:129]
	v_mfma_f32_32x32x16_bf16 v[130:145], v[28:31], v[0:3], v[130:145]
	global_load_dwordx4 v[232:235], v[248:249], off offset:1216
	global_load_dwordx4 v[236:239], v[250:251], off offset:1216
	v_mfma_f32_32x32x16_bf16 v[146:161], v[28:31], v[4:7], v[146:161]
	v_mfma_f32_32x32x16_bf16 v[162:177], v[28:31], v[8:11], v[162:177]
	v_mfma_f32_32x32x16_bf16 v[178:193], v[28:31], v[12:15], v[178:193]
	s_waitcnt lgkmcnt(0)
	s_barrier
	ds_read_b128 v[0:3], v56 offset:30720
	ds_read_b128 v[4:7], v56 offset:33280
	ds_read_b128 v[8:11], v57 offset:30720
	ds_read_b128 v[12:15], v57 offset:33280
	ds_read_b128 v[16:19], v57 offset:35840
	ds_read_b128 v[20:23], v57 offset:38400
	ds_read_b128 v[24:27], v56 offset:30752
	ds_read_b128 v[28:31], v56 offset:33312
	s_waitcnt lgkmcnt(4)
	v_mfma_f32_32x32x16_bf16 v[66:81], v[0:3], v[8:11], v[66:81]
	v_mfma_f32_32x32x16_bf16 v[82:97], v[0:3], v[12:15], v[82:97]
	s_waitcnt vmcnt(6)
	ds_write_b128 v58, v[32:35] offset:0
	ds_write_b128 v58, v[36:39] offset:5120
	s_waitcnt lgkmcnt(4)
	v_mfma_f32_32x32x16_bf16 v[98:113], v[0:3], v[16:19], v[98:113]
	v_mfma_f32_32x32x16_bf16 v[114:129], v[0:3], v[20:23], v[114:129]
	ds_read_b128 v[0:3], v57 offset:30752
	ds_write_b128 v58, v[40:43] offset:10240
	ds_write_b128 v58, v[44:47] offset:15360
	v_mfma_f32_32x32x16_bf16 v[130:145], v[4:7], v[8:11], v[130:145]
	v_mfma_f32_32x32x16_bf16 v[146:161], v[4:7], v[12:15], v[146:161]
	ds_write_b128 v58, v[48:51] offset:20480
	ds_write_b128 v58, v[52:55] offset:25600
	v_mfma_f32_32x32x16_bf16 v[162:177], v[4:7], v[16:19], v[162:177]
	v_mfma_f32_32x32x16_bf16 v[178:193], v[4:7], v[20:23], v[178:193]
	ds_read_b128 v[4:7], v57 offset:33312
	ds_read_b128 v[8:11], v57 offset:35872
	ds_read_b128 v[12:15], v57 offset:38432
	s_waitcnt lgkmcnt(2)
	v_mfma_f32_32x32x16_bf16 v[66:81], v[24:27], v[0:3], v[66:81]
	global_load_dwordx4 v[32:35], v[240:241], off offset:3328
	global_load_dwordx4 v[36:39], v[242:243], off offset:3328
	v_mfma_f32_32x32x16_bf16 v[82:97], v[24:27], v[4:7], v[82:97]
	s_waitcnt lgkmcnt(0)
	v_mfma_f32_32x32x16_bf16 v[98:113], v[24:27], v[8:11], v[98:113]
	global_load_dwordx4 v[40:43], v[244:245], off offset:1280
	global_load_dwordx4 v[44:47], v[246:247], off offset:1280
	v_mfma_f32_32x32x16_bf16 v[114:129], v[24:27], v[12:15], v[114:129]
	v_mfma_f32_32x32x16_bf16 v[130:145], v[28:31], v[0:3], v[130:145]
	global_load_dwordx4 v[48:51], v[248:249], off offset:1280
	global_load_dwordx4 v[52:55], v[250:251], off offset:1280
	v_mfma_f32_32x32x16_bf16 v[146:161], v[28:31], v[4:7], v[146:161]
	v_mfma_f32_32x32x16_bf16 v[162:177], v[28:31], v[8:11], v[162:177]
	v_mfma_f32_32x32x16_bf16 v[178:193], v[28:31], v[12:15], v[178:193]
	s_waitcnt lgkmcnt(0)
	s_barrier
; #define G_LOAD(S, kt_) do { G_LD1(S##a0, S##b0, 0, kt_); G_LD1(S##a1, S##b1, 1, kt_); G_LD1(S##a2, S##b2, 2, kt_); G_LD1(S##a3, S##b3, 3, kt_); } while (0)
; #define G_STORE(S, buf_) do { G_ST1(S##a0, S##b0, 0, buf_); G_ST1(S##a1, S##b1, 1, buf_); G_ST1(S##a2, S##b2, 2, buf_); G_ST1(S##a3, S##b3, 3, buf_); } while (0)
; template <class AL, class BL>
; DI void gemm_core(AL al, BL bl, int m0, int n0, int K, char* smem, f32x16 (&acc)[2][2]) {
;     ...
;   G_LOAD(x, 0);
;   G_STORE(x, 0);
;   G_LOAD(x, 1);
;   G_LOAD(y, (nk > 2) ? 2 : 1);
;   __syncthreads();
;   for (int kt = 0; kt < nk; kt += 2) {
;     G_TILE(0, x, true, (kt + 3 < nk), kt + 3);
;     __syncthreads();
;     G_TILE(1, y, (kt + 2 < nk), (kt + 4 < nk), kt + 4);
;     __syncthreads();
	ds_read_b128 v[0:3], v56 offset:0
	ds_read_b128 v[4:7], v56 offset:2560
	ds_read_b128 v[8:11], v57 offset:0
	ds_read_b128 v[12:15], v57 offset:2560
	ds_read_b128 v[16:19], v57 offset:5120
	ds_read_b128 v[20:23], v57 offset:7680
	ds_read_b128 v[24:27], v56 offset:32
	ds_read_b128 v[28:31], v56 offset:2592
	s_waitcnt lgkmcnt(4)
	v_mfma_f32_32x32x16_bf16 v[66:81], v[0:3], v[8:11], v[66:81]
	v_mfma_f32_32x32x16_bf16 v[82:97], v[0:3], v[12:15], v[82:97]
	s_waitcnt vmcnt(6)
	ds_write_b128 v58, v[214:217] offset:30720
	ds_write_b128 v58, v[218:221] offset:35840
	s_waitcnt lgkmcnt(4)
	v_mfma_f32_32x32x16_bf16 v[98:113], v[0:3], v[16:19], v[98:113]
	v_mfma_f32_32x32x16_bf16 v[114:129], v[0:3], v[20:23], v[114:129]
	ds_read_b128 v[0:3], v57 offset:32
	ds_write_b128 v58, v[222:225] offset:40960
	ds_write_b128 v58, v[228:231] offset:46080
	v_mfma_f32_32x32x16_bf16 v[130:145], v[4:7], v[8:11], v[130:145]
	v_mfma_f32_32x32x16_bf16 v[146:161], v[4:7], v[12:15], v[146:161]
	ds_write_b128 v58, v[232:235] offset:51200
	ds_write_b128 v58, v[236:239] offset:56320
	v_mfma_f32_32x32x16_bf16 v[162:177], v[4:7], v[16:19], v[162:177]
	v_mfma_f32_32x32x16_bf16 v[178:193], v[4:7], v[20:23], v[178:193]
	ds_read_b128 v[4:7], v57 offset:2592
	ds_read_b128 v[8:11], v57 offset:5152
	ds_read_b128 v[12:15], v57 offset:7712
	s_waitcnt lgkmcnt(2)
	v_mfma_f32_32x32x16_bf16 v[66:81], v[24:27], v[0:3], v[66:81]
	global_load_dwordx4 v[214:217], v[240:241], off offset:3392
	global_load_dwordx4 v[218:221], v[242:243], off offset:3392
	v_mfma_f32_32x32x16_bf16 v[82:97], v[24:27], v[4:7], v[82:97]
	s_waitcnt lgkmcnt(0)
	v_mfma_f32_32x32x16_bf16 v[98:113], v[24:27], v[8:11], v[98:113]
	global_load_dwordx4 v[222:225], v[244:245], off offset:1344
	global_load_dwordx4 v[228:231], v[246:247], off offset:1344
	v_mfma_f32_32x32x16_bf16 v[114:129], v[24:27], v[12:15], v[114:129]
	v_mfma_f32_32x32x16_bf16 v[130:145], v[28:31], v[0:3], v[130:145]
	global_load_dwordx4 v[232:235], v[248:249], off offset:1344
	global_load_dwordx4 v[236:239], v[250:251], off offset:1344
	v_mfma_f32_32x32x16_bf16 v[146:161], v[28:31], v[4:7], v[146:161]
	v_mfma_f32_32x32x16_bf16 v[162:177], v[28:31], v[8:11], v[162:177]
	v_mfma_f32_32x32x16_bf16 v[178:193], v[28:31], v[12:15], v[178:193]
	s_waitcnt lgkmcnt(0)
	s_barrier
	ds_read_b128 v[0:3], v56 offset:30720
	ds_read_b128 v[4:7], v56 offset:33280
	ds_read_b128 v[8:11], v57 offset:30720
	ds_read_b128 v[12:15], v57 offset:33280
	ds_read_b128 v[16:19], v57 offset:35840
	ds_read_b128 v[20:23], v57 offset:38400
	ds_read_b128 v[24:27], v56 offset:30752
	ds_read_b128 v[28:31], v56 offset:33312
	s_waitcnt lgkmcnt(4)
	v_mfma_f32_32x32x16_bf16 v[66:81], v[0:3], v[8:11], v[66:81]
	v_mfma_f32_32x32x16_bf16 v[82:97], v[0:3], v[12:15], v[82:97]
	s_waitcnt vmcnt(6)
	ds_write_b128 v58, v[32:35] offset:0
	ds_write_b128 v58, v[36:39] offset:5120
	s_waitcnt lgkmcnt(4)
	v_mfma_f32_32x32x16_bf16 v[98:113], v[0:3], v[16:19], v[98:113]
	v_mfma_f32_32x32x16_bf16 v[114:129], v[0:3], v[20:23], v[114:129]
	ds_read_b128 v[0:3], v57 offset:30752
	ds_write_b128 v58, v[40:43] offset:10240
	ds_write_b128 v58, v[44:47] offset:15360
	v_mfma_f32_32x32x16_bf16 v[130:145], v[4:7], v[8:11], v[130:145]
	v_mfma_f32_32x32x16_bf16 v[146:161], v[4:7], v[12:15], v[146:161]
	ds_write_b128 v58, v[48:51] offset:20480
	ds_write_b128 v58, v[52:55] offset:25600
	v_mfma_f32_32x32x16_bf16 v[162:177], v[4:7], v[16:19], v[162:177]
	v_mfma_f32_32x32x16_bf16 v[178:193], v[4:7], v[20:23], v[178:193]
	ds_read_b128 v[4:7], v57 offset:33312
	ds_read_b128 v[8:11], v57 offset:35872
	ds_read_b128 v[12:15], v57 offset:38432
	s_waitcnt lgkmcnt(2)
	v_mfma_f32_32x32x16_bf16 v[66:81], v[24:27], v[0:3], v[66:81]
	global_load_dwordx4 v[32:35], v[240:241], off offset:3456
	global_load_dwordx4 v[36:39], v[242:243], off offset:3456
	v_mfma_f32_32x32x16_bf16 v[82:97], v[24:27], v[4:7], v[82:97]
	s_waitcnt lgkmcnt(0)
	v_mfma_f32_32x32x16_bf16 v[98:113], v[24:27], v[8:11], v[98:113]
	global_load_dwordx4 v[40:43], v[244:245], off offset:1408
	global_load_dwordx4 v[44:47], v[246:247], off offset:1408
	v_mfma_f32_32x32x16_bf16 v[114:129], v[24:27], v[12:15], v[114:129]
	v_mfma_f32_32x32x16_bf16 v[130:145], v[28:31], v[0:3], v[130:145]
	global_load_dwordx4 v[48:51], v[248:249], off offset:1408
	global_load_dwordx4 v[52:55], v[250:251], off offset:1408
	v_mfma_f32_32x32x16_bf16 v[146:161], v[28:31], v[4:7], v[146:161]
	v_mfma_f32_32x32x16_bf16 v[162:177], v[28:31], v[8:11], v[162:177]
	v_mfma_f32_32x32x16_bf16 v[178:193], v[28:31], v[12:15], v[178:193]
	s_waitcnt lgkmcnt(0)
	s_barrier
; #define G_LOAD(S, kt_) do { G_LD1(S##a0, S##b0, 0, kt_); G_LD1(S##a1, S##b1, 1, kt_); G_LD1(S##a2, S##b2, 2, kt_); G_LD1(S##a3, S##b3, 3, kt_); } while (0)
; #define G_STORE(S, buf_) do { G_ST1(S##a0, S##b0, 0, buf_); G_ST1(S##a1, S##b1, 1, buf_); G_ST1(S##a2, S##b2, 2, buf_); G_ST1(S##a3, S##b3, 3, buf_); } while (0)
; template <class AL, class BL>
; DI void gemm_core(AL al, BL bl, int m0, int n0, int K, char* smem, f32x16 (&acc)[2][2]) {
;     ...
;   G_LOAD(x, 0);
;   G_STORE(x, 0);
;   G_LOAD(x, 1);
;   G_LOAD(y, (nk > 2) ? 2 : 1);
;   __syncthreads();
;   for (int kt = 0; kt < nk; kt += 2) {
;     G_TILE(0, x, true, (kt + 3 < nk), kt + 3);
;     __syncthreads();
;     G_TILE(1, y, (kt + 2 < nk), (kt + 4 < nk), kt + 4);
;     __syncthreads();
	ds_read_b128 v[0:3], v56 offset:0
	ds_read_b128 v[4:7], v56 offset:2560
	ds_read_b128 v[8:11], v57 offset:0
	ds_read_b128 v[12:15], v57 offset:2560
	ds_read_b128 v[16:19], v57 offset:5120
	ds_read_b128 v[20:23], v57 offset:7680
	ds_read_b128 v[24:27], v56 offset:32
	ds_read_b128 v[28:31], v56 offset:2592
	s_waitcnt lgkmcnt(4)
	v_mfma_f32_32x32x16_bf16 v[66:81], v[0:3], v[8:11], v[66:81]
	v_mfma_f32_32x32x16_bf16 v[82:97], v[0:3], v[12:15], v[82:97]
	s_waitcnt vmcnt(6)
	ds_write_b128 v58, v[214:217] offset:30720
	ds_write_b128 v58, v[218:221] offset:35840
	s_waitcnt lgkmcnt(4)
	v_mfma_f32_32x32x16_bf16 v[98:113], v[0:3], v[16:19], v[98:113]
	v_mfma_f32_32x32x16_bf16 v[114:129], v[0:3], v[20:23], v[114:129]
	ds_read_b128 v[0:3], v57 offset:32
	ds_write_b128 v58, v[222:225] offset:40960
	ds_write_b128 v58, v[228:231] offset:46080
	v_mfma_f32_32x32x16_bf16 v[130:145], v[4:7], v[8:11], v[130:145]
	v_mfma_f32_32x32x16_bf16 v[146:161], v[4:7], v[12:15], v[146:161]
	ds_write_b128 v58, v[232:235] offset:51200
	ds_write_b128 v58, v[236:239] offset:56320
	v_mfma_f32_32x32x16_bf16 v[162:177], v[4:7], v[16:19], v[162:177]
	v_mfma_f32_32x32x16_bf16 v[178:193], v[4:7], v[20:23], v[178:193]
	ds_read_b128 v[4:7], v57 offset:2592
	ds_read_b128 v[8:11], v57 offset:5152
	ds_read_b128 v[12:15], v57 offset:7712
	s_waitcnt lgkmcnt(2)
	v_mfma_f32_32x32x16_bf16 v[66:81], v[24:27], v[0:3], v[66:81]
	global_load_dwordx4 v[214:217], v[240:241], off offset:3520
	global_load_dwordx4 v[218:221], v[242:243], off offset:3520
	v_mfma_f32_32x32x16_bf16 v[82:97], v[24:27], v[4:7], v[82:97]
	s_waitcnt lgkmcnt(0)
	v_mfma_f32_32x32x16_bf16 v[98:113], v[24:27], v[8:11], v[98:113]
	global_load_dwordx4 v[222:225], v[244:245], off offset:1472
	global_load_dwordx4 v[228:231], v[246:247], off offset:1472
	v_mfma_f32_32x32x16_bf16 v[114:129], v[24:27], v[12:15], v[114:129]
	v_mfma_f32_32x32x16_bf16 v[130:145], v[28:31], v[0:3], v[130:145]
	global_load_dwordx4 v[232:235], v[248:249], off offset:1472
	global_load_dwordx4 v[236:239], v[250:251], off offset:1472
	v_mfma_f32_32x32x16_bf16 v[146:161], v[28:31], v[4:7], v[146:161]
	v_mfma_f32_32x32x16_bf16 v[162:177], v[28:31], v[8:11], v[162:177]
	v_mfma_f32_32x32x16_bf16 v[178:193], v[28:31], v[12:15], v[178:193]
	s_waitcnt lgkmcnt(0)
	s_barrier
	ds_read_b128 v[0:3], v56 offset:30720
	ds_read_b128 v[4:7], v56 offset:33280
	ds_read_b128 v[8:11], v57 offset:30720
	ds_read_b128 v[12:15], v57 offset:33280
	ds_read_b128 v[16:19], v57 offset:35840
	ds_read_b128 v[20:23], v57 offset:38400
	ds_read_b128 v[24:27], v56 offset:30752
	ds_read_b128 v[28:31], v56 offset:33312
	s_waitcnt lgkmcnt(4)
	v_mfma_f32_32x32x16_bf16 v[66:81], v[0:3], v[8:11], v[66:81]
	v_mfma_f32_32x32x16_bf16 v[82:97], v[0:3], v[12:15], v[82:97]
	s_waitcnt vmcnt(6)
	ds_write_b128 v58, v[32:35] offset:0
	ds_write_b128 v58, v[36:39] offset:5120
	s_waitcnt lgkmcnt(4)
	v_mfma_f32_32x32x16_bf16 v[98:113], v[0:3], v[16:19], v[98:113]
	v_mfma_f32_32x32x16_bf16 v[114:129], v[0:3], v[20:23], v[114:129]
	ds_read_b128 v[0:3], v57 offset:30752
	ds_write_b128 v58, v[40:43] offset:10240
	ds_write_b128 v58, v[44:47] offset:15360
	v_mfma_f32_32x32x16_bf16 v[130:145], v[4:7], v[8:11], v[130:145]
	v_mfma_f32_32x32x16_bf16 v[146:161], v[4:7], v[12:15], v[146:161]
	ds_write_b128 v58, v[48:51] offset:20480
	ds_write_b128 v58, v[52:55] offset:25600
	v_mfma_f32_32x32x16_bf16 v[162:177], v[4:7], v[16:19], v[162:177]
	v_mfma_f32_32x32x16_bf16 v[178:193], v[4:7], v[20:23], v[178:193]
	ds_read_b128 v[4:7], v57 offset:33312
	ds_read_b128 v[8:11], v57 offset:35872
	ds_read_b128 v[12:15], v57 offset:38432
	s_waitcnt lgkmcnt(2)
	v_mfma_f32_32x32x16_bf16 v[66:81], v[24:27], v[0:3], v[66:81]
	global_load_dwordx4 v[32:35], v[240:241], off offset:3584
	global_load_dwordx4 v[36:39], v[242:243], off offset:3584
	v_mfma_f32_32x32x16_bf16 v[82:97], v[24:27], v[4:7], v[82:97]
	s_waitcnt lgkmcnt(0)
	v_mfma_f32_32x32x16_bf16 v[98:113], v[24:27], v[8:11], v[98:113]
	global_load_dwordx4 v[40:43], v[244:245], off offset:1536
	global_load_dwordx4 v[44:47], v[246:247], off offset:1536
	v_mfma_f32_32x32x16_bf16 v[114:129], v[24:27], v[12:15], v[114:129]
	v_mfma_f32_32x32x16_bf16 v[130:145], v[28:31], v[0:3], v[130:145]
	global_load_dwordx4 v[48:51], v[248:249], off offset:1536
	global_load_dwordx4 v[52:55], v[250:251], off offset:1536
	v_mfma_f32_32x32x16_bf16 v[146:161], v[28:31], v[4:7], v[146:161]
	v_mfma_f32_32x32x16_bf16 v[162:177], v[28:31], v[8:11], v[162:177]
	v_mfma_f32_32x32x16_bf16 v[178:193], v[28:31], v[12:15], v[178:193]
	s_waitcnt lgkmcnt(0)
	s_barrier
; #define G_LOAD(S, kt_) do { G_LD1(S##a0, S##b0, 0, kt_); G_LD1(S##a1, S##b1, 1, kt_); G_LD1(S##a2, S##b2, 2, kt_); G_LD1(S##a3, S##b3, 3, kt_); } while (0)
; #define G_STORE(S, buf_) do { G_ST1(S##a0, S##b0, 0, buf_); G_ST1(S##a1, S##b1, 1, buf_); G_ST1(S##a2, S##b2, 2, buf_); G_ST1(S##a3, S##b3, 3, buf_); } while (0)
; template <class AL, class BL>
; DI void gemm_core(AL al, BL bl, int m0, int n0, int K, char* smem, f32x16 (&acc)[2][2]) {
;     ...
;   G_LOAD(x, 0);
;   G_STORE(x, 0);
;   G_LOAD(x, 1);
;   G_LOAD(y, (nk > 2) ? 2 : 1);
;   __syncthreads();
;   for (int kt = 0; kt < nk; kt += 2) {
;     G_TILE(0, x, true, (kt + 3 < nk), kt + 3);
;     __syncthreads();
;     G_TILE(1, y, (kt + 2 < nk), (kt + 4 < nk), kt + 4);
;     __syncthreads();
	ds_read_b128 v[0:3], v56 offset:0
	ds_read_b128 v[4:7], v56 offset:2560
	ds_read_b128 v[8:11], v57 offset:0
	ds_read_b128 v[12:15], v57 offset:2560
	ds_read_b128 v[16:19], v57 offset:5120
	ds_read_b128 v[20:23], v57 offset:7680
	ds_read_b128 v[24:27], v56 offset:32
	ds_read_b128 v[28:31], v56 offset:2592
	s_waitcnt lgkmcnt(4)
	v_mfma_f32_32x32x16_bf16 v[66:81], v[0:3], v[8:11], v[66:81]
	v_mfma_f32_32x32x16_bf16 v[82:97], v[0:3], v[12:15], v[82:97]
	s_waitcnt vmcnt(6)
	ds_write_b128 v58, v[214:217] offset:30720
	ds_write_b128 v58, v[218:221] offset:35840
	s_waitcnt lgkmcnt(4)
	v_mfma_f32_32x32x16_bf16 v[98:113], v[0:3], v[16:19], v[98:113]
	v_mfma_f32_32x32x16_bf16 v[114:129], v[0:3], v[20:23], v[114:129]
	ds_read_b128 v[0:3], v57 offset:32
	ds_write_b128 v58, v[222:225] offset:40960
	ds_write_b128 v58, v[228:231] offset:46080
	v_mfma_f32_32x32x16_bf16 v[130:145], v[4:7], v[8:11], v[130:145]
	v_mfma_f32_32x32x16_bf16 v[146:161], v[4:7], v[12:15], v[146:161]
	ds_write_b128 v58, v[232:235] offset:51200
	ds_write_b128 v58, v[236:239] offset:56320
	v_mfma_f32_32x32x16_bf16 v[162:177], v[4:7], v[16:19], v[162:177]
	v_mfma_f32_32x32x16_bf16 v[178:193], v[4:7], v[20:23], v[178:193]
	ds_read_b128 v[4:7], v57 offset:2592
	ds_read_b128 v[8:11], v57 offset:5152
	ds_read_b128 v[12:15], v57 offset:7712
	s_waitcnt lgkmcnt(2)
	v_mfma_f32_32x32x16_bf16 v[66:81], v[24:27], v[0:3], v[66:81]
	global_load_dwordx4 v[214:217], v[240:241], off offset:3648
	global_load_dwordx4 v[218:221], v[242:243], off offset:3648
	v_mfma_f32_32x32x16_bf16 v[82:97], v[24:27], v[4:7], v[82:97]
	s_waitcnt lgkmcnt(0)
	v_mfma_f32_32x32x16_bf16 v[98:113], v[24:27], v[8:11], v[98:113]
	global_load_dwordx4 v[222:225], v[244:245], off offset:1600
	global_load_dwordx4 v[228:231], v[246:247], off offset:1600
	v_mfma_f32_32x32x16_bf16 v[114:129], v[24:27], v[12:15], v[114:129]
	v_mfma_f32_32x32x16_bf16 v[130:145], v[28:31], v[0:3], v[130:145]
	global_load_dwordx4 v[232:235], v[248:249], off offset:1600
	global_load_dwordx4 v[236:239], v[250:251], off offset:1600
	v_mfma_f32_32x32x16_bf16 v[146:161], v[28:31], v[4:7], v[146:161]
	v_mfma_f32_32x32x16_bf16 v[162:177], v[28:31], v[8:11], v[162:177]
	v_mfma_f32_32x32x16_bf16 v[178:193], v[28:31], v[12:15], v[178:193]
	s_waitcnt lgkmcnt(0)
	s_barrier
	ds_read_b128 v[0:3], v56 offset:30720
	ds_read_b128 v[4:7], v56 offset:33280
	ds_read_b128 v[8:11], v57 offset:30720
	ds_read_b128 v[12:15], v57 offset:33280
	ds_read_b128 v[16:19], v57 offset:35840
	ds_read_b128 v[20:23], v57 offset:38400
	ds_read_b128 v[24:27], v56 offset:30752
	ds_read_b128 v[28:31], v56 offset:33312
	s_waitcnt lgkmcnt(4)
	v_mfma_f32_32x32x16_bf16 v[66:81], v[0:3], v[8:11], v[66:81]
	v_mfma_f32_32x32x16_bf16 v[82:97], v[0:3], v[12:15], v[82:97]
	s_waitcnt vmcnt(6)
	ds_write_b128 v58, v[32:35] offset:0
	ds_write_b128 v58, v[36:39] offset:5120
	s_waitcnt lgkmcnt(4)
	v_mfma_f32_32x32x16_bf16 v[98:113], v[0:3], v[16:19], v[98:113]
	v_mfma_f32_32x32x16_bf16 v[114:129], v[0:3], v[20:23], v[114:129]
	ds_read_b128 v[0:3], v57 offset:30752
	ds_write_b128 v58, v[40:43] offset:10240
	ds_write_b128 v58, v[44:47] offset:15360
	v_mfma_f32_32x32x16_bf16 v[130:145], v[4:7], v[8:11], v[130:145]
	v_mfma_f32_32x32x16_bf16 v[146:161], v[4:7], v[12:15], v[146:161]
	ds_write_b128 v58, v[48:51] offset:20480
	ds_write_b128 v58, v[52:55] offset:25600
	v_mfma_f32_32x32x16_bf16 v[162:177], v[4:7], v[16:19], v[162:177]
	v_mfma_f32_32x32x16_bf16 v[178:193], v[4:7], v[20:23], v[178:193]
	ds_read_b128 v[4:7], v57 offset:33312
	ds_read_b128 v[8:11], v57 offset:35872
	ds_read_b128 v[12:15], v57 offset:38432
	s_waitcnt lgkmcnt(2)
	v_mfma_f32_32x32x16_bf16 v[66:81], v[24:27], v[0:3], v[66:81]
	global_load_dwordx4 v[32:35], v[240:241], off offset:3712
	global_load_dwordx4 v[36:39], v[242:243], off offset:3712
	v_mfma_f32_32x32x16_bf16 v[82:97], v[24:27], v[4:7], v[82:97]
	s_waitcnt lgkmcnt(0)
	v_mfma_f32_32x32x16_bf16 v[98:113], v[24:27], v[8:11], v[98:113]
	global_load_dwordx4 v[40:43], v[244:245], off offset:1664
	global_load_dwordx4 v[44:47], v[246:247], off offset:1664
	v_mfma_f32_32x32x16_bf16 v[114:129], v[24:27], v[12:15], v[114:129]
	v_mfma_f32_32x32x16_bf16 v[130:145], v[28:31], v[0:3], v[130:145]
	global_load_dwordx4 v[48:51], v[248:249], off offset:1664
	global_load_dwordx4 v[52:55], v[250:251], off offset:1664
	v_mfma_f32_32x32x16_bf16 v[146:161], v[28:31], v[4:7], v[146:161]
	v_mfma_f32_32x32x16_bf16 v[162:177], v[28:31], v[8:11], v[162:177]
	v_mfma_f32_32x32x16_bf16 v[178:193], v[28:31], v[12:15], v[178:193]
	s_waitcnt lgkmcnt(0)
	s_barrier
; #define G_LOAD(S, kt_) do { G_LD1(S##a0, S##b0, 0, kt_); G_LD1(S##a1, S##b1, 1, kt_); G_LD1(S##a2, S##b2, 2, kt_); G_LD1(S##a3, S##b3, 3, kt_); } while (0)
; #define G_STORE(S, buf_) do { G_ST1(S##a0, S##b0, 0, buf_); G_ST1(S##a1, S##b1, 1, buf_); G_ST1(S##a2, S##b2, 2, buf_); G_ST1(S##a3, S##b3, 3, buf_); } while (0)
; template <class AL, class BL>
; DI void gemm_core(AL al, BL bl, int m0, int n0, int K, char* smem, f32x16 (&acc)[2][2]) {
;     ...
;   G_LOAD(x, 0);
;   G_STORE(x, 0);
;   G_LOAD(x, 1);
;   G_LOAD(y, (nk > 2) ? 2 : 1);
;   __syncthreads();
;   for (int kt = 0; kt < nk; kt += 2) {
;     G_TILE(0, x, true, (kt + 3 < nk), kt + 3);
;     __syncthreads();
;     G_TILE(1, y, (kt + 2 < nk), (kt + 4 < nk), kt + 4);
;     __syncthreads();
	ds_read_b128 v[0:3], v56 offset:0
	ds_read_b128 v[4:7], v56 offset:2560
	ds_read_b128 v[8:11], v57 offset:0
	ds_read_b128 v[12:15], v57 offset:2560
	ds_read_b128 v[16:19], v57 offset:5120
	ds_read_b128 v[20:23], v57 offset:7680
	ds_read_b128 v[24:27], v56 offset:32
	ds_read_b128 v[28:31], v56 offset:2592
	s_waitcnt lgkmcnt(4)
	v_mfma_f32_32x32x16_bf16 v[66:81], v[0:3], v[8:11], v[66:81]
	v_mfma_f32_32x32x16_bf16 v[82:97], v[0:3], v[12:15], v[82:97]
	s_waitcnt vmcnt(6)
	ds_write_b128 v58, v[214:217] offset:30720
	ds_write_b128 v58, v[218:221] offset:35840
	s_waitcnt lgkmcnt(4)
	v_mfma_f32_32x32x16_bf16 v[98:113], v[0:3], v[16:19], v[98:113]
	v_mfma_f32_32x32x16_bf16 v[114:129], v[0:3], v[20:23], v[114:129]
	ds_read_b128 v[0:3], v57 offset:32
	ds_write_b128 v58, v[222:225] offset:40960
	ds_write_b128 v58, v[228:231] offset:46080
	v_mfma_f32_32x32x16_bf16 v[130:145], v[4:7], v[8:11], v[130:145]
	v_mfma_f32_32x32x16_bf16 v[146:161], v[4:7], v[12:15], v[146:161]
	ds_write_b128 v58, v[232:235] offset:51200
	ds_write_b128 v58, v[236:239] offset:56320
	v_mfma_f32_32x32x16_bf16 v[162:177], v[4:7], v[16:19], v[162:177]
	v_mfma_f32_32x32x16_bf16 v[178:193], v[4:7], v[20:23], v[178:193]
	ds_read_b128 v[4:7], v57 offset:2592
	ds_read_b128 v[8:11], v57 offset:5152
	ds_read_b128 v[12:15], v57 offset:7712
	s_waitcnt lgkmcnt(2)
	v_mfma_f32_32x32x16_bf16 v[66:81], v[24:27], v[0:3], v[66:81]
	global_load_dwordx4 v[214:217], v[240:241], off offset:3776
	global_load_dwordx4 v[218:221], v[242:243], off offset:3776
	v_mfma_f32_32x32x16_bf16 v[82:97], v[24:27], v[4:7], v[82:97]
	s_waitcnt lgkmcnt(0)
	v_mfma_f32_32x32x16_bf16 v[98:113], v[24:27], v[8:11], v[98:113]
	global_load_dwordx4 v[222:225], v[244:245], off offset:1728
	global_load_dwordx4 v[228:231], v[246:247], off offset:1728
	v_mfma_f32_32x32x16_bf16 v[114:129], v[24:27], v[12:15], v[114:129]
	v_mfma_f32_32x32x16_bf16 v[130:145], v[28:31], v[0:3], v[130:145]
	global_load_dwordx4 v[232:235], v[248:249], off offset:1728
	global_load_dwordx4 v[236:239], v[250:251], off offset:1728
	v_mfma_f32_32x32x16_bf16 v[146:161], v[28:31], v[4:7], v[146:161]
	v_mfma_f32_32x32x16_bf16 v[162:177], v[28:31], v[8:11], v[162:177]
	v_mfma_f32_32x32x16_bf16 v[178:193], v[28:31], v[12:15], v[178:193]
	s_waitcnt lgkmcnt(0)
	s_barrier
	ds_read_b128 v[0:3], v56 offset:30720
	ds_read_b128 v[4:7], v56 offset:33280
	ds_read_b128 v[8:11], v57 offset:30720
	ds_read_b128 v[12:15], v57 offset:33280
	ds_read_b128 v[16:19], v57 offset:35840
	ds_read_b128 v[20:23], v57 offset:38400
	ds_read_b128 v[24:27], v56 offset:30752
	ds_read_b128 v[28:31], v56 offset:33312
	s_waitcnt lgkmcnt(4)
	v_mfma_f32_32x32x16_bf16 v[66:81], v[0:3], v[8:11], v[66:81]
	v_mfma_f32_32x32x16_bf16 v[82:97], v[0:3], v[12:15], v[82:97]
	s_waitcnt vmcnt(6)
	ds_write_b128 v58, v[32:35] offset:0
	ds_write_b128 v58, v[36:39] offset:5120
	s_waitcnt lgkmcnt(4)
	v_mfma_f32_32x32x16_bf16 v[98:113], v[0:3], v[16:19], v[98:113]
	v_mfma_f32_32x32x16_bf16 v[114:129], v[0:3], v[20:23], v[114:129]
	ds_read_b128 v[0:3], v57 offset:30752
	ds_write_b128 v58, v[40:43] offset:10240
	ds_write_b128 v58, v[44:47] offset:15360
	v_mfma_f32_32x32x16_bf16 v[130:145], v[4:7], v[8:11], v[130:145]
	v_mfma_f32_32x32x16_bf16 v[146:161], v[4:7], v[12:15], v[146:161]
	ds_write_b128 v58, v[48:51] offset:20480
	ds_write_b128 v58, v[52:55] offset:25600
	v_mfma_f32_32x32x16_bf16 v[162:177], v[4:7], v[16:19], v[162:177]
	v_mfma_f32_32x32x16_bf16 v[178:193], v[4:7], v[20:23], v[178:193]
	ds_read_b128 v[4:7], v57 offset:33312
	ds_read_b128 v[8:11], v57 offset:35872
	ds_read_b128 v[12:15], v57 offset:38432
	s_waitcnt lgkmcnt(2)
	v_mfma_f32_32x32x16_bf16 v[66:81], v[24:27], v[0:3], v[66:81]
	global_load_dwordx4 v[32:35], v[240:241], off offset:3840
	global_load_dwordx4 v[36:39], v[242:243], off offset:3840
	v_mfma_f32_32x32x16_bf16 v[82:97], v[24:27], v[4:7], v[82:97]
	s_waitcnt lgkmcnt(0)
	v_mfma_f32_32x32x16_bf16 v[98:113], v[24:27], v[8:11], v[98:113]
	global_load_dwordx4 v[40:43], v[244:245], off offset:1792
	global_load_dwordx4 v[44:47], v[246:247], off offset:1792
	v_mfma_f32_32x32x16_bf16 v[114:129], v[24:27], v[12:15], v[114:129]
	v_mfma_f32_32x32x16_bf16 v[130:145], v[28:31], v[0:3], v[130:145]
	global_load_dwordx4 v[48:51], v[248:249], off offset:1792
	global_load_dwordx4 v[52:55], v[250:251], off offset:1792
	v_mfma_f32_32x32x16_bf16 v[146:161], v[28:31], v[4:7], v[146:161]
	v_mfma_f32_32x32x16_bf16 v[162:177], v[28:31], v[8:11], v[162:177]
	v_mfma_f32_32x32x16_bf16 v[178:193], v[28:31], v[12:15], v[178:193]
	s_waitcnt lgkmcnt(0)
	s_barrier
; #define G_LOAD(S, kt_) do { G_LD1(S##a0, S##b0, 0, kt_); G_LD1(S##a1, S##b1, 1, kt_); G_LD1(S##a2, S##b2, 2, kt_); G_LD1(S##a3, S##b3, 3, kt_); } while (0)
; #define G_STORE(S, buf_) do { G_ST1(S##a0, S##b0, 0, buf_); G_ST1(S##a1, S##b1, 1, buf_); G_ST1(S##a2, S##b2, 2, buf_); G_ST1(S##a3, S##b3, 3, buf_); } while (0)
; template <class AL, class BL>
; DI void gemm_core(AL al, BL bl, int m0, int n0, int K, char* smem, f32x16 (&acc)[2][2]) {
;     ...
;   G_LOAD(x, 0);
;   G_STORE(x, 0);
;   G_LOAD(x, 1);
;   G_LOAD(y, (nk > 2) ? 2 : 1);
;   __syncthreads();
;   for (int kt = 0; kt < nk; kt += 2) {
;     G_TILE(0, x, true, (kt + 3 < nk), kt + 3);
;     __syncthreads();
;     G_TILE(1, y, (kt + 2 < nk), (kt + 4 < nk), kt + 4);
;     __syncthreads();
	ds_read_b128 v[0:3], v56 offset:0
	ds_read_b128 v[4:7], v56 offset:2560
	ds_read_b128 v[8:11], v57 offset:0
	ds_read_b128 v[12:15], v57 offset:2560
	ds_read_b128 v[16:19], v57 offset:5120
	ds_read_b128 v[20:23], v57 offset:7680
	ds_read_b128 v[24:27], v56 offset:32
	ds_read_b128 v[28:31], v56 offset:2592
	s_waitcnt lgkmcnt(4)
	v_mfma_f32_32x32x16_bf16 v[66:81], v[0:3], v[8:11], v[66:81]
	v_mfma_f32_32x32x16_bf16 v[82:97], v[0:3], v[12:15], v[82:97]
	s_waitcnt vmcnt(6)
	ds_write_b128 v58, v[214:217] offset:30720
	ds_write_b128 v58, v[218:221] offset:35840
	s_waitcnt lgkmcnt(4)
	v_mfma_f32_32x32x16_bf16 v[98:113], v[0:3], v[16:19], v[98:113]
	v_mfma_f32_32x32x16_bf16 v[114:129], v[0:3], v[20:23], v[114:129]
	ds_read_b128 v[0:3], v57 offset:32
	ds_write_b128 v58, v[222:225] offset:40960
	ds_write_b128 v58, v[228:231] offset:46080
	v_mfma_f32_32x32x16_bf16 v[130:145], v[4:7], v[8:11], v[130:145]
	v_mfma_f32_32x32x16_bf16 v[146:161], v[4:7], v[12:15], v[146:161]
	ds_write_b128 v58, v[232:235] offset:51200
	ds_write_b128 v58, v[236:239] offset:56320
	v_mfma_f32_32x32x16_bf16 v[162:177], v[4:7], v[16:19], v[162:177]
	v_mfma_f32_32x32x16_bf16 v[178:193], v[4:7], v[20:23], v[178:193]
	ds_read_b128 v[4:7], v57 offset:2592
	ds_read_b128 v[8:11], v57 offset:5152
	ds_read_b128 v[12:15], v57 offset:7712
	s_waitcnt lgkmcnt(2)
	v_mfma_f32_32x32x16_bf16 v[66:81], v[24:27], v[0:3], v[66:81]
	global_load_dwordx4 v[214:217], v[240:241], off offset:3904
	global_load_dwordx4 v[218:221], v[242:243], off offset:3904
	v_mfma_f32_32x32x16_bf16 v[82:97], v[24:27], v[4:7], v[82:97]
	s_waitcnt lgkmcnt(0)
	v_mfma_f32_32x32x16_bf16 v[98:113], v[24:27], v[8:11], v[98:113]
	global_load_dwordx4 v[222:225], v[244:245], off offset:1856
	global_load_dwordx4 v[228:231], v[246:247], off offset:1856
	v_mfma_f32_32x32x16_bf16 v[114:129], v[24:27], v[12:15], v[114:129]
	v_mfma_f32_32x32x16_bf16 v[130:145], v[28:31], v[0:3], v[130:145]
	global_load_dwordx4 v[232:235], v[248:249], off offset:1856
	global_load_dwordx4 v[236:239], v[250:251], off offset:1856
	v_mfma_f32_32x32x16_bf16 v[146:161], v[28:31], v[4:7], v[146:161]
	v_mfma_f32_32x32x16_bf16 v[162:177], v[28:31], v[8:11], v[162:177]
	v_mfma_f32_32x32x16_bf16 v[178:193], v[28:31], v[12:15], v[178:193]
	s_waitcnt lgkmcnt(0)
	s_barrier
	ds_read_b128 v[0:3], v56 offset:30720
	ds_read_b128 v[4:7], v56 offset:33280
	ds_read_b128 v[8:11], v57 offset:30720
	ds_read_b128 v[12:15], v57 offset:33280
	ds_read_b128 v[16:19], v57 offset:35840
	ds_read_b128 v[20:23], v57 offset:38400
	ds_read_b128 v[24:27], v56 offset:30752
	ds_read_b128 v[28:31], v56 offset:33312
	s_waitcnt lgkmcnt(4)
	v_mfma_f32_32x32x16_bf16 v[66:81], v[0:3], v[8:11], v[66:81]
	v_mfma_f32_32x32x16_bf16 v[82:97], v[0:3], v[12:15], v[82:97]
	s_waitcnt vmcnt(6)
	ds_write_b128 v58, v[32:35] offset:0
	ds_write_b128 v58, v[36:39] offset:5120
	s_waitcnt lgkmcnt(4)
	v_mfma_f32_32x32x16_bf16 v[98:113], v[0:3], v[16:19], v[98:113]
	v_mfma_f32_32x32x16_bf16 v[114:129], v[0:3], v[20:23], v[114:129]
	ds_read_b128 v[0:3], v57 offset:30752
	ds_write_b128 v58, v[40:43] offset:10240
	ds_write_b128 v58, v[44:47] offset:15360
	v_mfma_f32_32x32x16_bf16 v[130:145], v[4:7], v[8:11], v[130:145]
	v_mfma_f32_32x32x16_bf16 v[146:161], v[4:7], v[12:15], v[146:161]
	ds_write_b128 v58, v[48:51] offset:20480
	ds_write_b128 v58, v[52:55] offset:25600
	v_mfma_f32_32x32x16_bf16 v[162:177], v[4:7], v[16:19], v[162:177]
	v_mfma_f32_32x32x16_bf16 v[178:193], v[4:7], v[20:23], v[178:193]
	ds_read_b128 v[4:7], v57 offset:33312
	ds_read_b128 v[8:11], v57 offset:35872
	ds_read_b128 v[12:15], v57 offset:38432
	s_waitcnt lgkmcnt(2)
	v_mfma_f32_32x32x16_bf16 v[66:81], v[24:27], v[0:3], v[66:81]
	global_load_dwordx4 v[32:35], v[240:241], off offset:3968
	global_load_dwordx4 v[36:39], v[242:243], off offset:3968
	v_mfma_f32_32x32x16_bf16 v[82:97], v[24:27], v[4:7], v[82:97]
	s_waitcnt lgkmcnt(0)
	v_mfma_f32_32x32x16_bf16 v[98:113], v[24:27], v[8:11], v[98:113]
	global_load_dwordx4 v[40:43], v[244:245], off offset:1920
	global_load_dwordx4 v[44:47], v[246:247], off offset:1920
	v_mfma_f32_32x32x16_bf16 v[114:129], v[24:27], v[12:15], v[114:129]
	v_mfma_f32_32x32x16_bf16 v[130:145], v[28:31], v[0:3], v[130:145]
	global_load_dwordx4 v[48:51], v[248:249], off offset:1920
	global_load_dwordx4 v[52:55], v[250:251], off offset:1920
	v_mfma_f32_32x32x16_bf16 v[146:161], v[28:31], v[4:7], v[146:161]
	v_mfma_f32_32x32x16_bf16 v[162:177], v[28:31], v[8:11], v[162:177]
	v_mfma_f32_32x32x16_bf16 v[178:193], v[28:31], v[12:15], v[178:193]
	s_waitcnt lgkmcnt(0)
	s_barrier
; #define G_LOAD(S, kt_) do { G_LD1(S##a0, S##b0, 0, kt_); G_LD1(S##a1, S##b1, 1, kt_); G_LD1(S##a2, S##b2, 2, kt_); G_LD1(S##a3, S##b3, 3, kt_); } while (0)
; #define G_STORE(S, buf_) do { G_ST1(S##a0, S##b0, 0, buf_); G_ST1(S##a1, S##b1, 1, buf_); G_ST1(S##a2, S##b2, 2, buf_); G_ST1(S##a3, S##b3, 3, buf_); } while (0)
; template <class AL, class BL>
; DI void gemm_core(AL al, BL bl, int m0, int n0, int K, char* smem, f32x16 (&acc)[2][2]) {
;     ...
;   G_LOAD(x, 0);
;   G_STORE(x, 0);
;   G_LOAD(x, 1);
;   G_LOAD(y, (nk > 2) ? 2 : 1);
;   __syncthreads();
;   for (int kt = 0; kt < nk; kt += 2) {
;     G_TILE(0, x, true, (kt + 3 < nk), kt + 3);
;     __syncthreads();
;     G_TILE(1, y, (kt + 2 < nk), (kt + 4 < nk), kt + 4);
;     __syncthreads();
	ds_read_b128 v[0:3], v56 offset:0
	ds_read_b128 v[4:7], v56 offset:2560
	ds_read_b128 v[8:11], v57 offset:0
	ds_read_b128 v[12:15], v57 offset:2560
	ds_read_b128 v[16:19], v57 offset:5120
	ds_read_b128 v[20:23], v57 offset:7680
	ds_read_b128 v[24:27], v56 offset:32
	ds_read_b128 v[28:31], v56 offset:2592
	s_waitcnt lgkmcnt(4)
	v_mfma_f32_32x32x16_bf16 v[66:81], v[0:3], v[8:11], v[66:81]
	v_mfma_f32_32x32x16_bf16 v[82:97], v[0:3], v[12:15], v[82:97]
	s_waitcnt vmcnt(6)
	ds_write_b128 v58, v[214:217] offset:30720
	ds_write_b128 v58, v[218:221] offset:35840
	s_waitcnt lgkmcnt(4)
	v_mfma_f32_32x32x16_bf16 v[98:113], v[0:3], v[16:19], v[98:113]
	v_mfma_f32_32x32x16_bf16 v[114:129], v[0:3], v[20:23], v[114:129]
	ds_read_b128 v[0:3], v57 offset:32
	ds_write_b128 v58, v[222:225] offset:40960
	ds_write_b128 v58, v[228:231] offset:46080
	v_mfma_f32_32x32x16_bf16 v[130:145], v[4:7], v[8:11], v[130:145]
	v_mfma_f32_32x32x16_bf16 v[146:161], v[4:7], v[12:15], v[146:161]
	ds_write_b128 v58, v[232:235] offset:51200
	ds_write_b128 v58, v[236:239] offset:56320
	v_mfma_f32_32x32x16_bf16 v[162:177], v[4:7], v[16:19], v[162:177]
	v_mfma_f32_32x32x16_bf16 v[178:193], v[4:7], v[20:23], v[178:193]
	ds_read_b128 v[4:7], v57 offset:2592
	ds_read_b128 v[8:11], v57 offset:5152
	ds_read_b128 v[12:15], v57 offset:7712
	s_waitcnt lgkmcnt(2)
	v_mfma_f32_32x32x16_bf16 v[66:81], v[24:27], v[0:3], v[66:81]
	global_load_dwordx4 v[214:217], v[240:241], off offset:4032
	global_load_dwordx4 v[218:221], v[242:243], off offset:4032
	v_mfma_f32_32x32x16_bf16 v[82:97], v[24:27], v[4:7], v[82:97]
	s_waitcnt lgkmcnt(0)
	v_mfma_f32_32x32x16_bf16 v[98:113], v[24:27], v[8:11], v[98:113]
	global_load_dwordx4 v[222:225], v[244:245], off offset:1984
	global_load_dwordx4 v[228:231], v[246:247], off offset:1984
	v_mfma_f32_32x32x16_bf16 v[114:129], v[24:27], v[12:15], v[114:129]
	v_mfma_f32_32x32x16_bf16 v[130:145], v[28:31], v[0:3], v[130:145]
	global_load_dwordx4 v[232:235], v[248:249], off offset:1984
	global_load_dwordx4 v[236:239], v[250:251], off offset:1984
	v_mfma_f32_32x32x16_bf16 v[146:161], v[28:31], v[4:7], v[146:161]
	v_mfma_f32_32x32x16_bf16 v[162:177], v[28:31], v[8:11], v[162:177]
	v_mfma_f32_32x32x16_bf16 v[178:193], v[28:31], v[12:15], v[178:193]
	s_waitcnt lgkmcnt(0)
	s_barrier
	ds_read_b128 v[0:3], v56 offset:30720
	ds_read_b128 v[4:7], v56 offset:33280
	ds_read_b128 v[8:11], v57 offset:30720
	ds_read_b128 v[12:15], v57 offset:33280
	ds_read_b128 v[16:19], v57 offset:35840
	ds_read_b128 v[20:23], v57 offset:38400
	ds_read_b128 v[24:27], v56 offset:30752
	ds_read_b128 v[28:31], v56 offset:33312
	s_waitcnt lgkmcnt(4)
	v_mfma_f32_32x32x16_bf16 v[66:81], v[0:3], v[8:11], v[66:81]
	v_mfma_f32_32x32x16_bf16 v[82:97], v[0:3], v[12:15], v[82:97]
	s_waitcnt vmcnt(6)
	ds_write_b128 v58, v[32:35] offset:0
	ds_write_b128 v58, v[36:39] offset:5120
	s_waitcnt lgkmcnt(4)
	v_mfma_f32_32x32x16_bf16 v[98:113], v[0:3], v[16:19], v[98:113]
	v_mfma_f32_32x32x16_bf16 v[114:129], v[0:3], v[20:23], v[114:129]
	ds_read_b128 v[0:3], v57 offset:30752
	ds_write_b128 v58, v[40:43] offset:10240
	ds_write_b128 v58, v[44:47] offset:15360
	v_mfma_f32_32x32x16_bf16 v[130:145], v[4:7], v[8:11], v[130:145]
	v_mfma_f32_32x32x16_bf16 v[146:161], v[4:7], v[12:15], v[146:161]
	ds_write_b128 v58, v[48:51] offset:20480
	ds_write_b128 v58, v[52:55] offset:25600
	v_mfma_f32_32x32x16_bf16 v[162:177], v[4:7], v[16:19], v[162:177]
	v_mfma_f32_32x32x16_bf16 v[178:193], v[4:7], v[20:23], v[178:193]
	ds_read_b128 v[4:7], v57 offset:33312
	ds_read_b128 v[8:11], v57 offset:35872
	ds_read_b128 v[12:15], v57 offset:38432
	s_waitcnt lgkmcnt(2)
	v_mfma_f32_32x32x16_bf16 v[66:81], v[24:27], v[0:3], v[66:81]
	v_mfma_f32_32x32x16_bf16 v[82:97], v[24:27], v[4:7], v[82:97]
	s_waitcnt lgkmcnt(0)
	v_mfma_f32_32x32x16_bf16 v[98:113], v[24:27], v[8:11], v[98:113]
	v_mfma_f32_32x32x16_bf16 v[114:129], v[24:27], v[12:15], v[114:129]
	v_mfma_f32_32x32x16_bf16 v[130:145], v[28:31], v[0:3], v[130:145]
	v_mfma_f32_32x32x16_bf16 v[146:161], v[28:31], v[4:7], v[146:161]
	v_mfma_f32_32x32x16_bf16 v[162:177], v[28:31], v[8:11], v[162:177]
	v_mfma_f32_32x32x16_bf16 v[178:193], v[28:31], v[12:15], v[178:193]
	s_waitcnt lgkmcnt(0)
	s_barrier
	ds_read_b128 v[0:3], v56 offset:0
	ds_read_b128 v[4:7], v56 offset:2560
	ds_read_b128 v[8:11], v57 offset:0
	ds_read_b128 v[12:15], v57 offset:2560
	ds_read_b128 v[16:19], v57 offset:5120
	ds_read_b128 v[20:23], v57 offset:7680
	ds_read_b128 v[24:27], v56 offset:32
	ds_read_b128 v[28:31], v56 offset:2592
	s_waitcnt lgkmcnt(4)
	v_mfma_f32_32x32x16_bf16 v[66:81], v[0:3], v[8:11], v[66:81]
	v_mfma_f32_32x32x16_bf16 v[82:97], v[0:3], v[12:15], v[82:97]
	s_waitcnt vmcnt(0)
	ds_write_b128 v58, v[214:217] offset:30720
	ds_write_b128 v58, v[218:221] offset:35840
	s_waitcnt lgkmcnt(4)
	v_mfma_f32_32x32x16_bf16 v[98:113], v[0:3], v[16:19], v[98:113]
	v_mfma_f32_32x32x16_bf16 v[114:129], v[0:3], v[20:23], v[114:129]
	ds_read_b128 v[0:3], v57 offset:32
	ds_write_b128 v58, v[222:225] offset:40960
	ds_write_b128 v58, v[228:231] offset:46080
	v_mfma_f32_32x32x16_bf16 v[130:145], v[4:7], v[8:11], v[130:145]
	v_mfma_f32_32x32x16_bf16 v[146:161], v[4:7], v[12:15], v[146:161]
	ds_write_b128 v58, v[232:235] offset:51200
	ds_write_b128 v58, v[236:239] offset:56320
	v_mfma_f32_32x32x16_bf16 v[162:177], v[4:7], v[16:19], v[162:177]
	v_mfma_f32_32x32x16_bf16 v[178:193], v[4:7], v[20:23], v[178:193]
	ds_read_b128 v[4:7], v57 offset:2592
	ds_read_b128 v[8:11], v57 offset:5152
	ds_read_b128 v[12:15], v57 offset:7712
	s_waitcnt lgkmcnt(2)
	v_mfma_f32_32x32x16_bf16 v[66:81], v[24:27], v[0:3], v[66:81]
	v_mfma_f32_32x32x16_bf16 v[82:97], v[24:27], v[4:7], v[82:97]
	s_waitcnt lgkmcnt(0)
	v_mfma_f32_32x32x16_bf16 v[98:113], v[24:27], v[8:11], v[98:113]
	v_mfma_f32_32x32x16_bf16 v[114:129], v[24:27], v[12:15], v[114:129]
	v_mfma_f32_32x32x16_bf16 v[130:145], v[28:31], v[0:3], v[130:145]
	v_mfma_f32_32x32x16_bf16 v[146:161], v[28:31], v[4:7], v[146:161]
	v_mfma_f32_32x32x16_bf16 v[162:177], v[28:31], v[8:11], v[162:177]
	v_mfma_f32_32x32x16_bf16 v[178:193], v[28:31], v[12:15], v[178:193]
	s_waitcnt lgkmcnt(0)
	s_barrier
; template <class AL, class BL>
; DI void gemm_core(AL al, BL bl, int m0, int n0, int K, char* smem, f32x16 (&acc)[2][2]) {
;     ...
;   for (int kt = 0; kt < nk; kt += 2) {
;     G_TILE(0, x, true, (kt + 3 < nk), kt + 3);
;     __syncthreads();
;     G_TILE(1, y, (kt + 2 < nk), (kt + 4 < nk), kt + 4);
;     __syncthreads();
; DI void ffn_up_phase(const Params& p, const u16* xb, int ldx, const u16* wupT, u16* hid, char* smem) {
;     ...
;              [=](const f32x16 (&acc)[2][2], int m0, int n0) {
;                epi_bf16_tile(acc, m0, n0, hid + (long)m0 * 4096 + n0, 4096, smem, [=](int m, int n, float v) {
;                  const float a = fmaxf(v * rs[m], 0.f);
;                  return a * a;
;                });
	ds_read_b128 v[0:3], v56 offset:30720
	ds_read_b128 v[4:7], v56 offset:33280
	ds_read_b128 v[8:11], v57 offset:30720
	ds_read_b128 v[12:15], v57 offset:33280
	ds_read_b128 v[16:19], v57 offset:35840
	ds_read_b128 v[20:23], v57 offset:38400
	ds_read_b128 v[24:27], v56 offset:30752
	ds_read_b128 v[28:31], v56 offset:33312
	s_waitcnt lgkmcnt(4)
	v_mfma_f32_32x32x16_bf16 v[66:81], v[0:3], v[8:11], v[66:81]
	global_load_dword v32, v61, s[12:13] offset:0
	global_load_dword v33, v61, s[12:13] offset:4
	global_load_dword v34, v61, s[12:13] offset:8
	global_load_dword v35, v61, s[12:13] offset:12
	v_mfma_f32_32x32x16_bf16 v[82:97], v[0:3], v[12:15], v[82:97]
	s_waitcnt lgkmcnt(2)
	v_mfma_f32_32x32x16_bf16 v[98:113], v[0:3], v[16:19], v[98:113]
	global_load_dword v36, v61, s[12:13] offset:32
	global_load_dword v37, v61, s[12:13] offset:36
	global_load_dword v38, v61, s[12:13] offset:40
	global_load_dword v39, v61, s[12:13] offset:44
	v_mfma_f32_32x32x16_bf16 v[114:129], v[0:3], v[20:23], v[114:129]
	ds_read_b128 v[0:3], v57 offset:30752
	v_mfma_f32_32x32x16_bf16 v[130:145], v[4:7], v[8:11], v[130:145]
	global_load_dword v40, v61, s[12:13] offset:64
	global_load_dword v41, v61, s[12:13] offset:68
	global_load_dword v42, v61, s[12:13] offset:72
	global_load_dword v43, v61, s[12:13] offset:76
	v_mfma_f32_32x32x16_bf16 v[146:161], v[4:7], v[12:15], v[146:161]
	v_mfma_f32_32x32x16_bf16 v[162:177], v[4:7], v[16:19], v[162:177]
	global_load_dword v44, v61, s[12:13] offset:96
	global_load_dword v45, v61, s[12:13] offset:100
	global_load_dword v46, v61, s[12:13] offset:104
	global_load_dword v47, v61, s[12:13] offset:108
	v_mfma_f32_32x32x16_bf16 v[178:193], v[4:7], v[20:23], v[178:193]
	ds_read_b128 v[4:7], v57 offset:33312
	ds_read_b128 v[8:11], v57 offset:35872
	ds_read_b128 v[12:15], v57 offset:38432
	s_waitcnt lgkmcnt(2)
	v_mfma_f32_32x32x16_bf16 v[66:81], v[24:27], v[0:3], v[66:81]
	global_load_dword v48, v61, s[12:13] offset:128
	global_load_dword v49, v61, s[12:13] offset:132
	global_load_dword v50, v61, s[12:13] offset:136
	global_load_dword v51, v61, s[12:13] offset:140
	v_mfma_f32_32x32x16_bf16 v[82:97], v[24:27], v[4:7], v[82:97]
	s_waitcnt lgkmcnt(0)
	v_mfma_f32_32x32x16_bf16 v[98:113], v[24:27], v[8:11], v[98:113]
	global_load_dword v52, v61, s[12:13] offset:160
	global_load_dword v53, v61, s[12:13] offset:164
	global_load_dword v54, v61, s[12:13] offset:168
	global_load_dword v55, v61, s[12:13] offset:172
	v_mfma_f32_32x32x16_bf16 v[114:129], v[24:27], v[12:15], v[114:129]
	v_mfma_f32_32x32x16_bf16 v[130:145], v[28:31], v[0:3], v[130:145]
	global_load_dword v214, v61, s[12:13] offset:192
	global_load_dword v215, v61, s[12:13] offset:196
	global_load_dword v216, v61, s[12:13] offset:200
	global_load_dword v217, v61, s[12:13] offset:204
	v_mfma_f32_32x32x16_bf16 v[146:161], v[28:31], v[4:7], v[146:161]
	v_mfma_f32_32x32x16_bf16 v[162:177], v[28:31], v[8:11], v[162:177]
	global_load_dword v218, v61, s[12:13] offset:224
	global_load_dword v219, v61, s[12:13] offset:228
	global_load_dword v220, v61, s[12:13] offset:232
	global_load_dword v221, v61, s[12:13] offset:236
	v_mfma_f32_32x32x16_bf16 v[178:193], v[28:31], v[12:15], v[178:193]
	s_waitcnt lgkmcnt(0)
	s_barrier
	s_nop 7
	s_nop 3
	s_waitcnt vmcnt(0)
	v_mov_b32_e32 v0, v32
	v_mov_b32_e32 v1, v33
	v_mov_b32_e32 v2, v34
	v_mov_b32_e32 v3, v35
	v_mov_b32_e32 v4, v36
	v_mov_b32_e32 v5, v37
	v_mov_b32_e32 v6, v38
	v_mov_b32_e32 v7, v39
	v_mov_b32_e32 v8, v40
	v_mov_b32_e32 v9, v41
	v_mov_b32_e32 v10, v42
	v_mov_b32_e32 v11, v43
	v_mov_b32_e32 v12, v44
	v_mov_b32_e32 v13, v45
	v_mov_b32_e32 v14, v46
	v_mov_b32_e32 v15, v47
	v_mov_b32_e32 v16, v48
	v_mov_b32_e32 v17, v49
	v_mov_b32_e32 v18, v50
	v_mov_b32_e32 v19, v51
	v_mov_b32_e32 v20, v52
	v_mov_b32_e32 v21, v53
	v_mov_b32_e32 v22, v54
	v_mov_b32_e32 v23, v55
	v_mov_b32_e32 v24, v214
	v_mov_b32_e32 v25, v215
	v_mov_b32_e32 v26, v216
	v_mov_b32_e32 v27, v217
	v_mov_b32_e32 v28, v218
	v_mov_b32_e32 v29, v219
	v_mov_b32_e32 v30, v220
	v_mov_b32_e32 v31, v221
	s_add_u32 s98, s98, s50
	s_cmpk_lt_u32 s98, 2048
	s_cbranch_scc0 .Lfu1_nonext
	s_cmpk_lt_u32 s98, 2016
	s_cbranch_scc1 .Lfu1_m1
	s_sub_u32 s31, s98, 2016
	s_mov_b32 s33, 14
	s_branch .Lfu1_g1

; DI u16 f2bf(float x) { return (u16)(pack2(x, 0.f) & 0xffffu); }
; DI int opaque_tid() { int t = threadIdx.x; asm volatile("" : "+v"(t)); return t; }
; DI int crow(int i, int h) { return (i & 3) + 8 * (i >> 2) + 4 * h; }
; template <class F>
; DI void epi_bf16_tile(const f32x16 (&acc)[2][2], int m0, int n0, u16* dst0, long ld, char* smem, F f) {
;   const int tid = opaque_tid(), lane = tid & 63, w = tid >> 6, wm = w >> 1, wn = w & 1, h = lane >> 5;
;   u16* T = (u16*)smem;
; #pragma unroll
;   for (int mt = 0; mt < 2; mt++)
; #pragma unroll
;     for (int nt = 0; nt < 2; nt++)
; #pragma unroll
;       for (int i = 0; i < 16; i++) {
;         const int ml = wm * 64 + mt * 32 + crow(i, h), nl = wn * 64 + nt * 32 + (lane & 31);
;         T[ml * 136 + nl] = f2bf(f(m0 + ml, n0 + nl, acc[mt][nt][i]));
;       }
;   __syncthreads();
; DI void ffn_up_phase(const Params& p, const u16* xb, int ldx, const u16* wupT, u16* hid, char* smem) {
;     ...
;              [=](const f32x16 (&acc)[2][2], int m0, int n0) {
;                epi_bf16_tile(acc, m0, n0, hid + (long)m0 * 4096 + n0, 4096, smem, [=](int m, int n, float v) {
;                  const float a = fmaxf(v * rs[m], 0.f);
;                  return a * a;
;                });
.Lfu1_nonext:
	v_mul_f32_e32 v62, v66, v0
	v_max_f32_e32 v62, 0, v62
	v_mul_f32_e32 v62, v62, v62
	v_cvt_pk_bf16_f32 v62, v62, v62
	ds_write_b16 v59, v62 offset:0
	v_mul_f32_e32 v63, v67, v1
	v_max_f32_e32 v63, 0, v63
	v_mul_f32_e32 v63, v63, v63
	v_cvt_pk_bf16_f32 v63, v63, v63
	ds_write_b16 v59, v63 offset:528
	v_mul_f32_e32 v64, v68, v2
	v_max_f32_e32 v64, 0, v64
	v_mul_f32_e32 v64, v64, v64
	v_cvt_pk_bf16_f32 v64, v64, v64
	ds_write_b16 v59, v64 offset:1056
	v_mul_f32_e32 v62, v69, v3
	v_max_f32_e32 v62, 0, v62
	v_mul_f32_e32 v62, v62, v62
	v_cvt_pk_bf16_f32 v62, v62, v62
	ds_write_b16 v59, v62 offset:1584
	v_mul_f32_e32 v63, v70, v4
	v_max_f32_e32 v63, 0, v63
	v_mul_f32_e32 v63, v63, v63
	v_cvt_pk_bf16_f32 v63, v63, v63
	ds_write_b16 v59, v63 offset:4224
	v_mul_f32_e32 v64, v71, v5
	v_max_f32_e32 v64, 0, v64
	v_mul_f32_e32 v64, v64, v64
	v_cvt_pk_bf16_f32 v64, v64, v64
	ds_write_b16 v59, v64 offset:4752
	v_mul_f32_e32 v62, v72, v6
	v_max_f32_e32 v62, 0, v62
	v_mul_f32_e32 v62, v62, v62
	v_cvt_pk_bf16_f32 v62, v62, v62
	ds_write_b16 v59, v62 offset:5280
	v_mul_f32_e32 v63, v73, v7
	v_max_f32_e32 v63, 0, v63
	v_mul_f32_e32 v63, v63, v63
	v_cvt_pk_bf16_f32 v63, v63, v63
	ds_write_b16 v59, v63 offset:5808
	v_mul_f32_e32 v64, v74, v8
	v_max_f32_e32 v64, 0, v64
	v_mul_f32_e32 v64, v64, v64
	v_cvt_pk_bf16_f32 v64, v64, v64
	ds_write_b16 v59, v64 offset:8448
	v_mul_f32_e32 v62, v75, v9
	v_max_f32_e32 v62, 0, v62
	v_mul_f32_e32 v62, v62, v62
	v_cvt_pk_bf16_f32 v62, v62, v62
	ds_write_b16 v59, v62 offset:8976
	v_mul_f32_e32 v63, v76, v10
	v_max_f32_e32 v63, 0, v63
	v_mul_f32_e32 v63, v63, v63
	v_cvt_pk_bf16_f32 v63, v63, v63
	ds_write_b16 v59, v63 offset:9504
	v_mul_f32_e32 v64, v77, v11
	v_max_f32_e32 v64, 0, v64
	v_mul_f32_e32 v64, v64, v64
	v_cvt_pk_bf16_f32 v64, v64, v64
	ds_write_b16 v59, v64 offset:10032
	v_mul_f32_e32 v62, v78, v12
	v_max_f32_e32 v62, 0, v62
	v_mul_f32_e32 v62, v62, v62
	v_cvt_pk_bf16_f32 v62, v62, v62
	ds_write_b16 v59, v62 offset:12672
	v_mul_f32_e32 v63, v79, v13
	v_max_f32_e32 v63, 0, v63
	v_mul_f32_e32 v63, v63, v63
	v_cvt_pk_bf16_f32 v63, v63, v63
	ds_write_b16 v59, v63 offset:13200
	v_mul_f32_e32 v64, v80, v14
	v_max_f32_e32 v64, 0, v64
	v_mul_f32_e32 v64, v64, v64
	v_cvt_pk_bf16_f32 v64, v64, v64
	ds_write_b16 v59, v64 offset:13728
	v_mul_f32_e32 v62, v81, v15
	v_max_f32_e32 v62, 0, v62
	v_mul_f32_e32 v62, v62, v62
	v_cvt_pk_bf16_f32 v62, v62, v62
	ds_write_b16 v59, v62 offset:14256
	v_mul_f32_e32 v62, v82, v0
	v_max_f32_e32 v62, 0, v62
	v_mul_f32_e32 v62, v62, v62
	v_cvt_pk_bf16_f32 v62, v62, v62
	ds_write_b16 v59, v62 offset:64
	v_mul_f32_e32 v63, v83, v1
	v_max_f32_e32 v63, 0, v63
	v_mul_f32_e32 v63, v63, v63
	v_cvt_pk_bf16_f32 v63, v63, v63
	ds_write_b16 v59, v63 offset:592
	v_mul_f32_e32 v64, v84, v2
	v_max_f32_e32 v64, 0, v64
	v_mul_f32_e32 v64, v64, v64
	v_cvt_pk_bf16_f32 v64, v64, v64
	ds_write_b16 v59, v64 offset:1120
	v_mul_f32_e32 v62, v85, v3
	v_max_f32_e32 v62, 0, v62
	v_mul_f32_e32 v62, v62, v62
	v_cvt_pk_bf16_f32 v62, v62, v62
	ds_write_b16 v59, v62 offset:1648
	v_mul_f32_e32 v63, v86, v4
	v_max_f32_e32 v63, 0, v63
	v_mul_f32_e32 v63, v63, v63
	v_cvt_pk_bf16_f32 v63, v63, v63
	ds_write_b16 v59, v63 offset:4288
	v_mul_f32_e32 v64, v87, v5
	v_max_f32_e32 v64, 0, v64
	v_mul_f32_e32 v64, v64, v64
	v_cvt_pk_bf16_f32 v64, v64, v64
	ds_write_b16 v59, v64 offset:4816
	v_mul_f32_e32 v62, v88, v6
	v_max_f32_e32 v62, 0, v62
	v_mul_f32_e32 v62, v62, v62
	v_cvt_pk_bf16_f32 v62, v62, v62
	ds_write_b16 v59, v62 offset:5344
	v_mul_f32_e32 v63, v89, v7
	v_max_f32_e32 v63, 0, v63
	v_mul_f32_e32 v63, v63, v63
	v_cvt_pk_bf16_f32 v63, v63, v63
	ds_write_b16 v59, v63 offset:5872
	v_mul_f32_e32 v64, v90, v8
	v_max_f32_e32 v64, 0, v64
	v_mul_f32_e32 v64, v64, v64
	v_cvt_pk_bf16_f32 v64, v64, v64
	ds_write_b16 v59, v64 offset:8512
	v_mul_f32_e32 v62, v91, v9
	v_max_f32_e32 v62, 0, v62
	v_mul_f32_e32 v62, v62, v62
	v_cvt_pk_bf16_f32 v62, v62, v62
	ds_write_b16 v59, v62 offset:9040
	v_mul_f32_e32 v63, v92, v10
	v_max_f32_e32 v63, 0, v63
	v_mul_f32_e32 v63, v63, v63
	v_cvt_pk_bf16_f32 v63, v63, v63
	ds_write_b16 v59, v63 offset:9568
	v_mul_f32_e32 v64, v93, v11
	v_max_f32_e32 v64, 0, v64
	v_mul_f32_e32 v64, v64, v64
	v_cvt_pk_bf16_f32 v64, v64, v64
	ds_write_b16 v59, v64 offset:10096
	v_mul_f32_e32 v62, v94, v12
	v_max_f32_e32 v62, 0, v62
	v_mul_f32_e32 v62, v62, v62
	v_cvt_pk_bf16_f32 v62, v62, v62
	ds_write_b16 v59, v62 offset:12736
	v_mul_f32_e32 v63, v95, v13
	v_max_f32_e32 v63, 0, v63
	v_mul_f32_e32 v63, v63, v63
	v_cvt_pk_bf16_f32 v63, v63, v63
	ds_write_b16 v59, v63 offset:13264
	v_mul_f32_e32 v64, v96, v14
	v_max_f32_e32 v64, 0, v64
	v_mul_f32_e32 v64, v64, v64
	v_cvt_pk_bf16_f32 v64, v64, v64
	ds_write_b16 v59, v64 offset:13792
	v_mul_f32_e32 v62, v97, v15
	v_max_f32_e32 v62, 0, v62
	v_mul_f32_e32 v62, v62, v62
	v_cvt_pk_bf16_f32 v62, v62, v62
	ds_write_b16 v59, v62 offset:14320
	v_mul_f32_e32 v62, v98, v0
	v_max_f32_e32 v62, 0, v62
	v_mul_f32_e32 v62, v62, v62
	v_cvt_pk_bf16_f32 v62, v62, v62
	ds_write_b16 v59, v62 offset:128
	v_mul_f32_e32 v63, v99, v1
	v_max_f32_e32 v63, 0, v63
	v_mul_f32_e32 v63, v63, v63
	v_cvt_pk_bf16_f32 v63, v63, v63
	ds_write_b16 v59, v63 offset:656
	v_mul_f32_e32 v64, v100, v2
	v_max_f32_e32 v64, 0, v64
	v_mul_f32_e32 v64, v64, v64
	v_cvt_pk_bf16_f32 v64, v64, v64
	ds_write_b16 v59, v64 offset:1184
	v_mul_f32_e32 v62, v101, v3
	v_max_f32_e32 v62, 0, v62
	v_mul_f32_e32 v62, v62, v62
	v_cvt_pk_bf16_f32 v62, v62, v62
	ds_write_b16 v59, v62 offset:1712
	v_mul_f32_e32 v63, v102, v4
	v_max_f32_e32 v63, 0, v63
	v_mul_f32_e32 v63, v63, v63
	v_cvt_pk_bf16_f32 v63, v63, v63
	ds_write_b16 v59, v63 offset:4352
; DI u16 f2bf(float x) { return (u16)(pack2(x, 0.f) & 0xffffu); }
; DI int opaque_tid() { int t = threadIdx.x; asm volatile("" : "+v"(t)); return t; }
; DI int crow(int i, int h) { return (i & 3) + 8 * (i >> 2) + 4 * h; }
; template <class F>
; DI void epi_bf16_tile(const f32x16 (&acc)[2][2], int m0, int n0, u16* dst0, long ld, char* smem, F f) {
;   const int tid = opaque_tid(), lane = tid & 63, w = tid >> 6, wm = w >> 1, wn = w & 1, h = lane >> 5;
;   u16* T = (u16*)smem;
; #pragma unroll
;   for (int mt = 0; mt < 2; mt++)
; #pragma unroll
;     for (int nt = 0; nt < 2; nt++)
; #pragma unroll
;       for (int i = 0; i < 16; i++) {
;         const int ml = wm * 64 + mt * 32 + crow(i, h), nl = wn * 64 + nt * 32 + (lane & 31);
;         T[ml * 136 + nl] = f2bf(f(m0 + ml, n0 + nl, acc[mt][nt][i]));
;       }
;   __syncthreads();
; DI void ffn_up_phase(const Params& p, const u16* xb, int ldx, const u16* wupT, u16* hid, char* smem) {
;     ...
;              [=](const f32x16 (&acc)[2][2], int m0, int n0) {
;                epi_bf16_tile(acc, m0, n0, hid + (long)m0 * 4096 + n0, 4096, smem, [=](int m, int n, float v) {
;                  const float a = fmaxf(v * rs[m], 0.f);
;                  return a * a;
;                });
	v_mul_f32_e32 v64, v103, v5
	v_max_f32_e32 v64, 0, v64
	v_mul_f32_e32 v64, v64, v64
	v_cvt_pk_bf16_f32 v64, v64, v64
	ds_write_b16 v59, v64 offset:4880
	v_mul_f32_e32 v62, v104, v6
	v_max_f32_e32 v62, 0, v62
	v_mul_f32_e32 v62, v62, v62
	v_cvt_pk_bf16_f32 v62, v62, v62
	ds_write_b16 v59, v62 offset:5408
	v_mul_f32_e32 v63, v105, v7
	v_max_f32_e32 v63, 0, v63
	v_mul_f32_e32 v63, v63, v63
	v_cvt_pk_bf16_f32 v63, v63, v63
	ds_write_b16 v59, v63 offset:5936
	v_mul_f32_e32 v64, v106, v8
	v_max_f32_e32 v64, 0, v64
	v_mul_f32_e32 v64, v64, v64
	v_cvt_pk_bf16_f32 v64, v64, v64
	ds_write_b16 v59, v64 offset:8576
	v_mul_f32_e32 v62, v107, v9
	v_max_f32_e32 v62, 0, v62
	v_mul_f32_e32 v62, v62, v62
	v_cvt_pk_bf16_f32 v62, v62, v62
	ds_write_b16 v59, v62 offset:9104
	v_mul_f32_e32 v63, v108, v10
	v_max_f32_e32 v63, 0, v63
	v_mul_f32_e32 v63, v63, v63
	v_cvt_pk_bf16_f32 v63, v63, v63
	ds_write_b16 v59, v63 offset:9632
	v_mul_f32_e32 v64, v109, v11
	v_max_f32_e32 v64, 0, v64
	v_mul_f32_e32 v64, v64, v64
	v_cvt_pk_bf16_f32 v64, v64, v64
	ds_write_b16 v59, v64 offset:10160
	v_mul_f32_e32 v62, v110, v12
	v_max_f32_e32 v62, 0, v62
	v_mul_f32_e32 v62, v62, v62
	v_cvt_pk_bf16_f32 v62, v62, v62
	ds_write_b16 v59, v62 offset:12800
	v_mul_f32_e32 v63, v111, v13
	v_max_f32_e32 v63, 0, v63
	v_mul_f32_e32 v63, v63, v63
	v_cvt_pk_bf16_f32 v63, v63, v63
	ds_write_b16 v59, v63 offset:13328
	v_mul_f32_e32 v64, v112, v14
	v_max_f32_e32 v64, 0, v64
	v_mul_f32_e32 v64, v64, v64
	v_cvt_pk_bf16_f32 v64, v64, v64
	ds_write_b16 v59, v64 offset:13856
	v_mul_f32_e32 v62, v113, v15
	v_max_f32_e32 v62, 0, v62
	v_mul_f32_e32 v62, v62, v62
	v_cvt_pk_bf16_f32 v62, v62, v62
	ds_write_b16 v59, v62 offset:14384
	v_mul_f32_e32 v62, v114, v0
	v_max_f32_e32 v62, 0, v62
	v_mul_f32_e32 v62, v62, v62
	v_cvt_pk_bf16_f32 v62, v62, v62
	ds_write_b16 v59, v62 offset:192
	v_mul_f32_e32 v63, v115, v1
	v_max_f32_e32 v63, 0, v63
	v_mul_f32_e32 v63, v63, v63
	v_cvt_pk_bf16_f32 v63, v63, v63
	ds_write_b16 v59, v63 offset:720
	v_mul_f32_e32 v64, v116, v2
	v_max_f32_e32 v64, 0, v64
	v_mul_f32_e32 v64, v64, v64
	v_cvt_pk_bf16_f32 v64, v64, v64
	ds_write_b16 v59, v64 offset:1248
	v_mul_f32_e32 v62, v117, v3
	v_max_f32_e32 v62, 0, v62
	v_mul_f32_e32 v62, v62, v62
	v_cvt_pk_bf16_f32 v62, v62, v62
	ds_write_b16 v59, v62 offset:1776
	v_mul_f32_e32 v63, v118, v4
	v_max_f32_e32 v63, 0, v63
	v_mul_f32_e32 v63, v63, v63
	v_cvt_pk_bf16_f32 v63, v63, v63
	ds_write_b16 v59, v63 offset:4416
	v_mul_f32_e32 v64, v119, v5
	v_max_f32_e32 v64, 0, v64
	v_mul_f32_e32 v64, v64, v64
	v_cvt_pk_bf16_f32 v64, v64, v64
	ds_write_b16 v59, v64 offset:4944
	v_mul_f32_e32 v62, v120, v6
	v_max_f32_e32 v62, 0, v62
	v_mul_f32_e32 v62, v62, v62
	v_cvt_pk_bf16_f32 v62, v62, v62
	ds_write_b16 v59, v62 offset:5472
	v_mul_f32_e32 v63, v121, v7
	v_max_f32_e32 v63, 0, v63
	v_mul_f32_e32 v63, v63, v63
	v_cvt_pk_bf16_f32 v63, v63, v63
	ds_write_b16 v59, v63 offset:6000
	v_mul_f32_e32 v64, v122, v8
	v_max_f32_e32 v64, 0, v64
	v_mul_f32_e32 v64, v64, v64
	v_cvt_pk_bf16_f32 v64, v64, v64
	ds_write_b16 v59, v64 offset:8640
	v_mul_f32_e32 v62, v123, v9
	v_max_f32_e32 v62, 0, v62
	v_mul_f32_e32 v62, v62, v62
	v_cvt_pk_bf16_f32 v62, v62, v62
	ds_write_b16 v59, v62 offset:9168
	v_mul_f32_e32 v63, v124, v10
	v_max_f32_e32 v63, 0, v63
	v_mul_f32_e32 v63, v63, v63
	v_cvt_pk_bf16_f32 v63, v63, v63
	ds_write_b16 v59, v63 offset:9696
	v_mul_f32_e32 v64, v125, v11
	v_max_f32_e32 v64, 0, v64
	v_mul_f32_e32 v64, v64, v64
	v_cvt_pk_bf16_f32 v64, v64, v64
	ds_write_b16 v59, v64 offset:10224
	v_mul_f32_e32 v62, v126, v12
	v_max_f32_e32 v62, 0, v62
	v_mul_f32_e32 v62, v62, v62
	v_cvt_pk_bf16_f32 v62, v62, v62
	ds_write_b16 v59, v62 offset:12864
	v_mul_f32_e32 v63, v127, v13
	v_max_f32_e32 v63, 0, v63
	v_mul_f32_e32 v63, v63, v63
	v_cvt_pk_bf16_f32 v63, v63, v63
	ds_write_b16 v59, v63 offset:13392
	v_mul_f32_e32 v64, v128, v14
	v_max_f32_e32 v64, 0, v64
	v_mul_f32_e32 v64, v64, v64
	v_cvt_pk_bf16_f32 v64, v64, v64
	ds_write_b16 v59, v64 offset:13920
	v_mul_f32_e32 v62, v129, v15
	v_max_f32_e32 v62, 0, v62
	v_mul_f32_e32 v62, v62, v62
	v_cvt_pk_bf16_f32 v62, v62, v62
	ds_write_b16 v59, v62 offset:14448
	v_mul_f32_e32 v62, v130, v16
	v_max_f32_e32 v62, 0, v62
	v_mul_f32_e32 v62, v62, v62
	v_cvt_pk_bf16_f32 v62, v62, v62
	ds_write_b16 v59, v62 offset:16896
	v_mul_f32_e32 v63, v131, v17
	v_max_f32_e32 v63, 0, v63
	v_mul_f32_e32 v63, v63, v63
	v_cvt_pk_bf16_f32 v63, v63, v63
	ds_write_b16 v59, v63 offset:17424
	v_mul_f32_e32 v64, v132, v18
	v_max_f32_e32 v64, 0, v64
	v_mul_f32_e32 v64, v64, v64
	v_cvt_pk_bf16_f32 v64, v64, v64
	ds_write_b16 v59, v64 offset:17952
	v_mul_f32_e32 v62, v133, v19
	v_max_f32_e32 v62, 0, v62
	v_mul_f32_e32 v62, v62, v62
	v_cvt_pk_bf16_f32 v62, v62, v62
	ds_write_b16 v59, v62 offset:18480
	v_mul_f32_e32 v63, v134, v20
	v_max_f32_e32 v63, 0, v63
	v_mul_f32_e32 v63, v63, v63
	v_cvt_pk_bf16_f32 v63, v63, v63
	ds_write_b16 v59, v63 offset:21120
	v_mul_f32_e32 v64, v135, v21
	v_max_f32_e32 v64, 0, v64
	v_mul_f32_e32 v64, v64, v64
	v_cvt_pk_bf16_f32 v64, v64, v64
	ds_write_b16 v59, v64 offset:21648
	v_mul_f32_e32 v62, v136, v22
	v_max_f32_e32 v62, 0, v62
	v_mul_f32_e32 v62, v62, v62
	v_cvt_pk_bf16_f32 v62, v62, v62
	ds_write_b16 v59, v62 offset:22176
	v_mul_f32_e32 v63, v137, v23
	v_max_f32_e32 v63, 0, v63
	v_mul_f32_e32 v63, v63, v63
	v_cvt_pk_bf16_f32 v63, v63, v63
	ds_write_b16 v59, v63 offset:22704
	v_mul_f32_e32 v64, v138, v24
	v_max_f32_e32 v64, 0, v64
	v_mul_f32_e32 v64, v64, v64
	v_cvt_pk_bf16_f32 v64, v64, v64
	ds_write_b16 v59, v64 offset:25344
	v_mul_f32_e32 v62, v139, v25
	v_max_f32_e32 v62, 0, v62
	v_mul_f32_e32 v62, v62, v62
; DI u16 f2bf(float x) { return (u16)(pack2(x, 0.f) & 0xffffu); }
; DI int opaque_tid() { int t = threadIdx.x; asm volatile("" : "+v"(t)); return t; }
; DI int crow(int i, int h) { return (i & 3) + 8 * (i >> 2) + 4 * h; }
; template <class F>
; DI void epi_bf16_tile(const f32x16 (&acc)[2][2], int m0, int n0, u16* dst0, long ld, char* smem, F f) {
;   const int tid = opaque_tid(), lane = tid & 63, w = tid >> 6, wm = w >> 1, wn = w & 1, h = lane >> 5;
;   u16* T = (u16*)smem;
; #pragma unroll
;   for (int mt = 0; mt < 2; mt++)
; #pragma unroll
;     for (int nt = 0; nt < 2; nt++)
; #pragma unroll
;       for (int i = 0; i < 16; i++) {
;         const int ml = wm * 64 + mt * 32 + crow(i, h), nl = wn * 64 + nt * 32 + (lane & 31);
;         T[ml * 136 + nl] = f2bf(f(m0 + ml, n0 + nl, acc[mt][nt][i]));
;       }
;   __syncthreads();
; DI void ffn_up_phase(const Params& p, const u16* xb, int ldx, const u16* wupT, u16* hid, char* smem) {
;     ...
;              [=](const f32x16 (&acc)[2][2], int m0, int n0) {
;                epi_bf16_tile(acc, m0, n0, hid + (long)m0 * 4096 + n0, 4096, smem, [=](int m, int n, float v) {
;                  const float a = fmaxf(v * rs[m], 0.f);
;                  return a * a;
;                });
	v_cvt_pk_bf16_f32 v62, v62, v62
	ds_write_b16 v59, v62 offset:25872
	v_mul_f32_e32 v63, v140, v26
	v_max_f32_e32 v63, 0, v63
	v_mul_f32_e32 v63, v63, v63
	v_cvt_pk_bf16_f32 v63, v63, v63
	ds_write_b16 v59, v63 offset:26400
	v_mul_f32_e32 v64, v141, v27
	v_max_f32_e32 v64, 0, v64
	v_mul_f32_e32 v64, v64, v64
	v_cvt_pk_bf16_f32 v64, v64, v64
	ds_write_b16 v59, v64 offset:26928
	v_mul_f32_e32 v62, v142, v28
	v_max_f32_e32 v62, 0, v62
	v_mul_f32_e32 v62, v62, v62
	v_cvt_pk_bf16_f32 v62, v62, v62
	ds_write_b16 v59, v62 offset:29568
	v_mul_f32_e32 v63, v143, v29
	v_max_f32_e32 v63, 0, v63
	v_mul_f32_e32 v63, v63, v63
	v_cvt_pk_bf16_f32 v63, v63, v63
	ds_write_b16 v59, v63 offset:30096
	v_mul_f32_e32 v64, v144, v30
	v_max_f32_e32 v64, 0, v64
	v_mul_f32_e32 v64, v64, v64
	v_cvt_pk_bf16_f32 v64, v64, v64
	ds_write_b16 v59, v64 offset:30624
	v_mul_f32_e32 v62, v145, v31
	v_max_f32_e32 v62, 0, v62
	v_mul_f32_e32 v62, v62, v62
	v_cvt_pk_bf16_f32 v62, v62, v62
	ds_write_b16 v59, v62 offset:31152
	v_mul_f32_e32 v62, v146, v16
	v_max_f32_e32 v62, 0, v62
	v_mul_f32_e32 v62, v62, v62
	v_cvt_pk_bf16_f32 v62, v62, v62
	ds_write_b16 v59, v62 offset:16960
	v_mul_f32_e32 v63, v147, v17
	v_max_f32_e32 v63, 0, v63
	v_mul_f32_e32 v63, v63, v63
	v_cvt_pk_bf16_f32 v63, v63, v63
	ds_write_b16 v59, v63 offset:17488
	v_mul_f32_e32 v64, v148, v18
	v_max_f32_e32 v64, 0, v64
	v_mul_f32_e32 v64, v64, v64
	v_cvt_pk_bf16_f32 v64, v64, v64
	ds_write_b16 v59, v64 offset:18016
	v_mul_f32_e32 v62, v149, v19
	v_max_f32_e32 v62, 0, v62
	v_mul_f32_e32 v62, v62, v62
	v_cvt_pk_bf16_f32 v62, v62, v62
	ds_write_b16 v59, v62 offset:18544
	v_mul_f32_e32 v63, v150, v20
	v_max_f32_e32 v63, 0, v63
	v_mul_f32_e32 v63, v63, v63
	v_cvt_pk_bf16_f32 v63, v63, v63
	ds_write_b16 v59, v63 offset:21184
	v_mul_f32_e32 v64, v151, v21
	v_max_f32_e32 v64, 0, v64
	v_mul_f32_e32 v64, v64, v64
	v_cvt_pk_bf16_f32 v64, v64, v64
	ds_write_b16 v59, v64 offset:21712
	v_mul_f32_e32 v62, v152, v22
	v_max_f32_e32 v62, 0, v62
	v_mul_f32_e32 v62, v62, v62
	v_cvt_pk_bf16_f32 v62, v62, v62
	ds_write_b16 v59, v62 offset:22240
	v_mul_f32_e32 v63, v153, v23
	v_max_f32_e32 v63, 0, v63
	v_mul_f32_e32 v63, v63, v63
	v_cvt_pk_bf16_f32 v63, v63, v63
	ds_write_b16 v59, v63 offset:22768
	v_mul_f32_e32 v64, v154, v24
	v_max_f32_e32 v64, 0, v64
	v_mul_f32_e32 v64, v64, v64
	v_cvt_pk_bf16_f32 v64, v64, v64
	ds_write_b16 v59, v64 offset:25408
	v_mul_f32_e32 v62, v155, v25
	v_max_f32_e32 v62, 0, v62
	v_mul_f32_e32 v62, v62, v62
	v_cvt_pk_bf16_f32 v62, v62, v62
	ds_write_b16 v59, v62 offset:25936
	v_mul_f32_e32 v63, v156, v26
	v_max_f32_e32 v63, 0, v63
	v_mul_f32_e32 v63, v63, v63
	v_cvt_pk_bf16_f32 v63, v63, v63
	ds_write_b16 v59, v63 offset:26464
	v_mul_f32_e32 v64, v157, v27
	v_max_f32_e32 v64, 0, v64
	v_mul_f32_e32 v64, v64, v64
	v_cvt_pk_bf16_f32 v64, v64, v64
	ds_write_b16 v59, v64 offset:26992
	v_mul_f32_e32 v62, v158, v28
	v_max_f32_e32 v62, 0, v62
	v_mul_f32_e32 v62, v62, v62
	v_cvt_pk_bf16_f32 v62, v62, v62
	ds_write_b16 v59, v62 offset:29632
	v_mul_f32_e32 v63, v159, v29
	v_max_f32_e32 v63, 0, v63
	v_mul_f32_e32 v63, v63, v63
	v_cvt_pk_bf16_f32 v63, v63, v63
	ds_write_b16 v59, v63 offset:30160
	v_mul_f32_e32 v64, v160, v30
	v_max_f32_e32 v64, 0, v64
	v_mul_f32_e32 v64, v64, v64
	v_cvt_pk_bf16_f32 v64, v64, v64
	ds_write_b16 v59, v64 offset:30688
	v_mul_f32_e32 v62, v161, v31
	v_max_f32_e32 v62, 0, v62
	v_mul_f32_e32 v62, v62, v62
	v_cvt_pk_bf16_f32 v62, v62, v62
	ds_write_b16 v59, v62 offset:31216
	v_mul_f32_e32 v62, v162, v16
	v_max_f32_e32 v62, 0, v62
	v_mul_f32_e32 v62, v62, v62
	v_cvt_pk_bf16_f32 v62, v62, v62
	ds_write_b16 v59, v62 offset:17024
	v_mul_f32_e32 v63, v163, v17
	v_max_f32_e32 v63, 0, v63
	v_mul_f32_e32 v63, v63, v63
	v_cvt_pk_bf16_f32 v63, v63, v63
	ds_write_b16 v59, v63 offset:17552
	v_mul_f32_e32 v64, v164, v18
	v_max_f32_e32 v64, 0, v64
	v_mul_f32_e32 v64, v64, v64
	v_cvt_pk_bf16_f32 v64, v64, v64
	ds_write_b16 v59, v64 offset:18080
	v_mul_f32_e32 v62, v165, v19
	v_max_f32_e32 v62, 0, v62
	v_mul_f32_e32 v62, v62, v62
	v_cvt_pk_bf16_f32 v62, v62, v62
	ds_write_b16 v59, v62 offset:18608
	v_mul_f32_e32 v63, v166, v20
	v_max_f32_e32 v63, 0, v63
	v_mul_f32_e32 v63, v63, v63
	v_cvt_pk_bf16_f32 v63, v63, v63
	ds_write_b16 v59, v63 offset:21248
	v_mul_f32_e32 v64, v167, v21
	v_max_f32_e32 v64, 0, v64
	v_mul_f32_e32 v64, v64, v64
	v_cvt_pk_bf16_f32 v64, v64, v64
	ds_write_b16 v59, v64 offset:21776
	v_mul_f32_e32 v62, v168, v22
	v_max_f32_e32 v62, 0, v62
	v_mul_f32_e32 v62, v62, v62
	v_cvt_pk_bf16_f32 v62, v62, v62
	ds_write_b16 v59, v62 offset:22304
	v_mul_f32_e32 v63, v169, v23
	v_max_f32_e32 v63, 0, v63
	v_mul_f32_e32 v63, v63, v63
	v_cvt_pk_bf16_f32 v63, v63, v63
	ds_write_b16 v59, v63 offset:22832
	v_mul_f32_e32 v64, v170, v24
	v_max_f32_e32 v64, 0, v64
	v_mul_f32_e32 v64, v64, v64
	v_cvt_pk_bf16_f32 v64, v64, v64
	ds_write_b16 v59, v64 offset:25472
	v_mul_f32_e32 v62, v171, v25
	v_max_f32_e32 v62, 0, v62
	v_mul_f32_e32 v62, v62, v62
	v_cvt_pk_bf16_f32 v62, v62, v62
	ds_write_b16 v59, v62 offset:26000
	v_mul_f32_e32 v63, v172, v26
	v_max_f32_e32 v63, 0, v63
	v_mul_f32_e32 v63, v63, v63
	v_cvt_pk_bf16_f32 v63, v63, v63
	ds_write_b16 v59, v63 offset:26528
	v_mul_f32_e32 v64, v173, v27
	v_max_f32_e32 v64, 0, v64
	v_mul_f32_e32 v64, v64, v64
	v_cvt_pk_bf16_f32 v64, v64, v64
	ds_write_b16 v59, v64 offset:27056
	v_mul_f32_e32 v62, v174, v28
	v_max_f32_e32 v62, 0, v62
	v_mul_f32_e32 v62, v62, v62
	v_cvt_pk_bf16_f32 v62, v62, v62
	ds_write_b16 v59, v62 offset:29696
	v_mul_f32_e32 v63, v175, v29
	v_max_f32_e32 v63, 0, v63
	v_mul_f32_e32 v63, v63, v63
	v_cvt_pk_bf16_f32 v63, v63, v63
; DI u16 f2bf(float x) { return (u16)(pack2(x, 0.f) & 0xffffu); }
; DI int opaque_tid() { int t = threadIdx.x; asm volatile("" : "+v"(t)); return t; }
; DI int crow(int i, int h) { return (i & 3) + 8 * (i >> 2) + 4 * h; }
; template <class F>
; DI void epi_bf16_tile(const f32x16 (&acc)[2][2], int m0, int n0, u16* dst0, long ld, char* smem, F f) {
;   const int tid = opaque_tid(), lane = tid & 63, w = tid >> 6, wm = w >> 1, wn = w & 1, h = lane >> 5;
;   u16* T = (u16*)smem;
; #pragma unroll
;   for (int mt = 0; mt < 2; mt++)
; #pragma unroll
;     for (int nt = 0; nt < 2; nt++)
; #pragma unroll
;       for (int i = 0; i < 16; i++) {
;         const int ml = wm * 64 + mt * 32 + crow(i, h), nl = wn * 64 + nt * 32 + (lane & 31);
;         T[ml * 136 + nl] = f2bf(f(m0 + ml, n0 + nl, acc[mt][nt][i]));
;       }
;   __syncthreads();
; #pragma unroll
;   for (int j = 0; j < 8; j++) {
;     const int idx = tid + 256 * j, row = idx >> 4, ch = idx & 15;
;     *(uint4*)(dst0 + (long)row * ld + ch * 8) = *(const uint4*)(T + row * 136 + ch * 8);
;   }
;   __syncthreads();
; }
; template <class AL, class BL, class EP>
; DI void gemm_phase(int MT, int NTL, int K, AL al, BL bl, EP ep, char* smem) {
;   for (int t = blockIdx.x; t < MT * NTL; t += gridDim.x) {
;     const int tm = t % MT, tn = t / MT;
;     f32x16 acc[2][2];
;     gemm_core(al, bl, tm * 128, tn * 128, K, smem, acc);
;     ep(acc, tm * 128, tn * 128);
	ds_write_b16 v59, v63 offset:30224
	v_mul_f32_e32 v64, v176, v30
	v_max_f32_e32 v64, 0, v64
	v_mul_f32_e32 v64, v64, v64
	v_cvt_pk_bf16_f32 v64, v64, v64
	ds_write_b16 v59, v64 offset:30752
	v_mul_f32_e32 v62, v177, v31
	v_max_f32_e32 v62, 0, v62
	v_mul_f32_e32 v62, v62, v62
	v_cvt_pk_bf16_f32 v62, v62, v62
	ds_write_b16 v59, v62 offset:31280
	v_mul_f32_e32 v62, v178, v16
	v_max_f32_e32 v62, 0, v62
	v_mul_f32_e32 v62, v62, v62
	v_cvt_pk_bf16_f32 v62, v62, v62
	ds_write_b16 v59, v62 offset:17088
	v_mul_f32_e32 v63, v179, v17
	v_max_f32_e32 v63, 0, v63
	v_mul_f32_e32 v63, v63, v63
	v_cvt_pk_bf16_f32 v63, v63, v63
	ds_write_b16 v59, v63 offset:17616
	v_mul_f32_e32 v64, v180, v18
	v_max_f32_e32 v64, 0, v64
	v_mul_f32_e32 v64, v64, v64
	v_cvt_pk_bf16_f32 v64, v64, v64
	ds_write_b16 v59, v64 offset:18144
	v_mul_f32_e32 v62, v181, v19
	v_max_f32_e32 v62, 0, v62
	v_mul_f32_e32 v62, v62, v62
	v_cvt_pk_bf16_f32 v62, v62, v62
	ds_write_b16 v59, v62 offset:18672
	v_mul_f32_e32 v63, v182, v20
	v_max_f32_e32 v63, 0, v63
	v_mul_f32_e32 v63, v63, v63
	v_cvt_pk_bf16_f32 v63, v63, v63
	ds_write_b16 v59, v63 offset:21312
	v_mul_f32_e32 v64, v183, v21
	v_max_f32_e32 v64, 0, v64
	v_mul_f32_e32 v64, v64, v64
	v_cvt_pk_bf16_f32 v64, v64, v64
	ds_write_b16 v59, v64 offset:21840
	v_mul_f32_e32 v62, v184, v22
	v_max_f32_e32 v62, 0, v62
	v_mul_f32_e32 v62, v62, v62
	v_cvt_pk_bf16_f32 v62, v62, v62
	ds_write_b16 v59, v62 offset:22368
	v_mul_f32_e32 v63, v185, v23
	v_max_f32_e32 v63, 0, v63
	v_mul_f32_e32 v63, v63, v63
	v_cvt_pk_bf16_f32 v63, v63, v63
	ds_write_b16 v59, v63 offset:22896
	v_mul_f32_e32 v64, v186, v24
	v_max_f32_e32 v64, 0, v64
	v_mul_f32_e32 v64, v64, v64
	v_cvt_pk_bf16_f32 v64, v64, v64
	ds_write_b16 v59, v64 offset:25536
	v_mul_f32_e32 v62, v187, v25
	v_max_f32_e32 v62, 0, v62
	v_mul_f32_e32 v62, v62, v62
	v_cvt_pk_bf16_f32 v62, v62, v62
	ds_write_b16 v59, v62 offset:26064
	v_mul_f32_e32 v63, v188, v26
	v_max_f32_e32 v63, 0, v63
	v_mul_f32_e32 v63, v63, v63
	v_cvt_pk_bf16_f32 v63, v63, v63
	ds_write_b16 v59, v63 offset:26592
	v_mul_f32_e32 v64, v189, v27
	v_max_f32_e32 v64, 0, v64
	v_mul_f32_e32 v64, v64, v64
	v_cvt_pk_bf16_f32 v64, v64, v64
	ds_write_b16 v59, v64 offset:27120
	v_mul_f32_e32 v62, v190, v28
	v_max_f32_e32 v62, 0, v62
	v_mul_f32_e32 v62, v62, v62
	v_cvt_pk_bf16_f32 v62, v62, v62
	ds_write_b16 v59, v62 offset:29760
	v_mul_f32_e32 v63, v191, v29
	v_max_f32_e32 v63, 0, v63
	v_mul_f32_e32 v63, v63, v63
	v_cvt_pk_bf16_f32 v63, v63, v63
	ds_write_b16 v59, v63 offset:30288
	v_mul_f32_e32 v64, v192, v30
	v_max_f32_e32 v64, 0, v64
	v_mul_f32_e32 v64, v64, v64
	v_cvt_pk_bf16_f32 v64, v64, v64
	ds_write_b16 v59, v64 offset:30816
	v_mul_f32_e32 v62, v193, v31
	v_max_f32_e32 v62, 0, v62
	v_mul_f32_e32 v62, v62, v62
	v_cvt_pk_bf16_f32 v62, v62, v62
	ds_write_b16 v59, v62 offset:31344
	s_waitcnt lgkmcnt(0)
	s_barrier
	ds_read_b128 v[0:3], v60 offset:0
	ds_read_b128 v[4:7], v60 offset:4224
	ds_read_b128 v[8:11], v60 offset:8448
	ds_read_b128 v[12:15], v60 offset:12672
	ds_read_b128 v[16:19], v60 offset:16896
	ds_read_b128 v[20:23], v60 offset:21120
	ds_read_b128 v[24:27], v60 offset:25344
	ds_read_b128 v[28:31], v60 offset:29568
	s_waitcnt lgkmcnt(7)
	global_store_dwordx4 v227, v[0:3], s[18:19]
	s_add_u32 s18, s18, 65536
	s_addc_u32 s19, s19, 0
	ds_read_b128 v[0:3], v60 offset:33792
	s_waitcnt lgkmcnt(7)
	global_store_dwordx4 v227, v[4:7], s[18:19]
	s_add_u32 s18, s18, 65536
	s_addc_u32 s19, s19, 0
	ds_read_b128 v[4:7], v60 offset:38016
	s_waitcnt lgkmcnt(7)
	global_store_dwordx4 v227, v[8:11], s[18:19]
	s_add_u32 s18, s18, 65536
	s_addc_u32 s19, s19, 0
	ds_read_b128 v[8:11], v60 offset:42240
	s_waitcnt lgkmcnt(7)
	global_store_dwordx4 v227, v[12:15], s[18:19]
	s_add_u32 s18, s18, 65536
	s_addc_u32 s19, s19, 0
	ds_read_b128 v[12:15], v60 offset:46464
	s_waitcnt lgkmcnt(7)
	global_store_dwordx4 v227, v[16:19], s[18:19]
	s_add_u32 s18, s18, 65536
	s_addc_u32 s19, s19, 0
	ds_read_b128 v[16:19], v60 offset:50688
	s_waitcnt lgkmcnt(7)
	global_store_dwordx4 v227, v[20:23], s[18:19]
	s_add_u32 s18, s18, 65536
	s_addc_u32 s19, s19, 0
	ds_read_b128 v[20:23], v60 offset:54912
	s_waitcnt lgkmcnt(7)
	global_store_dwordx4 v227, v[24:27], s[18:19]
	s_add_u32 s18, s18, 65536
	s_addc_u32 s19, s19, 0
	ds_read_b128 v[24:27], v60 offset:59136
	s_waitcnt lgkmcnt(7)
	global_store_dwordx4 v227, v[28:31], s[18:19]
	s_add_u32 s18, s18, 65536
	s_addc_u32 s19, s19, 0
	ds_read_b128 v[28:31], v60 offset:63360
	s_waitcnt lgkmcnt(7)
	global_store_dwordx4 v227, v[0:3], s[18:19]
	s_add_u32 s18, s18, 65536
	s_addc_u32 s19, s19, 0
	s_waitcnt lgkmcnt(6)
	global_store_dwordx4 v227, v[4:7], s[18:19]
	s_add_u32 s18, s18, 65536
	s_addc_u32 s19, s19, 0
	s_waitcnt lgkmcnt(5)
	global_store_dwordx4 v227, v[8:11], s[18:19]
	s_add_u32 s18, s18, 65536
	s_addc_u32 s19, s19, 0
	s_waitcnt lgkmcnt(4)
	global_store_dwordx4 v227, v[12:15], s[18:19]
	s_add_u32 s18, s18, 65536
	s_addc_u32 s19, s19, 0
	s_waitcnt lgkmcnt(3)
	global_store_dwordx4 v227, v[16:19], s[18:19]
	s_add_u32 s18, s18, 65536
	s_addc_u32 s19, s19, 0
	s_waitcnt lgkmcnt(2)
	global_store_dwordx4 v227, v[20:23], s[18:19]
	s_add_u32 s18, s18, 65536
	s_addc_u32 s19, s19, 0
	s_waitcnt lgkmcnt(1)
	global_store_dwordx4 v227, v[24:27], s[18:19]
	s_add_u32 s18, s18, 65536
	s_addc_u32 s19, s19, 0
	s_waitcnt lgkmcnt(0)
	global_store_dwordx4 v227, v[28:31], s[18:19]
	s_barrier
	s_cmpk_lt_u32 s98, 2048
	s_cbranch_scc1 .Lfu1_tile
	s_cmpk_lt_u32 s78, 0xe0
	s_cbranch_scc0 .Lfu1_s2
	s_cmpk_ge_u32 s78, 0x70
	s_cselect_b32 s0, 1, 0
	s_mul_i32 s1, s0, 0x70
	s_sub_u32 s1, s78, s1
	s_add_u32 s1, s1, 32
	s_add_u32 s0, s0, 28
	s_branch .Lfu1_s3
